# GEMM epilogue stores at agent scope (sc1 only) instead of system scope (sc0 sc1)
# speedup vs baseline: 1.0084x; 1.0084x over previous
.Lg16_proj_k:
	s_add_i32 s3, s1, 2
	s_lshl_b32 s96, s3, 13
	s_add_i32 m0, vcc_lo, 16384
	v_lshl_add_u64 v[160:161], v[188:189], 0, s[96:97]
	global_load_lds_dwordx4 v[160:161], off
	global_load_lds_dwordx4 v[160:161], off offset:1024
	ds_read_b128 v[236:239], v196 offset:0
	ds_read_b128 v[240:243], v162 offset:0
	ds_read_b128 v[244:247], v196 offset:2048
	ds_read_b128 v[248:251], v162 offset:2048
	s_add_i32 s3, s1, 2
	s_lshl_b32 s96, s3, 11
	v_lshl_add_u64 v[198:199], v[184:185], 0, s[96:97]
	v_lshl_add_u64 v[200:201], v[186:187], 0, s[96:97]
	s_waitcnt vmcnt(8) lgkmcnt(3)
	v_mfma_f32_16x16x32_bf16 v[16:19], v[236:239], v[128:131], v[16:19]
	v_mfma_f32_16x16x32_bf16 v[24:27], v[236:239], v[132:135], v[24:27]
	v_mfma_f32_16x16x32_bf16 v[0:3], v[236:239], v[136:139], v[0:3]
	v_mfma_f32_16x16x32_bf16 v[8:11], v[236:239], v[140:143], v[8:11]
	ds_read_b128 v[236:239], v196 offset:4096
	s_waitcnt lgkmcnt(3)
	v_mfma_f32_16x16x32_bf16 v[20:23], v[240:243], v[128:131], v[20:23]
	v_mfma_f32_16x16x32_bf16 v[28:31], v[240:243], v[132:135], v[28:31]
	v_mfma_f32_16x16x32_bf16 v[4:7], v[240:243], v[136:139], v[4:7]
	v_mfma_f32_16x16x32_bf16 v[12:15], v[240:243], v[140:143], v[12:15]
	ds_read_b128 v[240:243], v162 offset:4096
	s_waitcnt lgkmcnt(3)
	v_mfma_f32_16x16x32_bf16 v[112:115], v[244:247], v[128:131], v[112:115]
	v_mfma_f32_16x16x32_bf16 v[120:123], v[244:247], v[132:135], v[120:123]
	v_mfma_f32_16x16x32_bf16 v[96:99], v[244:247], v[136:139], v[96:99]
	v_mfma_f32_16x16x32_bf16 v[104:107], v[244:247], v[140:143], v[104:107]
	ds_read_b128 v[244:247], v196 offset:6144
	s_waitcnt lgkmcnt(3)
	v_mfma_f32_16x16x32_bf16 v[116:119], v[248:251], v[128:131], v[116:119]
	v_mfma_f32_16x16x32_bf16 v[124:127], v[248:251], v[132:135], v[124:127]
	v_mfma_f32_16x16x32_bf16 v[100:103], v[248:251], v[136:139], v[100:103]
	v_mfma_f32_16x16x32_bf16 v[108:111], v[248:251], v[140:143], v[108:111]
	ds_read_b128 v[248:251], v162 offset:6144
	s_waitcnt lgkmcnt(3)
	v_mfma_f32_16x16x32_bf16 v[80:83], v[236:239], v[128:131], v[80:83]
	v_mfma_f32_16x16x32_bf16 v[88:91], v[236:239], v[132:135], v[88:91]
	v_mfma_f32_16x16x32_bf16 v[48:51], v[236:239], v[136:139], v[48:51]
	v_mfma_f32_16x16x32_bf16 v[56:59], v[236:239], v[140:143], v[56:59]
	s_waitcnt lgkmcnt(2)
	v_mfma_f32_16x16x32_bf16 v[84:87], v[240:243], v[128:131], v[84:87]
	v_mfma_f32_16x16x32_bf16 v[92:95], v[240:243], v[132:135], v[92:95]
	v_mfma_f32_16x16x32_bf16 v[52:55], v[240:243], v[136:139], v[52:55]
	v_mfma_f32_16x16x32_bf16 v[60:63], v[240:243], v[140:143], v[60:63]
	s_waitcnt lgkmcnt(1)
	v_mfma_f32_16x16x32_bf16 v[64:67], v[244:247], v[128:131], v[64:67]
	v_mfma_f32_16x16x32_bf16 v[72:75], v[244:247], v[132:135], v[72:75]
	v_mfma_f32_16x16x32_bf16 v[32:35], v[244:247], v[136:139], v[32:35]
	v_mfma_f32_16x16x32_bf16 v[40:43], v[244:247], v[140:143], v[40:43]
	s_waitcnt lgkmcnt(0)
	v_mfma_f32_16x16x32_bf16 v[68:71], v[248:251], v[128:131], v[68:71]
	v_mfma_f32_16x16x32_bf16 v[76:79], v[248:251], v[132:135], v[76:79]
	v_mfma_f32_16x16x32_bf16 v[36:39], v[248:251], v[136:139], v[36:39]
	v_mfma_f32_16x16x32_bf16 v[44:47], v[248:251], v[140:143], v[44:47]
	global_load_dwordx4 v[128:131], v[198:199], off
	global_load_dwordx4 v[132:135], v[198:199], off offset:256
	global_load_dwordx4 v[136:139], v[200:201], off
	global_load_dwordx4 v[140:143], v[200:201], off offset:256
	s_waitcnt vmcnt(10)
	s_barrier
	s_add_i32 s3, s1, 3
	s_lshl_b32 s96, s3, 13
	s_mov_b32 m0, vcc_lo
	v_lshl_add_u64 v[160:161], v[188:189], 0, s[96:97]
	global_load_lds_dwordx4 v[160:161], off
	global_load_lds_dwordx4 v[160:161], off offset:1024
	ds_read_b128 v[236:239], v196 offset:8192
	ds_read_b128 v[240:243], v162 offset:8192
	ds_read_b128 v[244:247], v196 offset:10240
	ds_read_b128 v[248:251], v162 offset:10240
	s_add_i32 s3, s1, 3
	s_lshl_b32 s96, s3, 11
	v_lshl_add_u64 v[198:199], v[184:185], 0, s[96:97]
	v_lshl_add_u64 v[200:201], v[186:187], 0, s[96:97]
	s_waitcnt vmcnt(8) lgkmcnt(3)
	v_mfma_f32_16x16x32_bf16 v[16:19], v[236:239], v[144:147], v[16:19]
	v_mfma_f32_16x16x32_bf16 v[24:27], v[236:239], v[148:151], v[24:27]
	v_mfma_f32_16x16x32_bf16 v[0:3], v[236:239], v[152:155], v[0:3]
	v_mfma_f32_16x16x32_bf16 v[8:11], v[236:239], v[156:159], v[8:11]
	ds_read_b128 v[236:239], v196 offset:12288
	s_waitcnt lgkmcnt(3)
	v_mfma_f32_16x16x32_bf16 v[20:23], v[240:243], v[144:147], v[20:23]
	v_mfma_f32_16x16x32_bf16 v[28:31], v[240:243], v[148:151], v[28:31]
	v_mfma_f32_16x16x32_bf16 v[4:7], v[240:243], v[152:155], v[4:7]
	v_mfma_f32_16x16x32_bf16 v[12:15], v[240:243], v[156:159], v[12:15]
	ds_read_b128 v[240:243], v162 offset:12288
	s_waitcnt lgkmcnt(3)
	v_mfma_f32_16x16x32_bf16 v[112:115], v[244:247], v[144:147], v[112:115]
	v_mfma_f32_16x16x32_bf16 v[120:123], v[244:247], v[148:151], v[120:123]
	v_mfma_f32_16x16x32_bf16 v[96:99], v[244:247], v[152:155], v[96:99]
	v_mfma_f32_16x16x32_bf16 v[104:107], v[244:247], v[156:159], v[104:107]
	ds_read_b128 v[244:247], v196 offset:14336
	s_waitcnt lgkmcnt(3)
	v_mfma_f32_16x16x32_bf16 v[116:119], v[248:251], v[144:147], v[116:119]
	v_mfma_f32_16x16x32_bf16 v[124:127], v[248:251], v[148:151], v[124:127]
	v_mfma_f32_16x16x32_bf16 v[100:103], v[248:251], v[152:155], v[100:103]
	v_mfma_f32_16x16x32_bf16 v[108:111], v[248:251], v[156:159], v[108:111]
	ds_read_b128 v[248:251], v162 offset:14336
	s_waitcnt lgkmcnt(3)
	v_mfma_f32_16x16x32_bf16 v[80:83], v[236:239], v[144:147], v[80:83]
	v_mfma_f32_16x16x32_bf16 v[88:91], v[236:239], v[148:151], v[88:91]
	v_mfma_f32_16x16x32_bf16 v[48:51], v[236:239], v[152:155], v[48:51]
	v_mfma_f32_16x16x32_bf16 v[56:59], v[236:239], v[156:159], v[56:59]
	s_waitcnt lgkmcnt(2)
	v_mfma_f32_16x16x32_bf16 v[84:87], v[240:243], v[144:147], v[84:87]
	v_mfma_f32_16x16x32_bf16 v[92:95], v[240:243], v[148:151], v[92:95]
	v_mfma_f32_16x16x32_bf16 v[52:55], v[240:243], v[152:155], v[52:55]
	v_mfma_f32_16x16x32_bf16 v[60:63], v[240:243], v[156:159], v[60:63]
	s_waitcnt lgkmcnt(1)
	v_mfma_f32_16x16x32_bf16 v[64:67], v[244:247], v[144:147], v[64:67]
	v_mfma_f32_16x16x32_bf16 v[72:75], v[244:247], v[148:151], v[72:75]
	v_mfma_f32_16x16x32_bf16 v[32:35], v[244:247], v[152:155], v[32:35]
	v_mfma_f32_16x16x32_bf16 v[40:43], v[244:247], v[156:159], v[40:43]
	s_waitcnt lgkmcnt(0)
	v_mfma_f32_16x16x32_bf16 v[68:71], v[248:251], v[144:147], v[68:71]
	v_mfma_f32_16x16x32_bf16 v[76:79], v[248:251], v[148:151], v[76:79]
	v_mfma_f32_16x16x32_bf16 v[36:39], v[248:251], v[152:155], v[36:39]
	v_mfma_f32_16x16x32_bf16 v[44:47], v[248:251], v[156:159], v[44:47]
	global_load_dwordx4 v[144:147], v[198:199], off
	global_load_dwordx4 v[148:151], v[198:199], off offset:256
	global_load_dwordx4 v[152:155], v[200:201], off
	global_load_dwordx4 v[156:159], v[200:201], off offset:256
	s_waitcnt vmcnt(10)
	s_barrier
	s_add_i32 s3, s1, 4
	s_lshl_b32 s96, s3, 13
	s_add_i32 m0, vcc_lo, 8192
	v_lshl_add_u64 v[160:161], v[188:189], 0, s[96:97]
	global_load_lds_dwordx4 v[160:161], off
	global_load_lds_dwordx4 v[160:161], off offset:1024
	ds_read_b128 v[236:239], v196 offset:16384
	ds_read_b128 v[240:243], v162 offset:16384
	ds_read_b128 v[244:247], v196 offset:18432
	ds_read_b128 v[248:251], v162 offset:18432
	s_add_i32 s3, s1, 4
	s_lshl_b32 s96, s3, 11
	v_lshl_add_u64 v[198:199], v[184:185], 0, s[96:97]
	v_lshl_add_u64 v[200:201], v[186:187], 0, s[96:97]
	s_waitcnt vmcnt(8) lgkmcnt(3)
	v_mfma_f32_16x16x32_bf16 v[16:19], v[236:239], v[128:131], v[16:19]
	v_mfma_f32_16x16x32_bf16 v[24:27], v[236:239], v[132:135], v[24:27]
	v_mfma_f32_16x16x32_bf16 v[0:3], v[236:239], v[136:139], v[0:3]
	v_mfma_f32_16x16x32_bf16 v[8:11], v[236:239], v[140:143], v[8:11]
	ds_read_b128 v[236:239], v196 offset:20480
	s_waitcnt lgkmcnt(3)
	v_mfma_f32_16x16x32_bf16 v[20:23], v[240:243], v[128:131], v[20:23]
	v_mfma_f32_16x16x32_bf16 v[28:31], v[240:243], v[132:135], v[28:31]
	v_mfma_f32_16x16x32_bf16 v[4:7], v[240:243], v[136:139], v[4:7]
	v_mfma_f32_16x16x32_bf16 v[12:15], v[240:243], v[140:143], v[12:15]
	ds_read_b128 v[240:243], v162 offset:20480
	s_waitcnt lgkmcnt(3)
	v_mfma_f32_16x16x32_bf16 v[112:115], v[244:247], v[128:131], v[112:115]
	v_mfma_f32_16x16x32_bf16 v[120:123], v[244:247], v[132:135], v[120:123]
	v_mfma_f32_16x16x32_bf16 v[96:99], v[244:247], v[136:139], v[96:99]
	v_mfma_f32_16x16x32_bf16 v[104:107], v[244:247], v[140:143], v[104:107]
	ds_read_b128 v[244:247], v196 offset:22528
	s_waitcnt lgkmcnt(3)
	v_mfma_f32_16x16x32_bf16 v[116:119], v[248:251], v[128:131], v[116:119]
	v_mfma_f32_16x16x32_bf16 v[124:127], v[248:251], v[132:135], v[124:127]
	v_mfma_f32_16x16x32_bf16 v[100:103], v[248:251], v[136:139], v[100:103]
	v_mfma_f32_16x16x32_bf16 v[108:111], v[248:251], v[140:143], v[108:111]
	ds_read_b128 v[248:251], v162 offset:22528
	s_waitcnt lgkmcnt(3)
	v_mfma_f32_16x16x32_bf16 v[80:83], v[236:239], v[128:131], v[80:83]
	v_mfma_f32_16x16x32_bf16 v[88:91], v[236:239], v[132:135], v[88:91]
	v_mfma_f32_16x16x32_bf16 v[48:51], v[236:239], v[136:139], v[48:51]
	v_mfma_f32_16x16x32_bf16 v[56:59], v[236:239], v[140:143], v[56:59]
	s_waitcnt lgkmcnt(2)
	v_mfma_f32_16x16x32_bf16 v[84:87], v[240:243], v[128:131], v[84:87]
	v_mfma_f32_16x16x32_bf16 v[92:95], v[240:243], v[132:135], v[92:95]
	v_mfma_f32_16x16x32_bf16 v[52:55], v[240:243], v[136:139], v[52:55]
	v_mfma_f32_16x16x32_bf16 v[60:63], v[240:243], v[140:143], v[60:63]
	s_waitcnt lgkmcnt(1)
	v_mfma_f32_16x16x32_bf16 v[64:67], v[244:247], v[128:131], v[64:67]
	v_mfma_f32_16x16x32_bf16 v[72:75], v[244:247], v[132:135], v[72:75]
	v_mfma_f32_16x16x32_bf16 v[32:35], v[244:247], v[136:139], v[32:35]
	v_mfma_f32_16x16x32_bf16 v[40:43], v[244:247], v[140:143], v[40:43]
	s_waitcnt lgkmcnt(0)
	v_mfma_f32_16x16x32_bf16 v[68:71], v[248:251], v[128:131], v[68:71]
	v_mfma_f32_16x16x32_bf16 v[76:79], v[248:251], v[132:135], v[76:79]
	v_mfma_f32_16x16x32_bf16 v[36:39], v[248:251], v[136:139], v[36:39]
	v_mfma_f32_16x16x32_bf16 v[44:47], v[248:251], v[140:143], v[44:47]
	global_load_dwordx4 v[128:131], v[198:199], off
	global_load_dwordx4 v[132:135], v[198:199], off offset:256
	global_load_dwordx4 v[136:139], v[200:201], off
	global_load_dwordx4 v[140:143], v[200:201], off offset:256
	s_waitcnt vmcnt(10)
	s_barrier
	s_add_i32 s3, s1, 5
	s_lshl_b32 s96, s3, 13
	s_add_i32 m0, vcc_lo, 16384
	v_lshl_add_u64 v[160:161], v[188:189], 0, s[96:97]
	global_load_lds_dwordx4 v[160:161], off
	global_load_lds_dwordx4 v[160:161], off offset:1024
	ds_read_b128 v[236:239], v196 offset:0
	ds_read_b128 v[240:243], v162 offset:0
	ds_read_b128 v[244:247], v196 offset:2048
	ds_read_b128 v[248:251], v162 offset:2048
	s_add_i32 s3, s1, 5
	s_lshl_b32 s96, s3, 11
	v_lshl_add_u64 v[198:199], v[184:185], 0, s[96:97]
	v_lshl_add_u64 v[200:201], v[186:187], 0, s[96:97]
	s_waitcnt vmcnt(8) lgkmcnt(3)
	v_mfma_f32_16x16x32_bf16 v[16:19], v[236:239], v[144:147], v[16:19]
	v_mfma_f32_16x16x32_bf16 v[24:27], v[236:239], v[148:151], v[24:27]
	v_mfma_f32_16x16x32_bf16 v[0:3], v[236:239], v[152:155], v[0:3]
	v_mfma_f32_16x16x32_bf16 v[8:11], v[236:239], v[156:159], v[8:11]
	ds_read_b128 v[236:239], v196 offset:4096
	s_waitcnt lgkmcnt(3)
	v_mfma_f32_16x16x32_bf16 v[20:23], v[240:243], v[144:147], v[20:23]
	v_mfma_f32_16x16x32_bf16 v[28:31], v[240:243], v[148:151], v[28:31]
	v_mfma_f32_16x16x32_bf16 v[4:7], v[240:243], v[152:155], v[4:7]
	v_mfma_f32_16x16x32_bf16 v[12:15], v[240:243], v[156:159], v[12:15]
	ds_read_b128 v[240:243], v162 offset:4096
	s_waitcnt lgkmcnt(3)
	v_mfma_f32_16x16x32_bf16 v[112:115], v[244:247], v[144:147], v[112:115]
	v_mfma_f32_16x16x32_bf16 v[120:123], v[244:247], v[148:151], v[120:123]
	v_mfma_f32_16x16x32_bf16 v[96:99], v[244:247], v[152:155], v[96:99]
	v_mfma_f32_16x16x32_bf16 v[104:107], v[244:247], v[156:159], v[104:107]
	ds_read_b128 v[244:247], v196 offset:6144
	s_waitcnt lgkmcnt(3)
	v_mfma_f32_16x16x32_bf16 v[116:119], v[248:251], v[144:147], v[116:119]
	v_mfma_f32_16x16x32_bf16 v[124:127], v[248:251], v[148:151], v[124:127]
	v_mfma_f32_16x16x32_bf16 v[100:103], v[248:251], v[152:155], v[100:103]
	v_mfma_f32_16x16x32_bf16 v[108:111], v[248:251], v[156:159], v[108:111]
	ds_read_b128 v[248:251], v162 offset:6144
	s_waitcnt lgkmcnt(3)
	v_mfma_f32_16x16x32_bf16 v[80:83], v[236:239], v[144:147], v[80:83]
	v_mfma_f32_16x16x32_bf16 v[88:91], v[236:239], v[148:151], v[88:91]
	v_mfma_f32_16x16x32_bf16 v[48:51], v[236:239], v[152:155], v[48:51]
	v_mfma_f32_16x16x32_bf16 v[56:59], v[236:239], v[156:159], v[56:59]
	s_waitcnt lgkmcnt(2)
	v_mfma_f32_16x16x32_bf16 v[84:87], v[240:243], v[144:147], v[84:87]
	v_mfma_f32_16x16x32_bf16 v[92:95], v[240:243], v[148:151], v[92:95]
	v_mfma_f32_16x16x32_bf16 v[52:55], v[240:243], v[152:155], v[52:55]
	v_mfma_f32_16x16x32_bf16 v[60:63], v[240:243], v[156:159], v[60:63]
	s_waitcnt lgkmcnt(1)
	v_mfma_f32_16x16x32_bf16 v[64:67], v[244:247], v[144:147], v[64:67]
	v_mfma_f32_16x16x32_bf16 v[72:75], v[244:247], v[148:151], v[72:75]
	v_mfma_f32_16x16x32_bf16 v[32:35], v[244:247], v[152:155], v[32:35]
	v_mfma_f32_16x16x32_bf16 v[40:43], v[244:247], v[156:159], v[40:43]
	s_waitcnt lgkmcnt(0)
	v_mfma_f32_16x16x32_bf16 v[68:71], v[248:251], v[144:147], v[68:71]
	v_mfma_f32_16x16x32_bf16 v[76:79], v[248:251], v[148:151], v[76:79]
	v_mfma_f32_16x16x32_bf16 v[36:39], v[248:251], v[152:155], v[36:39]
	v_mfma_f32_16x16x32_bf16 v[44:47], v[248:251], v[156:159], v[44:47]
	global_load_dwordx4 v[144:147], v[198:199], off
	global_load_dwordx4 v[148:151], v[198:199], off offset:256
	global_load_dwordx4 v[152:155], v[200:201], off
	global_load_dwordx4 v[156:159], v[200:201], off offset:256
	s_waitcnt vmcnt(10)
	s_barrier
	s_add_i32 s3, s1, 6
	s_lshl_b32 s96, s3, 13
	s_mov_b32 m0, vcc_lo
	v_lshl_add_u64 v[160:161], v[188:189], 0, s[96:97]
	global_load_lds_dwordx4 v[160:161], off
	global_load_lds_dwordx4 v[160:161], off offset:1024
	ds_read_b128 v[236:239], v196 offset:8192
	ds_read_b128 v[240:243], v162 offset:8192
	ds_read_b128 v[244:247], v196 offset:10240
	ds_read_b128 v[248:251], v162 offset:10240
	s_add_i32 s3, s1, 6
	s_lshl_b32 s96, s3, 11
	v_lshl_add_u64 v[198:199], v[184:185], 0, s[96:97]
	v_lshl_add_u64 v[200:201], v[186:187], 0, s[96:97]
	s_waitcnt vmcnt(8) lgkmcnt(3)
	v_mfma_f32_16x16x32_bf16 v[16:19], v[236:239], v[128:131], v[16:19]
	v_mfma_f32_16x16x32_bf16 v[24:27], v[236:239], v[132:135], v[24:27]
	v_mfma_f32_16x16x32_bf16 v[0:3], v[236:239], v[136:139], v[0:3]
	v_mfma_f32_16x16x32_bf16 v[8:11], v[236:239], v[140:143], v[8:11]
	ds_read_b128 v[236:239], v196 offset:12288
	s_waitcnt lgkmcnt(3)
	v_mfma_f32_16x16x32_bf16 v[20:23], v[240:243], v[128:131], v[20:23]
	v_mfma_f32_16x16x32_bf16 v[28:31], v[240:243], v[132:135], v[28:31]
	v_mfma_f32_16x16x32_bf16 v[4:7], v[240:243], v[136:139], v[4:7]
	v_mfma_f32_16x16x32_bf16 v[12:15], v[240:243], v[140:143], v[12:15]
	ds_read_b128 v[240:243], v162 offset:12288
	s_waitcnt lgkmcnt(3)
	v_mfma_f32_16x16x32_bf16 v[112:115], v[244:247], v[128:131], v[112:115]
	v_mfma_f32_16x16x32_bf16 v[120:123], v[244:247], v[132:135], v[120:123]
	v_mfma_f32_16x16x32_bf16 v[96:99], v[244:247], v[136:139], v[96:99]
	v_mfma_f32_16x16x32_bf16 v[104:107], v[244:247], v[140:143], v[104:107]
	ds_read_b128 v[244:247], v196 offset:14336
	s_waitcnt lgkmcnt(3)
	v_mfma_f32_16x16x32_bf16 v[116:119], v[248:251], v[128:131], v[116:119]
	v_mfma_f32_16x16x32_bf16 v[124:127], v[248:251], v[132:135], v[124:127]
	v_mfma_f32_16x16x32_bf16 v[100:103], v[248:251], v[136:139], v[100:103]
	v_mfma_f32_16x16x32_bf16 v[108:111], v[248:251], v[140:143], v[108:111]
	ds_read_b128 v[248:251], v162 offset:14336
	s_waitcnt lgkmcnt(3)
	v_mfma_f32_16x16x32_bf16 v[80:83], v[236:239], v[128:131], v[80:83]
	v_mfma_f32_16x16x32_bf16 v[88:91], v[236:239], v[132:135], v[88:91]
	v_mfma_f32_16x16x32_bf16 v[48:51], v[236:239], v[136:139], v[48:51]
	v_mfma_f32_16x16x32_bf16 v[56:59], v[236:239], v[140:143], v[56:59]
	s_waitcnt lgkmcnt(2)
	v_mfma_f32_16x16x32_bf16 v[84:87], v[240:243], v[128:131], v[84:87]
	v_mfma_f32_16x16x32_bf16 v[92:95], v[240:243], v[132:135], v[92:95]
	v_mfma_f32_16x16x32_bf16 v[52:55], v[240:243], v[136:139], v[52:55]
	v_mfma_f32_16x16x32_bf16 v[60:63], v[240:243], v[140:143], v[60:63]
	s_waitcnt lgkmcnt(1)
	v_mfma_f32_16x16x32_bf16 v[64:67], v[244:247], v[128:131], v[64:67]
	v_mfma_f32_16x16x32_bf16 v[72:75], v[244:247], v[132:135], v[72:75]
	v_mfma_f32_16x16x32_bf16 v[32:35], v[244:247], v[136:139], v[32:35]
	v_mfma_f32_16x16x32_bf16 v[40:43], v[244:247], v[140:143], v[40:43]
	s_waitcnt lgkmcnt(0)
	v_mfma_f32_16x16x32_bf16 v[68:71], v[248:251], v[128:131], v[68:71]
	v_mfma_f32_16x16x32_bf16 v[76:79], v[248:251], v[132:135], v[76:79]
	v_mfma_f32_16x16x32_bf16 v[36:39], v[248:251], v[136:139], v[36:39]
	v_mfma_f32_16x16x32_bf16 v[44:47], v[248:251], v[140:143], v[44:47]
	global_load_dwordx4 v[128:131], v[198:199], off
	global_load_dwordx4 v[132:135], v[198:199], off offset:256
	global_load_dwordx4 v[136:139], v[200:201], off
	global_load_dwordx4 v[140:143], v[200:201], off offset:256
	s_waitcnt vmcnt(10)
	s_barrier
	s_add_i32 s3, s1, 7
	s_lshl_b32 s96, s3, 13
	s_add_i32 m0, vcc_lo, 8192
	v_lshl_add_u64 v[160:161], v[188:189], 0, s[96:97]
	global_load_lds_dwordx4 v[160:161], off
	global_load_lds_dwordx4 v[160:161], off offset:1024
	ds_read_b128 v[236:239], v196 offset:16384
	ds_read_b128 v[240:243], v162 offset:16384
	ds_read_b128 v[244:247], v196 offset:18432
	ds_read_b128 v[248:251], v162 offset:18432
	s_add_i32 s3, s1, 7
	s_lshl_b32 s96, s3, 11
	v_lshl_add_u64 v[198:199], v[184:185], 0, s[96:97]
	v_lshl_add_u64 v[200:201], v[186:187], 0, s[96:97]
	s_waitcnt vmcnt(8) lgkmcnt(3)
	v_mfma_f32_16x16x32_bf16 v[16:19], v[236:239], v[144:147], v[16:19]
	v_mfma_f32_16x16x32_bf16 v[24:27], v[236:239], v[148:151], v[24:27]
	v_mfma_f32_16x16x32_bf16 v[0:3], v[236:239], v[152:155], v[0:3]
	v_mfma_f32_16x16x32_bf16 v[8:11], v[236:239], v[156:159], v[8:11]
	ds_read_b128 v[236:239], v196 offset:20480
	s_waitcnt lgkmcnt(3)
	v_mfma_f32_16x16x32_bf16 v[20:23], v[240:243], v[144:147], v[20:23]
	v_mfma_f32_16x16x32_bf16 v[28:31], v[240:243], v[148:151], v[28:31]
	v_mfma_f32_16x16x32_bf16 v[4:7], v[240:243], v[152:155], v[4:7]
	v_mfma_f32_16x16x32_bf16 v[12:15], v[240:243], v[156:159], v[12:15]
	ds_read_b128 v[240:243], v162 offset:20480
	s_waitcnt lgkmcnt(3)
	v_mfma_f32_16x16x32_bf16 v[112:115], v[244:247], v[144:147], v[112:115]
	v_mfma_f32_16x16x32_bf16 v[120:123], v[244:247], v[148:151], v[120:123]
	v_mfma_f32_16x16x32_bf16 v[96:99], v[244:247], v[152:155], v[96:99]
	v_mfma_f32_16x16x32_bf16 v[104:107], v[244:247], v[156:159], v[104:107]
	ds_read_b128 v[244:247], v196 offset:22528
	s_waitcnt lgkmcnt(3)
	v_mfma_f32_16x16x32_bf16 v[116:119], v[248:251], v[144:147], v[116:119]
	v_mfma_f32_16x16x32_bf16 v[124:127], v[248:251], v[148:151], v[124:127]
	v_mfma_f32_16x16x32_bf16 v[100:103], v[248:251], v[152:155], v[100:103]
	v_mfma_f32_16x16x32_bf16 v[108:111], v[248:251], v[156:159], v[108:111]
	ds_read_b128 v[248:251], v162 offset:22528
	s_waitcnt lgkmcnt(3)
	v_mfma_f32_16x16x32_bf16 v[80:83], v[236:239], v[144:147], v[80:83]
	v_mfma_f32_16x16x32_bf16 v[88:91], v[236:239], v[148:151], v[88:91]
	v_mfma_f32_16x16x32_bf16 v[48:51], v[236:239], v[152:155], v[48:51]
	v_mfma_f32_16x16x32_bf16 v[56:59], v[236:239], v[156:159], v[56:59]
	s_waitcnt lgkmcnt(2)
	v_mfma_f32_16x16x32_bf16 v[84:87], v[240:243], v[144:147], v[84:87]
	v_mfma_f32_16x16x32_bf16 v[92:95], v[240:243], v[148:151], v[92:95]
	v_mfma_f32_16x16x32_bf16 v[52:55], v[240:243], v[152:155], v[52:55]
	v_mfma_f32_16x16x32_bf16 v[60:63], v[240:243], v[156:159], v[60:63]
	s_waitcnt lgkmcnt(1)
	v_mfma_f32_16x16x32_bf16 v[64:67], v[244:247], v[144:147], v[64:67]
	v_mfma_f32_16x16x32_bf16 v[72:75], v[244:247], v[148:151], v[72:75]
	v_mfma_f32_16x16x32_bf16 v[32:35], v[244:247], v[152:155], v[32:35]
	v_mfma_f32_16x16x32_bf16 v[40:43], v[244:247], v[156:159], v[40:43]
	s_waitcnt lgkmcnt(0)
	v_mfma_f32_16x16x32_bf16 v[68:71], v[248:251], v[144:147], v[68:71]
	v_mfma_f32_16x16x32_bf16 v[76:79], v[248:251], v[148:151], v[76:79]
	v_mfma_f32_16x16x32_bf16 v[36:39], v[248:251], v[152:155], v[36:39]
	v_mfma_f32_16x16x32_bf16 v[44:47], v[248:251], v[156:159], v[44:47]
	global_load_dwordx4 v[144:147], v[198:199], off
	global_load_dwordx4 v[148:151], v[198:199], off offset:256
	global_load_dwordx4 v[152:155], v[200:201], off
	global_load_dwordx4 v[156:159], v[200:201], off offset:256
	s_waitcnt vmcnt(10)
	s_barrier
	s_add_i32 s1, s1, 6
	s_cmp_lt_u32 s1, 30
	s_cbranch_scc1 .Lg16_proj_k
	ds_read_b128 v[236:239], v196 offset:0
	ds_read_b128 v[240:243], v162 offset:0
	ds_read_b128 v[244:247], v196 offset:2048
	ds_read_b128 v[248:251], v162 offset:2048
	s_waitcnt vmcnt(6) lgkmcnt(3)
	v_mfma_f32_16x16x32_bf16 v[16:19], v[236:239], v[128:131], v[16:19]
	v_mfma_f32_16x16x32_bf16 v[24:27], v[236:239], v[132:135], v[24:27]
	v_mfma_f32_16x16x32_bf16 v[0:3], v[236:239], v[136:139], v[0:3]
	v_mfma_f32_16x16x32_bf16 v[8:11], v[236:239], v[140:143], v[8:11]
	ds_read_b128 v[236:239], v196 offset:4096
	s_waitcnt lgkmcnt(3)
	v_mfma_f32_16x16x32_bf16 v[20:23], v[240:243], v[128:131], v[20:23]
	v_mfma_f32_16x16x32_bf16 v[28:31], v[240:243], v[132:135], v[28:31]
	v_mfma_f32_16x16x32_bf16 v[4:7], v[240:243], v[136:139], v[4:7]
	v_mfma_f32_16x16x32_bf16 v[12:15], v[240:243], v[140:143], v[12:15]
	ds_read_b128 v[240:243], v162 offset:4096
	s_waitcnt lgkmcnt(3)
	v_mfma_f32_16x16x32_bf16 v[112:115], v[244:247], v[128:131], v[112:115]
	v_mfma_f32_16x16x32_bf16 v[120:123], v[244:247], v[132:135], v[120:123]
	v_mfma_f32_16x16x32_bf16 v[96:99], v[244:247], v[136:139], v[96:99]
	v_mfma_f32_16x16x32_bf16 v[104:107], v[244:247], v[140:143], v[104:107]
	ds_read_b128 v[244:247], v196 offset:6144
	s_waitcnt lgkmcnt(3)
	v_mfma_f32_16x16x32_bf16 v[116:119], v[248:251], v[128:131], v[116:119]
	v_mfma_f32_16x16x32_bf16 v[124:127], v[248:251], v[132:135], v[124:127]
	v_mfma_f32_16x16x32_bf16 v[100:103], v[248:251], v[136:139], v[100:103]
	v_mfma_f32_16x16x32_bf16 v[108:111], v[248:251], v[140:143], v[108:111]
	ds_read_b128 v[248:251], v162 offset:6144
	s_waitcnt lgkmcnt(3)
	v_mfma_f32_16x16x32_bf16 v[80:83], v[236:239], v[128:131], v[80:83]
	v_mfma_f32_16x16x32_bf16 v[88:91], v[236:239], v[132:135], v[88:91]
	v_mfma_f32_16x16x32_bf16 v[48:51], v[236:239], v[136:139], v[48:51]
	v_mfma_f32_16x16x32_bf16 v[56:59], v[236:239], v[140:143], v[56:59]
	s_waitcnt lgkmcnt(2)
	v_mfma_f32_16x16x32_bf16 v[84:87], v[240:243], v[128:131], v[84:87]
	v_mfma_f32_16x16x32_bf16 v[92:95], v[240:243], v[132:135], v[92:95]
	v_mfma_f32_16x16x32_bf16 v[52:55], v[240:243], v[136:139], v[52:55]
	v_mfma_f32_16x16x32_bf16 v[60:63], v[240:243], v[140:143], v[60:63]
	s_waitcnt lgkmcnt(1)
	v_mfma_f32_16x16x32_bf16 v[64:67], v[244:247], v[128:131], v[64:67]
	v_mfma_f32_16x16x32_bf16 v[72:75], v[244:247], v[132:135], v[72:75]
	v_mfma_f32_16x16x32_bf16 v[32:35], v[244:247], v[136:139], v[32:35]
	v_mfma_f32_16x16x32_bf16 v[40:43], v[244:247], v[140:143], v[40:43]
	s_waitcnt lgkmcnt(0)
	v_mfma_f32_16x16x32_bf16 v[68:71], v[248:251], v[128:131], v[68:71]
	v_mfma_f32_16x16x32_bf16 v[76:79], v[248:251], v[132:135], v[76:79]
	v_mfma_f32_16x16x32_bf16 v[36:39], v[248:251], v[136:139], v[36:39]
	v_mfma_f32_16x16x32_bf16 v[44:47], v[248:251], v[140:143], v[44:47]
	s_waitcnt vmcnt(4)
	s_barrier
	ds_read_b128 v[236:239], v196 offset:8192
	ds_read_b128 v[240:243], v162 offset:8192
	ds_read_b128 v[244:247], v196 offset:10240
	ds_read_b128 v[248:251], v162 offset:10240
	s_waitcnt vmcnt(0) lgkmcnt(3)
	v_mfma_f32_16x16x32_bf16 v[16:19], v[236:239], v[144:147], v[16:19]
	v_mfma_f32_16x16x32_bf16 v[24:27], v[236:239], v[148:151], v[24:27]
	v_mfma_f32_16x16x32_bf16 v[0:3], v[236:239], v[152:155], v[0:3]
	v_mfma_f32_16x16x32_bf16 v[8:11], v[236:239], v[156:159], v[8:11]
	ds_read_b128 v[236:239], v196 offset:12288
	s_waitcnt lgkmcnt(3)
	v_mfma_f32_16x16x32_bf16 v[20:23], v[240:243], v[144:147], v[20:23]
	v_mfma_f32_16x16x32_bf16 v[28:31], v[240:243], v[148:151], v[28:31]
	v_mfma_f32_16x16x32_bf16 v[4:7], v[240:243], v[152:155], v[4:7]
	v_mfma_f32_16x16x32_bf16 v[12:15], v[240:243], v[156:159], v[12:15]
	ds_read_b128 v[240:243], v162 offset:12288
	s_waitcnt lgkmcnt(3)
	v_mfma_f32_16x16x32_bf16 v[112:115], v[244:247], v[144:147], v[112:115]
	v_mfma_f32_16x16x32_bf16 v[120:123], v[244:247], v[148:151], v[120:123]
	v_mfma_f32_16x16x32_bf16 v[96:99], v[244:247], v[152:155], v[96:99]
	v_mfma_f32_16x16x32_bf16 v[104:107], v[244:247], v[156:159], v[104:107]
	ds_read_b128 v[244:247], v196 offset:14336
	s_waitcnt lgkmcnt(3)
	v_mfma_f32_16x16x32_bf16 v[116:119], v[248:251], v[144:147], v[116:119]
	v_mfma_f32_16x16x32_bf16 v[124:127], v[248:251], v[148:151], v[124:127]
	v_mfma_f32_16x16x32_bf16 v[100:103], v[248:251], v[152:155], v[100:103]
	v_mfma_f32_16x16x32_bf16 v[108:111], v[248:251], v[156:159], v[108:111]
	ds_read_b128 v[248:251], v162 offset:14336
	s_waitcnt lgkmcnt(3)
	v_mfma_f32_16x16x32_bf16 v[80:83], v[236:239], v[144:147], v[80:83]
	v_mfma_f32_16x16x32_bf16 v[88:91], v[236:239], v[148:151], v[88:91]
	v_mfma_f32_16x16x32_bf16 v[48:51], v[236:239], v[152:155], v[48:51]
	v_mfma_f32_16x16x32_bf16 v[56:59], v[236:239], v[156:159], v[56:59]
	s_waitcnt lgkmcnt(2)
	v_mfma_f32_16x16x32_bf16 v[84:87], v[240:243], v[144:147], v[84:87]
	v_mfma_f32_16x16x32_bf16 v[92:95], v[240:243], v[148:151], v[92:95]
	v_mfma_f32_16x16x32_bf16 v[52:55], v[240:243], v[152:155], v[52:55]
	v_mfma_f32_16x16x32_bf16 v[60:63], v[240:243], v[156:159], v[60:63]
	s_waitcnt lgkmcnt(1)
	v_mfma_f32_16x16x32_bf16 v[64:67], v[244:247], v[144:147], v[64:67]
	v_mfma_f32_16x16x32_bf16 v[72:75], v[244:247], v[148:151], v[72:75]
	v_mfma_f32_16x16x32_bf16 v[32:35], v[244:247], v[152:155], v[32:35]
	v_mfma_f32_16x16x32_bf16 v[40:43], v[244:247], v[156:159], v[40:43]
	s_waitcnt lgkmcnt(0)
	v_mfma_f32_16x16x32_bf16 v[68:71], v[248:251], v[144:147], v[68:71]
	v_mfma_f32_16x16x32_bf16 v[76:79], v[248:251], v[148:151], v[76:79]
	v_mfma_f32_16x16x32_bf16 v[36:39], v[248:251], v[152:155], v[36:39]
	v_mfma_f32_16x16x32_bf16 v[44:47], v[248:251], v[156:159], v[44:47]
	s_barrier
	s_nop 7
	s_nop 1
	s_waitcnt vmcnt(0)
	s_waitcnt vmcnt(0)
	v_and_b32_e32 v128, 63, v179
	v_lshrrev_b32_e32 v129, 6, v179
	s_lshl_b32 s20, s2, 8
	s_cmp_eq_u32 s0, 23
	s_cbranch_scc1 .Lpe_proj_ab
	v_readlane_b32 s14, v254, 15
	v_readlane_b32 s15, v254, 16
	v_readlane_b32 s16, v254, 17
	v_readlane_b32 s17, v254, 18
	s_movk_i32 s22, 0x900
	s_movk_i32 s23, 0x300
	s_cmp_lt_u32 s0, 20
	s_cselect_b32 s14, s14, s16
	s_cselect_b32 s15, s15, s17
	s_cselect_b32 s18, s22, s23
	s_movk_i32 s22, 0xf500
	s_movk_i32 s23, 0xec00
	s_cselect_b32 s19, s22, s23
	s_movk_i32 s22, 0xb00
	s_cmp_lt_u32 s0, 11
	s_cselect_b32 s14, s66, s14
	s_cselect_b32 s15, s67, s15
	s_cselect_b32 s18, s22, s18
	s_cselect_b32 s19, 0, s19
	s_mul_hi_u32 s21, s20, s18
	s_mul_i32 s20, s20, s18
	s_lshl_b32 s22, s0, 8
	s_add_i32 s22, s22, s19
	s_add_u32 s12, s14, s20
	s_addc_u32 s13, s15, s21
	s_add_u32 s12, s12, s22
	s_addc_u32 s13, s13, 0
	v_mul_u32_u24_e32 v188, 0x2400, v129
	v_and_b32_e32 v189, 15, v128
	v_mul_u32_u24_e32 v189, 0x90, v189
	v_add_u32_e32 v130, v188, v189
	v_lshrrev_b32_e32 v189, 4, v128
	v_lshl_add_u32 v130, v189, 4, v130
	v_lshrrev_b32_e32 v189, 3, v128
	v_mul_u32_u24_e32 v132, 0x90, v189
	v_add_u32_e32 v131, v188, v132
	v_and_b32_e32 v188, 7, v128
	v_lshlrev_b32_e32 v188, 4, v188
	v_add_u32_e32 v131, v131, v188
	v_lshl_add_u32 v189, v129, 6, v189
	v_add_u32_e32 v132, 0, v189
	v_add_u32_e32 v133, 8, v189
	v_add_u32_e32 v134, 16, v189
	v_add_u32_e32 v135, 24, v189
	v_add_u32_e32 v136, 32, v189
	v_add_u32_e32 v137, 40, v189
	v_add_u32_e32 v138, 48, v189
	v_add_u32_e32 v139, 56, v189
	v_mul_lo_u32 v132, v132, s18
	v_mul_lo_u32 v133, v133, s18
	v_mul_lo_u32 v134, v134, s18
	v_mul_lo_u32 v135, v135, s18
	v_mul_lo_u32 v136, v136, s18
	v_mul_lo_u32 v137, v137, s18
	v_mul_lo_u32 v138, v138, s18
	v_mul_lo_u32 v139, v139, s18
	v_add_u32_e32 v132, v132, v188
	v_add_u32_e32 v133, v133, v188
	v_add_u32_e32 v134, v134, v188
	v_add_u32_e32 v135, v135, v188
	v_add_u32_e32 v136, v136, v188
	v_add_u32_e32 v137, v137, v188
	v_add_u32_e32 v138, v138, v188
	v_add_u32_e32 v139, v139, v188
	v_cvt_pk_bf16_f32 v140, v16, v17
	v_cvt_pk_bf16_f32 v141, v18, v19
	v_cvt_pk_bf16_f32 v142, v20, v21
	v_cvt_pk_bf16_f32 v143, v22, v23
	ds_write_b128 v130, v[140:143]
	v_cvt_pk_bf16_f32 v144, v112, v113
	v_cvt_pk_bf16_f32 v145, v114, v115
	v_cvt_pk_bf16_f32 v146, v116, v117
	v_cvt_pk_bf16_f32 v147, v118, v119
	ds_write_b128 v130, v[144:147] offset:64
	v_cvt_pk_bf16_f32 v140, v24, v25
	v_cvt_pk_bf16_f32 v141, v26, v27
	v_cvt_pk_bf16_f32 v142, v28, v29
	v_cvt_pk_bf16_f32 v143, v30, v31
	ds_write_b128 v130, v[140:143] offset:2304
	v_cvt_pk_bf16_f32 v144, v120, v121
	v_cvt_pk_bf16_f32 v145, v122, v123
	v_cvt_pk_bf16_f32 v146, v124, v125
	v_cvt_pk_bf16_f32 v147, v126, v127
	ds_write_b128 v130, v[144:147] offset:2368
	v_cvt_pk_bf16_f32 v140, v0, v1
	v_cvt_pk_bf16_f32 v141, v2, v3
	v_cvt_pk_bf16_f32 v142, v4, v5
	v_cvt_pk_bf16_f32 v143, v6, v7
	ds_write_b128 v130, v[140:143] offset:4608
	v_cvt_pk_bf16_f32 v144, v96, v97
	v_cvt_pk_bf16_f32 v145, v98, v99
	v_cvt_pk_bf16_f32 v146, v100, v101
	v_cvt_pk_bf16_f32 v147, v102, v103
	ds_write_b128 v130, v[144:147] offset:4672
	v_cvt_pk_bf16_f32 v140, v8, v9
	v_cvt_pk_bf16_f32 v141, v10, v11
	v_cvt_pk_bf16_f32 v142, v12, v13
	v_cvt_pk_bf16_f32 v143, v14, v15
	ds_write_b128 v130, v[140:143] offset:6912
	v_cvt_pk_bf16_f32 v144, v104, v105
	v_cvt_pk_bf16_f32 v145, v106, v107
	v_cvt_pk_bf16_f32 v146, v108, v109
	v_cvt_pk_bf16_f32 v147, v110, v111
	ds_write_b128 v130, v[144:147] offset:6976
	s_waitcnt lgkmcnt(0)
	ds_read_b128 v[148:151], v131
	ds_read_b128 v[152:155], v131 offset:1152
	ds_read_b128 v[156:159], v131 offset:2304
	ds_read_b128 v[160:163], v131 offset:3456
	ds_read_b128 v[164:167], v131 offset:4608
	ds_read_b128 v[168:171], v131 offset:5760
	ds_read_b128 v[172:175], v131 offset:6912
	ds_read_b128 v[184:187], v131 offset:8064
	s_waitcnt lgkmcnt(7)
	global_store_dwordx4 v132, v[148:151], s[12:13] sc1
	s_waitcnt lgkmcnt(6)
	global_store_dwordx4 v133, v[152:155], s[12:13] sc1
	s_waitcnt lgkmcnt(5)
	global_store_dwordx4 v134, v[156:159], s[12:13] sc1
	s_waitcnt lgkmcnt(4)
	global_store_dwordx4 v135, v[160:163], s[12:13] sc1
	s_waitcnt lgkmcnt(3)
	global_store_dwordx4 v136, v[164:167], s[12:13] sc1
	s_waitcnt lgkmcnt(2)
	global_store_dwordx4 v137, v[168:171], s[12:13] sc1
	s_waitcnt lgkmcnt(1)
	global_store_dwordx4 v138, v[172:175], s[12:13] sc1
	s_waitcnt lgkmcnt(0)
	global_store_dwordx4 v139, v[184:187], s[12:13] sc1
	v_cvt_pk_bf16_f32 v140, v80, v81
	v_cvt_pk_bf16_f32 v141, v82, v83
	v_cvt_pk_bf16_f32 v142, v84, v85
	v_cvt_pk_bf16_f32 v143, v86, v87
	ds_write_b128 v130, v[140:143]
	v_cvt_pk_bf16_f32 v144, v64, v65
	v_cvt_pk_bf16_f32 v145, v66, v67
	v_cvt_pk_bf16_f32 v146, v68, v69
	v_cvt_pk_bf16_f32 v147, v70, v71
	ds_write_b128 v130, v[144:147] offset:64
	v_cvt_pk_bf16_f32 v140, v88, v89
	v_cvt_pk_bf16_f32 v141, v90, v91
	v_cvt_pk_bf16_f32 v142, v92, v93
	v_cvt_pk_bf16_f32 v143, v94, v95
	ds_write_b128 v130, v[140:143] offset:2304
	v_cvt_pk_bf16_f32 v144, v72, v73
	v_cvt_pk_bf16_f32 v145, v74, v75
	v_cvt_pk_bf16_f32 v146, v76, v77
	v_cvt_pk_bf16_f32 v147, v78, v79
	ds_write_b128 v130, v[144:147] offset:2368
	v_cvt_pk_bf16_f32 v140, v48, v49
	v_cvt_pk_bf16_f32 v141, v50, v51
	v_cvt_pk_bf16_f32 v142, v52, v53
	v_cvt_pk_bf16_f32 v143, v54, v55
	ds_write_b128 v130, v[140:143] offset:4608
	v_cvt_pk_bf16_f32 v144, v32, v33
	v_cvt_pk_bf16_f32 v145, v34, v35
	v_cvt_pk_bf16_f32 v146, v36, v37
	v_cvt_pk_bf16_f32 v147, v38, v39
	ds_write_b128 v130, v[144:147] offset:4672
	v_cvt_pk_bf16_f32 v140, v56, v57
	v_cvt_pk_bf16_f32 v141, v58, v59
	v_cvt_pk_bf16_f32 v142, v60, v61
	v_cvt_pk_bf16_f32 v143, v62, v63
	ds_write_b128 v130, v[140:143] offset:6912
	v_cvt_pk_bf16_f32 v144, v40, v41
	v_cvt_pk_bf16_f32 v145, v42, v43
	v_cvt_pk_bf16_f32 v146, v44, v45
	v_cvt_pk_bf16_f32 v147, v46, v47
	ds_write_b128 v130, v[144:147] offset:6976
	s_waitcnt lgkmcnt(0)
	ds_read_b128 v[148:151], v131
	ds_read_b128 v[152:155], v131 offset:1152
	ds_read_b128 v[156:159], v131 offset:2304
	ds_read_b128 v[160:163], v131 offset:3456
	ds_read_b128 v[164:167], v131 offset:4608
	ds_read_b128 v[168:171], v131 offset:5760
	ds_read_b128 v[172:175], v131 offset:6912
	ds_read_b128 v[184:187], v131 offset:8064
	s_waitcnt lgkmcnt(7)
	global_store_dwordx4 v132, v[148:151], s[12:13] offset:128 sc1
	s_waitcnt lgkmcnt(6)
	global_store_dwordx4 v133, v[152:155], s[12:13] offset:128 sc1
	s_waitcnt lgkmcnt(5)
	global_store_dwordx4 v134, v[156:159], s[12:13] offset:128 sc1
	s_waitcnt lgkmcnt(4)
	global_store_dwordx4 v135, v[160:163], s[12:13] offset:128 sc1
	s_waitcnt lgkmcnt(3)
	global_store_dwordx4 v136, v[164:167], s[12:13] offset:128 sc1
	s_waitcnt lgkmcnt(2)
	global_store_dwordx4 v137, v[168:171], s[12:13] offset:128 sc1
	s_waitcnt lgkmcnt(1)
	global_store_dwordx4 v138, v[172:175], s[12:13] offset:128 sc1
	s_waitcnt lgkmcnt(0)
	global_store_dwordx4 v139, v[184:187], s[12:13] offset:128 sc1
	s_branch .Lpe_proj_end
.Lpe_proj_ab:
	v_readlane_b32 s14, v254, 19
	v_readlane_b32 s15, v254, 20
	s_mul_i32 s20, s20, 0x60
	s_add_u32 s12, s14, s20
	s_addc_u32 s13, s15, 0
	v_and_b32_e32 v189, 15, v128
	v_lshl_add_u32 v189, v129, 6, v189
	v_mul_u32_u24_e32 v189, 0x60, v189
	v_lshrrev_b32_e32 v188, 4, v128
	v_lshl_add_u32 v189, v188, 5, v189
	v_cmp_gt_u32_e32 vcc, 48, v128
	s_and_saveexec_b64 s[14:15], vcc
	global_store_dwordx4 v189, v[16:19], s[12:13] sc1
	global_store_dwordx4 v189, v[20:23], s[12:13] offset:16 sc1
	global_store_dwordx4 v189, v[24:27], s[12:13] offset:1536 sc1
	global_store_dwordx4 v189, v[28:31], s[12:13] offset:1552 sc1
	s_add_u32 s12, s12, 0xc00
	s_addc_u32 s13, s13, 0
	global_store_dwordx4 v189, v[0:3], s[12:13] sc1
	global_store_dwordx4 v189, v[4:7], s[12:13] offset:16 sc1
	global_store_dwordx4 v189, v[8:11], s[12:13] offset:1536 sc1
	global_store_dwordx4 v189, v[12:15], s[12:13] offset:1552 sc1
	s_mov_b64 exec, s[14:15]

.Lg16_out_k:
	s_add_i32 s9, s3, 2
	s_lshl_b32 s96, s9, 13
	s_add_i32 m0, vcc_lo, 16384
	v_lshl_add_u64 v[160:161], v[188:189], 0, s[96:97]
	global_load_lds_dwordx4 v[160:161], off
	global_load_lds_dwordx4 v[160:161], off offset:1024
	ds_read_b128 v[196:199], v246 offset:0
	ds_read_b128 v[200:203], v162 offset:0
	ds_read_b128 v[204:207], v246 offset:2048
	ds_read_b128 v[242:245], v162 offset:2048
	s_add_i32 s9, s3, 2
	s_lshl_b32 s96, s9, 11
	v_lshl_add_u64 v[248:249], v[184:185], 0, s[96:97]
	v_lshl_add_u64 v[250:251], v[186:187], 0, s[96:97]
	s_waitcnt vmcnt(8) lgkmcnt(3)
	v_mfma_f32_16x16x32_bf16 v[112:115], v[196:199], v[128:131], v[112:115]
	v_mfma_f32_16x16x32_bf16 v[120:123], v[196:199], v[132:135], v[120:123]
	v_mfma_f32_16x16x32_bf16 v[48:51], v[196:199], v[136:139], v[48:51]
	v_mfma_f32_16x16x32_bf16 v[56:59], v[196:199], v[140:143], v[56:59]
	ds_read_b128 v[196:199], v246 offset:4096
	s_waitcnt lgkmcnt(3)
	v_mfma_f32_16x16x32_bf16 v[116:119], v[200:203], v[128:131], v[116:119]
	v_mfma_f32_16x16x32_bf16 v[124:127], v[200:203], v[132:135], v[124:127]
	v_mfma_f32_16x16x32_bf16 v[52:55], v[200:203], v[136:139], v[52:55]
	v_mfma_f32_16x16x32_bf16 v[60:63], v[200:203], v[140:143], v[60:63]
	ds_read_b128 v[200:203], v162 offset:4096
	s_waitcnt lgkmcnt(3)
	v_mfma_f32_16x16x32_bf16 v[96:99], v[204:207], v[128:131], v[96:99]
	v_mfma_f32_16x16x32_bf16 v[104:107], v[204:207], v[132:135], v[104:107]
	v_mfma_f32_16x16x32_bf16 v[32:35], v[204:207], v[136:139], v[32:35]
	v_mfma_f32_16x16x32_bf16 v[40:43], v[204:207], v[140:143], v[40:43]
	ds_read_b128 v[204:207], v246 offset:6144
	s_waitcnt lgkmcnt(3)
	v_mfma_f32_16x16x32_bf16 v[100:103], v[242:245], v[128:131], v[100:103]
	v_mfma_f32_16x16x32_bf16 v[108:111], v[242:245], v[132:135], v[108:111]
	v_mfma_f32_16x16x32_bf16 v[36:39], v[242:245], v[136:139], v[36:39]
	v_mfma_f32_16x16x32_bf16 v[44:47], v[242:245], v[140:143], v[44:47]
	ds_read_b128 v[242:245], v162 offset:6144
	s_waitcnt lgkmcnt(3)
	v_mfma_f32_16x16x32_bf16 v[80:83], v[196:199], v[128:131], v[80:83]
	v_mfma_f32_16x16x32_bf16 v[88:91], v[196:199], v[132:135], v[88:91]
	v_mfma_f32_16x16x32_bf16 v[16:19], v[196:199], v[136:139], v[16:19]
	v_mfma_f32_16x16x32_bf16 v[24:27], v[196:199], v[140:143], v[24:27]
	s_waitcnt lgkmcnt(2)
	v_mfma_f32_16x16x32_bf16 v[84:87], v[200:203], v[128:131], v[84:87]
	v_mfma_f32_16x16x32_bf16 v[92:95], v[200:203], v[132:135], v[92:95]
	v_mfma_f32_16x16x32_bf16 v[20:23], v[200:203], v[136:139], v[20:23]
	v_mfma_f32_16x16x32_bf16 v[28:31], v[200:203], v[140:143], v[28:31]
	s_waitcnt lgkmcnt(1)
	v_mfma_f32_16x16x32_bf16 v[64:67], v[204:207], v[128:131], v[64:67]
	v_mfma_f32_16x16x32_bf16 v[72:75], v[204:207], v[132:135], v[72:75]
	v_mfma_f32_16x16x32_bf16 v[0:3], v[204:207], v[136:139], v[0:3]
	v_mfma_f32_16x16x32_bf16 v[8:11], v[204:207], v[140:143], v[8:11]
	s_waitcnt lgkmcnt(0)
	v_mfma_f32_16x16x32_bf16 v[68:71], v[242:245], v[128:131], v[68:71]
	v_mfma_f32_16x16x32_bf16 v[76:79], v[242:245], v[132:135], v[76:79]
	v_mfma_f32_16x16x32_bf16 v[4:7], v[242:245], v[136:139], v[4:7]
	v_mfma_f32_16x16x32_bf16 v[12:15], v[242:245], v[140:143], v[12:15]
	global_load_dwordx4 v[128:131], v[248:249], off
	global_load_dwordx4 v[132:135], v[248:249], off offset:256
	global_load_dwordx4 v[136:139], v[250:251], off
	global_load_dwordx4 v[140:143], v[250:251], off offset:256
	s_waitcnt vmcnt(10)
	s_barrier
	s_add_i32 s9, s3, 3
	s_lshl_b32 s96, s9, 13
	s_mov_b32 m0, vcc_lo
	v_lshl_add_u64 v[160:161], v[188:189], 0, s[96:97]
	global_load_lds_dwordx4 v[160:161], off
	global_load_lds_dwordx4 v[160:161], off offset:1024
	ds_read_b128 v[196:199], v246 offset:8192
	ds_read_b128 v[200:203], v162 offset:8192
	ds_read_b128 v[204:207], v246 offset:10240
	ds_read_b128 v[242:245], v162 offset:10240
	s_add_i32 s9, s3, 3
	s_lshl_b32 s96, s9, 11
	v_lshl_add_u64 v[248:249], v[184:185], 0, s[96:97]
	v_lshl_add_u64 v[250:251], v[186:187], 0, s[96:97]
	s_waitcnt vmcnt(8) lgkmcnt(3)
	v_mfma_f32_16x16x32_bf16 v[112:115], v[196:199], v[144:147], v[112:115]
	v_mfma_f32_16x16x32_bf16 v[120:123], v[196:199], v[148:151], v[120:123]
	v_mfma_f32_16x16x32_bf16 v[48:51], v[196:199], v[152:155], v[48:51]
	v_mfma_f32_16x16x32_bf16 v[56:59], v[196:199], v[156:159], v[56:59]
	ds_read_b128 v[196:199], v246 offset:12288
	s_waitcnt lgkmcnt(3)
	v_mfma_f32_16x16x32_bf16 v[116:119], v[200:203], v[144:147], v[116:119]
	v_mfma_f32_16x16x32_bf16 v[124:127], v[200:203], v[148:151], v[124:127]
	v_mfma_f32_16x16x32_bf16 v[52:55], v[200:203], v[152:155], v[52:55]
	v_mfma_f32_16x16x32_bf16 v[60:63], v[200:203], v[156:159], v[60:63]
	ds_read_b128 v[200:203], v162 offset:12288
	s_waitcnt lgkmcnt(3)
	v_mfma_f32_16x16x32_bf16 v[96:99], v[204:207], v[144:147], v[96:99]
	v_mfma_f32_16x16x32_bf16 v[104:107], v[204:207], v[148:151], v[104:107]
	v_mfma_f32_16x16x32_bf16 v[32:35], v[204:207], v[152:155], v[32:35]
	v_mfma_f32_16x16x32_bf16 v[40:43], v[204:207], v[156:159], v[40:43]
	ds_read_b128 v[204:207], v246 offset:14336
	s_waitcnt lgkmcnt(3)
	v_mfma_f32_16x16x32_bf16 v[100:103], v[242:245], v[144:147], v[100:103]
	v_mfma_f32_16x16x32_bf16 v[108:111], v[242:245], v[148:151], v[108:111]
	v_mfma_f32_16x16x32_bf16 v[36:39], v[242:245], v[152:155], v[36:39]
	v_mfma_f32_16x16x32_bf16 v[44:47], v[242:245], v[156:159], v[44:47]
	ds_read_b128 v[242:245], v162 offset:14336
	s_waitcnt lgkmcnt(3)
	v_mfma_f32_16x16x32_bf16 v[80:83], v[196:199], v[144:147], v[80:83]
	v_mfma_f32_16x16x32_bf16 v[88:91], v[196:199], v[148:151], v[88:91]
	v_mfma_f32_16x16x32_bf16 v[16:19], v[196:199], v[152:155], v[16:19]
	v_mfma_f32_16x16x32_bf16 v[24:27], v[196:199], v[156:159], v[24:27]
	s_waitcnt lgkmcnt(2)
	v_mfma_f32_16x16x32_bf16 v[84:87], v[200:203], v[144:147], v[84:87]
	v_mfma_f32_16x16x32_bf16 v[92:95], v[200:203], v[148:151], v[92:95]
	v_mfma_f32_16x16x32_bf16 v[20:23], v[200:203], v[152:155], v[20:23]
	v_mfma_f32_16x16x32_bf16 v[28:31], v[200:203], v[156:159], v[28:31]
	s_waitcnt lgkmcnt(1)
	v_mfma_f32_16x16x32_bf16 v[64:67], v[204:207], v[144:147], v[64:67]
	v_mfma_f32_16x16x32_bf16 v[72:75], v[204:207], v[148:151], v[72:75]
	v_mfma_f32_16x16x32_bf16 v[0:3], v[204:207], v[152:155], v[0:3]
	v_mfma_f32_16x16x32_bf16 v[8:11], v[204:207], v[156:159], v[8:11]
	s_waitcnt lgkmcnt(0)
	v_mfma_f32_16x16x32_bf16 v[68:71], v[242:245], v[144:147], v[68:71]
	v_mfma_f32_16x16x32_bf16 v[76:79], v[242:245], v[148:151], v[76:79]
	v_mfma_f32_16x16x32_bf16 v[4:7], v[242:245], v[152:155], v[4:7]
	v_mfma_f32_16x16x32_bf16 v[12:15], v[242:245], v[156:159], v[12:15]
	global_load_dwordx4 v[144:147], v[248:249], off
	global_load_dwordx4 v[148:151], v[248:249], off offset:256
	global_load_dwordx4 v[152:155], v[250:251], off
	global_load_dwordx4 v[156:159], v[250:251], off offset:256
	s_waitcnt vmcnt(10)
	s_barrier
	s_add_i32 s9, s3, 4
	s_lshl_b32 s96, s9, 13
	s_add_i32 m0, vcc_lo, 8192
	v_lshl_add_u64 v[160:161], v[188:189], 0, s[96:97]
	global_load_lds_dwordx4 v[160:161], off
	global_load_lds_dwordx4 v[160:161], off offset:1024
	ds_read_b128 v[196:199], v246 offset:16384
	ds_read_b128 v[200:203], v162 offset:16384
	ds_read_b128 v[204:207], v246 offset:18432
	ds_read_b128 v[242:245], v162 offset:18432
	s_add_i32 s9, s3, 4
	s_lshl_b32 s96, s9, 11
	v_lshl_add_u64 v[248:249], v[184:185], 0, s[96:97]
	v_lshl_add_u64 v[250:251], v[186:187], 0, s[96:97]
	s_waitcnt vmcnt(8) lgkmcnt(3)
	v_mfma_f32_16x16x32_bf16 v[112:115], v[196:199], v[128:131], v[112:115]
	v_mfma_f32_16x16x32_bf16 v[120:123], v[196:199], v[132:135], v[120:123]
	v_mfma_f32_16x16x32_bf16 v[48:51], v[196:199], v[136:139], v[48:51]
	v_mfma_f32_16x16x32_bf16 v[56:59], v[196:199], v[140:143], v[56:59]
	ds_read_b128 v[196:199], v246 offset:20480
	s_waitcnt lgkmcnt(3)
	v_mfma_f32_16x16x32_bf16 v[116:119], v[200:203], v[128:131], v[116:119]
	v_mfma_f32_16x16x32_bf16 v[124:127], v[200:203], v[132:135], v[124:127]
	v_mfma_f32_16x16x32_bf16 v[52:55], v[200:203], v[136:139], v[52:55]
	v_mfma_f32_16x16x32_bf16 v[60:63], v[200:203], v[140:143], v[60:63]
	ds_read_b128 v[200:203], v162 offset:20480
	s_waitcnt lgkmcnt(3)
	v_mfma_f32_16x16x32_bf16 v[96:99], v[204:207], v[128:131], v[96:99]
	v_mfma_f32_16x16x32_bf16 v[104:107], v[204:207], v[132:135], v[104:107]
	v_mfma_f32_16x16x32_bf16 v[32:35], v[204:207], v[136:139], v[32:35]
	v_mfma_f32_16x16x32_bf16 v[40:43], v[204:207], v[140:143], v[40:43]
	ds_read_b128 v[204:207], v246 offset:22528
	s_waitcnt lgkmcnt(3)
	v_mfma_f32_16x16x32_bf16 v[100:103], v[242:245], v[128:131], v[100:103]
	v_mfma_f32_16x16x32_bf16 v[108:111], v[242:245], v[132:135], v[108:111]
	v_mfma_f32_16x16x32_bf16 v[36:39], v[242:245], v[136:139], v[36:39]
	v_mfma_f32_16x16x32_bf16 v[44:47], v[242:245], v[140:143], v[44:47]
	ds_read_b128 v[242:245], v162 offset:22528
	s_waitcnt lgkmcnt(3)
	v_mfma_f32_16x16x32_bf16 v[80:83], v[196:199], v[128:131], v[80:83]
	v_mfma_f32_16x16x32_bf16 v[88:91], v[196:199], v[132:135], v[88:91]
	v_mfma_f32_16x16x32_bf16 v[16:19], v[196:199], v[136:139], v[16:19]
	v_mfma_f32_16x16x32_bf16 v[24:27], v[196:199], v[140:143], v[24:27]
	s_waitcnt lgkmcnt(2)
	v_mfma_f32_16x16x32_bf16 v[84:87], v[200:203], v[128:131], v[84:87]
	v_mfma_f32_16x16x32_bf16 v[92:95], v[200:203], v[132:135], v[92:95]
	v_mfma_f32_16x16x32_bf16 v[20:23], v[200:203], v[136:139], v[20:23]
	v_mfma_f32_16x16x32_bf16 v[28:31], v[200:203], v[140:143], v[28:31]
	s_waitcnt lgkmcnt(1)
	v_mfma_f32_16x16x32_bf16 v[64:67], v[204:207], v[128:131], v[64:67]
	v_mfma_f32_16x16x32_bf16 v[72:75], v[204:207], v[132:135], v[72:75]
	v_mfma_f32_16x16x32_bf16 v[0:3], v[204:207], v[136:139], v[0:3]
	v_mfma_f32_16x16x32_bf16 v[8:11], v[204:207], v[140:143], v[8:11]
	s_waitcnt lgkmcnt(0)
	v_mfma_f32_16x16x32_bf16 v[68:71], v[242:245], v[128:131], v[68:71]
	v_mfma_f32_16x16x32_bf16 v[76:79], v[242:245], v[132:135], v[76:79]
	v_mfma_f32_16x16x32_bf16 v[4:7], v[242:245], v[136:139], v[4:7]
	v_mfma_f32_16x16x32_bf16 v[12:15], v[242:245], v[140:143], v[12:15]
	global_load_dwordx4 v[128:131], v[248:249], off
	global_load_dwordx4 v[132:135], v[248:249], off offset:256
	global_load_dwordx4 v[136:139], v[250:251], off
	global_load_dwordx4 v[140:143], v[250:251], off offset:256
	s_waitcnt vmcnt(10)
	s_barrier
	s_add_i32 s9, s3, 5
	s_lshl_b32 s96, s9, 13
	s_add_i32 m0, vcc_lo, 16384
	v_lshl_add_u64 v[160:161], v[188:189], 0, s[96:97]
	global_load_lds_dwordx4 v[160:161], off
	global_load_lds_dwordx4 v[160:161], off offset:1024
	ds_read_b128 v[196:199], v246 offset:0
	ds_read_b128 v[200:203], v162 offset:0
	ds_read_b128 v[204:207], v246 offset:2048
	ds_read_b128 v[242:245], v162 offset:2048
	s_add_i32 s9, s3, 5
	s_lshl_b32 s96, s9, 11
	v_lshl_add_u64 v[248:249], v[184:185], 0, s[96:97]
	v_lshl_add_u64 v[250:251], v[186:187], 0, s[96:97]
	s_waitcnt vmcnt(8) lgkmcnt(3)
	v_mfma_f32_16x16x32_bf16 v[112:115], v[196:199], v[144:147], v[112:115]
	v_mfma_f32_16x16x32_bf16 v[120:123], v[196:199], v[148:151], v[120:123]
	v_mfma_f32_16x16x32_bf16 v[48:51], v[196:199], v[152:155], v[48:51]
	v_mfma_f32_16x16x32_bf16 v[56:59], v[196:199], v[156:159], v[56:59]
	ds_read_b128 v[196:199], v246 offset:4096
	s_waitcnt lgkmcnt(3)
	v_mfma_f32_16x16x32_bf16 v[116:119], v[200:203], v[144:147], v[116:119]
	v_mfma_f32_16x16x32_bf16 v[124:127], v[200:203], v[148:151], v[124:127]
	v_mfma_f32_16x16x32_bf16 v[52:55], v[200:203], v[152:155], v[52:55]
	v_mfma_f32_16x16x32_bf16 v[60:63], v[200:203], v[156:159], v[60:63]
	ds_read_b128 v[200:203], v162 offset:4096
	s_waitcnt lgkmcnt(3)
	v_mfma_f32_16x16x32_bf16 v[96:99], v[204:207], v[144:147], v[96:99]
	v_mfma_f32_16x16x32_bf16 v[104:107], v[204:207], v[148:151], v[104:107]
	v_mfma_f32_16x16x32_bf16 v[32:35], v[204:207], v[152:155], v[32:35]
	v_mfma_f32_16x16x32_bf16 v[40:43], v[204:207], v[156:159], v[40:43]
	ds_read_b128 v[204:207], v246 offset:6144
	s_waitcnt lgkmcnt(3)
	v_mfma_f32_16x16x32_bf16 v[100:103], v[242:245], v[144:147], v[100:103]
	v_mfma_f32_16x16x32_bf16 v[108:111], v[242:245], v[148:151], v[108:111]
	v_mfma_f32_16x16x32_bf16 v[36:39], v[242:245], v[152:155], v[36:39]
	v_mfma_f32_16x16x32_bf16 v[44:47], v[242:245], v[156:159], v[44:47]
	ds_read_b128 v[242:245], v162 offset:6144
	s_waitcnt lgkmcnt(3)
	v_mfma_f32_16x16x32_bf16 v[80:83], v[196:199], v[144:147], v[80:83]
	v_mfma_f32_16x16x32_bf16 v[88:91], v[196:199], v[148:151], v[88:91]
	v_mfma_f32_16x16x32_bf16 v[16:19], v[196:199], v[152:155], v[16:19]
	v_mfma_f32_16x16x32_bf16 v[24:27], v[196:199], v[156:159], v[24:27]
	s_waitcnt lgkmcnt(2)
	v_mfma_f32_16x16x32_bf16 v[84:87], v[200:203], v[144:147], v[84:87]
	v_mfma_f32_16x16x32_bf16 v[92:95], v[200:203], v[148:151], v[92:95]
	v_mfma_f32_16x16x32_bf16 v[20:23], v[200:203], v[152:155], v[20:23]
	v_mfma_f32_16x16x32_bf16 v[28:31], v[200:203], v[156:159], v[28:31]
	s_waitcnt lgkmcnt(1)
	v_mfma_f32_16x16x32_bf16 v[64:67], v[204:207], v[144:147], v[64:67]
	v_mfma_f32_16x16x32_bf16 v[72:75], v[204:207], v[148:151], v[72:75]
	v_mfma_f32_16x16x32_bf16 v[0:3], v[204:207], v[152:155], v[0:3]
	v_mfma_f32_16x16x32_bf16 v[8:11], v[204:207], v[156:159], v[8:11]
	s_waitcnt lgkmcnt(0)
	v_mfma_f32_16x16x32_bf16 v[68:71], v[242:245], v[144:147], v[68:71]
	v_mfma_f32_16x16x32_bf16 v[76:79], v[242:245], v[148:151], v[76:79]
	v_mfma_f32_16x16x32_bf16 v[4:7], v[242:245], v[152:155], v[4:7]
	v_mfma_f32_16x16x32_bf16 v[12:15], v[242:245], v[156:159], v[12:15]
	global_load_dwordx4 v[144:147], v[248:249], off
	global_load_dwordx4 v[148:151], v[248:249], off offset:256
	global_load_dwordx4 v[152:155], v[250:251], off
	global_load_dwordx4 v[156:159], v[250:251], off offset:256
	s_waitcnt vmcnt(10)
	s_barrier
	s_add_i32 s9, s3, 6
	s_lshl_b32 s96, s9, 13
	s_mov_b32 m0, vcc_lo
	v_lshl_add_u64 v[160:161], v[188:189], 0, s[96:97]
	global_load_lds_dwordx4 v[160:161], off
	global_load_lds_dwordx4 v[160:161], off offset:1024
	ds_read_b128 v[196:199], v246 offset:8192
	ds_read_b128 v[200:203], v162 offset:8192
	ds_read_b128 v[204:207], v246 offset:10240
	ds_read_b128 v[242:245], v162 offset:10240
	s_add_i32 s9, s3, 6
	s_lshl_b32 s96, s9, 11
	v_lshl_add_u64 v[248:249], v[184:185], 0, s[96:97]
	v_lshl_add_u64 v[250:251], v[186:187], 0, s[96:97]
	s_waitcnt vmcnt(8) lgkmcnt(3)
	v_mfma_f32_16x16x32_bf16 v[112:115], v[196:199], v[128:131], v[112:115]
	v_mfma_f32_16x16x32_bf16 v[120:123], v[196:199], v[132:135], v[120:123]
	v_mfma_f32_16x16x32_bf16 v[48:51], v[196:199], v[136:139], v[48:51]
	v_mfma_f32_16x16x32_bf16 v[56:59], v[196:199], v[140:143], v[56:59]
	ds_read_b128 v[196:199], v246 offset:12288
	s_waitcnt lgkmcnt(3)
	v_mfma_f32_16x16x32_bf16 v[116:119], v[200:203], v[128:131], v[116:119]
	v_mfma_f32_16x16x32_bf16 v[124:127], v[200:203], v[132:135], v[124:127]
	v_mfma_f32_16x16x32_bf16 v[52:55], v[200:203], v[136:139], v[52:55]
	v_mfma_f32_16x16x32_bf16 v[60:63], v[200:203], v[140:143], v[60:63]
	ds_read_b128 v[200:203], v162 offset:12288
	s_waitcnt lgkmcnt(3)
	v_mfma_f32_16x16x32_bf16 v[96:99], v[204:207], v[128:131], v[96:99]
	v_mfma_f32_16x16x32_bf16 v[104:107], v[204:207], v[132:135], v[104:107]
	v_mfma_f32_16x16x32_bf16 v[32:35], v[204:207], v[136:139], v[32:35]
	v_mfma_f32_16x16x32_bf16 v[40:43], v[204:207], v[140:143], v[40:43]
	ds_read_b128 v[204:207], v246 offset:14336
	s_waitcnt lgkmcnt(3)
	v_mfma_f32_16x16x32_bf16 v[100:103], v[242:245], v[128:131], v[100:103]
	v_mfma_f32_16x16x32_bf16 v[108:111], v[242:245], v[132:135], v[108:111]
	v_mfma_f32_16x16x32_bf16 v[36:39], v[242:245], v[136:139], v[36:39]
	v_mfma_f32_16x16x32_bf16 v[44:47], v[242:245], v[140:143], v[44:47]
	ds_read_b128 v[242:245], v162 offset:14336
	s_waitcnt lgkmcnt(3)
	v_mfma_f32_16x16x32_bf16 v[80:83], v[196:199], v[128:131], v[80:83]
	v_mfma_f32_16x16x32_bf16 v[88:91], v[196:199], v[132:135], v[88:91]
	v_mfma_f32_16x16x32_bf16 v[16:19], v[196:199], v[136:139], v[16:19]
	v_mfma_f32_16x16x32_bf16 v[24:27], v[196:199], v[140:143], v[24:27]
	s_waitcnt lgkmcnt(2)
	v_mfma_f32_16x16x32_bf16 v[84:87], v[200:203], v[128:131], v[84:87]
	v_mfma_f32_16x16x32_bf16 v[92:95], v[200:203], v[132:135], v[92:95]
	v_mfma_f32_16x16x32_bf16 v[20:23], v[200:203], v[136:139], v[20:23]
	v_mfma_f32_16x16x32_bf16 v[28:31], v[200:203], v[140:143], v[28:31]
	s_waitcnt lgkmcnt(1)
	v_mfma_f32_16x16x32_bf16 v[64:67], v[204:207], v[128:131], v[64:67]
	v_mfma_f32_16x16x32_bf16 v[72:75], v[204:207], v[132:135], v[72:75]
	v_mfma_f32_16x16x32_bf16 v[0:3], v[204:207], v[136:139], v[0:3]
	v_mfma_f32_16x16x32_bf16 v[8:11], v[204:207], v[140:143], v[8:11]
	s_waitcnt lgkmcnt(0)
	v_mfma_f32_16x16x32_bf16 v[68:71], v[242:245], v[128:131], v[68:71]
	v_mfma_f32_16x16x32_bf16 v[76:79], v[242:245], v[132:135], v[76:79]
	v_mfma_f32_16x16x32_bf16 v[4:7], v[242:245], v[136:139], v[4:7]
	v_mfma_f32_16x16x32_bf16 v[12:15], v[242:245], v[140:143], v[12:15]
	global_load_dwordx4 v[128:131], v[248:249], off
	global_load_dwordx4 v[132:135], v[248:249], off offset:256
	global_load_dwordx4 v[136:139], v[250:251], off
	global_load_dwordx4 v[140:143], v[250:251], off offset:256
	s_waitcnt vmcnt(10)
	s_barrier
	s_add_i32 s9, s3, 7
	s_lshl_b32 s96, s9, 13
	s_add_i32 m0, vcc_lo, 8192
	v_lshl_add_u64 v[160:161], v[188:189], 0, s[96:97]
	global_load_lds_dwordx4 v[160:161], off
	global_load_lds_dwordx4 v[160:161], off offset:1024
	ds_read_b128 v[196:199], v246 offset:16384
	ds_read_b128 v[200:203], v162 offset:16384
	ds_read_b128 v[204:207], v246 offset:18432
	ds_read_b128 v[242:245], v162 offset:18432
	s_add_i32 s9, s3, 7
	s_lshl_b32 s96, s9, 11
	v_lshl_add_u64 v[248:249], v[184:185], 0, s[96:97]
	v_lshl_add_u64 v[250:251], v[186:187], 0, s[96:97]
	s_waitcnt vmcnt(8) lgkmcnt(3)
	v_mfma_f32_16x16x32_bf16 v[112:115], v[196:199], v[144:147], v[112:115]
	v_mfma_f32_16x16x32_bf16 v[120:123], v[196:199], v[148:151], v[120:123]
	v_mfma_f32_16x16x32_bf16 v[48:51], v[196:199], v[152:155], v[48:51]
	v_mfma_f32_16x16x32_bf16 v[56:59], v[196:199], v[156:159], v[56:59]
	ds_read_b128 v[196:199], v246 offset:20480
	s_waitcnt lgkmcnt(3)
	v_mfma_f32_16x16x32_bf16 v[116:119], v[200:203], v[144:147], v[116:119]
	v_mfma_f32_16x16x32_bf16 v[124:127], v[200:203], v[148:151], v[124:127]
	v_mfma_f32_16x16x32_bf16 v[52:55], v[200:203], v[152:155], v[52:55]
	v_mfma_f32_16x16x32_bf16 v[60:63], v[200:203], v[156:159], v[60:63]
	ds_read_b128 v[200:203], v162 offset:20480
	s_waitcnt lgkmcnt(3)
	v_mfma_f32_16x16x32_bf16 v[96:99], v[204:207], v[144:147], v[96:99]
	v_mfma_f32_16x16x32_bf16 v[104:107], v[204:207], v[148:151], v[104:107]
	v_mfma_f32_16x16x32_bf16 v[32:35], v[204:207], v[152:155], v[32:35]
	v_mfma_f32_16x16x32_bf16 v[40:43], v[204:207], v[156:159], v[40:43]
	ds_read_b128 v[204:207], v246 offset:22528
	s_waitcnt lgkmcnt(3)
	v_mfma_f32_16x16x32_bf16 v[100:103], v[242:245], v[144:147], v[100:103]
	v_mfma_f32_16x16x32_bf16 v[108:111], v[242:245], v[148:151], v[108:111]
	v_mfma_f32_16x16x32_bf16 v[36:39], v[242:245], v[152:155], v[36:39]
	v_mfma_f32_16x16x32_bf16 v[44:47], v[242:245], v[156:159], v[44:47]
	ds_read_b128 v[242:245], v162 offset:22528
	s_waitcnt lgkmcnt(3)
	v_mfma_f32_16x16x32_bf16 v[80:83], v[196:199], v[144:147], v[80:83]
	v_mfma_f32_16x16x32_bf16 v[88:91], v[196:199], v[148:151], v[88:91]
	v_mfma_f32_16x16x32_bf16 v[16:19], v[196:199], v[152:155], v[16:19]
	v_mfma_f32_16x16x32_bf16 v[24:27], v[196:199], v[156:159], v[24:27]
	s_waitcnt lgkmcnt(2)
	v_mfma_f32_16x16x32_bf16 v[84:87], v[200:203], v[144:147], v[84:87]
	v_mfma_f32_16x16x32_bf16 v[92:95], v[200:203], v[148:151], v[92:95]
	v_mfma_f32_16x16x32_bf16 v[20:23], v[200:203], v[152:155], v[20:23]
	v_mfma_f32_16x16x32_bf16 v[28:31], v[200:203], v[156:159], v[28:31]
	s_waitcnt lgkmcnt(1)
	v_mfma_f32_16x16x32_bf16 v[64:67], v[204:207], v[144:147], v[64:67]
	v_mfma_f32_16x16x32_bf16 v[72:75], v[204:207], v[148:151], v[72:75]
	v_mfma_f32_16x16x32_bf16 v[0:3], v[204:207], v[152:155], v[0:3]
	v_mfma_f32_16x16x32_bf16 v[8:11], v[204:207], v[156:159], v[8:11]
	s_waitcnt lgkmcnt(0)
	v_mfma_f32_16x16x32_bf16 v[68:71], v[242:245], v[144:147], v[68:71]
	v_mfma_f32_16x16x32_bf16 v[76:79], v[242:245], v[148:151], v[76:79]
	v_mfma_f32_16x16x32_bf16 v[4:7], v[242:245], v[152:155], v[4:7]
	v_mfma_f32_16x16x32_bf16 v[12:15], v[242:245], v[156:159], v[12:15]
	global_load_dwordx4 v[144:147], v[248:249], off
	global_load_dwordx4 v[148:151], v[248:249], off offset:256
	global_load_dwordx4 v[152:155], v[250:251], off
	global_load_dwordx4 v[156:159], v[250:251], off offset:256
	s_waitcnt vmcnt(10)
	s_barrier
	s_add_i32 s3, s3, 6
	s_cmp_lt_u32 s3, 30
	s_cbranch_scc1 .Lg16_out_k
	ds_read_b128 v[196:199], v246 offset:0
	ds_read_b128 v[200:203], v162 offset:0
	ds_read_b128 v[204:207], v246 offset:2048
	ds_read_b128 v[242:245], v162 offset:2048
	s_waitcnt vmcnt(6) lgkmcnt(3)
	v_mfma_f32_16x16x32_bf16 v[112:115], v[196:199], v[128:131], v[112:115]
	v_mfma_f32_16x16x32_bf16 v[120:123], v[196:199], v[132:135], v[120:123]
	v_mfma_f32_16x16x32_bf16 v[48:51], v[196:199], v[136:139], v[48:51]
	v_mfma_f32_16x16x32_bf16 v[56:59], v[196:199], v[140:143], v[56:59]
	ds_read_b128 v[196:199], v246 offset:4096
	s_waitcnt lgkmcnt(3)
	v_mfma_f32_16x16x32_bf16 v[116:119], v[200:203], v[128:131], v[116:119]
	v_mfma_f32_16x16x32_bf16 v[124:127], v[200:203], v[132:135], v[124:127]
	v_mfma_f32_16x16x32_bf16 v[52:55], v[200:203], v[136:139], v[52:55]
	v_mfma_f32_16x16x32_bf16 v[60:63], v[200:203], v[140:143], v[60:63]
	ds_read_b128 v[200:203], v162 offset:4096
	s_waitcnt lgkmcnt(3)
	v_mfma_f32_16x16x32_bf16 v[96:99], v[204:207], v[128:131], v[96:99]
	v_mfma_f32_16x16x32_bf16 v[104:107], v[204:207], v[132:135], v[104:107]
	v_mfma_f32_16x16x32_bf16 v[32:35], v[204:207], v[136:139], v[32:35]
	v_mfma_f32_16x16x32_bf16 v[40:43], v[204:207], v[140:143], v[40:43]
	ds_read_b128 v[204:207], v246 offset:6144
	s_waitcnt lgkmcnt(3)
	v_mfma_f32_16x16x32_bf16 v[100:103], v[242:245], v[128:131], v[100:103]
	v_mfma_f32_16x16x32_bf16 v[108:111], v[242:245], v[132:135], v[108:111]
	v_mfma_f32_16x16x32_bf16 v[36:39], v[242:245], v[136:139], v[36:39]
	v_mfma_f32_16x16x32_bf16 v[44:47], v[242:245], v[140:143], v[44:47]
	ds_read_b128 v[242:245], v162 offset:6144
	s_waitcnt lgkmcnt(3)
	v_mfma_f32_16x16x32_bf16 v[80:83], v[196:199], v[128:131], v[80:83]
	v_mfma_f32_16x16x32_bf16 v[88:91], v[196:199], v[132:135], v[88:91]
	v_mfma_f32_16x16x32_bf16 v[16:19], v[196:199], v[136:139], v[16:19]
	v_mfma_f32_16x16x32_bf16 v[24:27], v[196:199], v[140:143], v[24:27]
	s_waitcnt lgkmcnt(2)
	v_mfma_f32_16x16x32_bf16 v[84:87], v[200:203], v[128:131], v[84:87]
	v_mfma_f32_16x16x32_bf16 v[92:95], v[200:203], v[132:135], v[92:95]
	v_mfma_f32_16x16x32_bf16 v[20:23], v[200:203], v[136:139], v[20:23]
	v_mfma_f32_16x16x32_bf16 v[28:31], v[200:203], v[140:143], v[28:31]
	s_waitcnt lgkmcnt(1)
	v_mfma_f32_16x16x32_bf16 v[64:67], v[204:207], v[128:131], v[64:67]
	v_mfma_f32_16x16x32_bf16 v[72:75], v[204:207], v[132:135], v[72:75]
	v_mfma_f32_16x16x32_bf16 v[0:3], v[204:207], v[136:139], v[0:3]
	v_mfma_f32_16x16x32_bf16 v[8:11], v[204:207], v[140:143], v[8:11]
	s_waitcnt lgkmcnt(0)
	v_mfma_f32_16x16x32_bf16 v[68:71], v[242:245], v[128:131], v[68:71]
	v_mfma_f32_16x16x32_bf16 v[76:79], v[242:245], v[132:135], v[76:79]
	v_mfma_f32_16x16x32_bf16 v[4:7], v[242:245], v[136:139], v[4:7]
	v_mfma_f32_16x16x32_bf16 v[12:15], v[242:245], v[140:143], v[12:15]
	s_waitcnt vmcnt(4)
	s_barrier
	ds_read_b128 v[196:199], v246 offset:8192
	ds_read_b128 v[200:203], v162 offset:8192
	ds_read_b128 v[204:207], v246 offset:10240
	ds_read_b128 v[242:245], v162 offset:10240
	s_waitcnt vmcnt(0) lgkmcnt(3)
	v_mfma_f32_16x16x32_bf16 v[112:115], v[196:199], v[144:147], v[112:115]
	v_mfma_f32_16x16x32_bf16 v[120:123], v[196:199], v[148:151], v[120:123]
	v_mfma_f32_16x16x32_bf16 v[48:51], v[196:199], v[152:155], v[48:51]
	v_mfma_f32_16x16x32_bf16 v[56:59], v[196:199], v[156:159], v[56:59]
	ds_read_b128 v[196:199], v246 offset:12288
	s_waitcnt lgkmcnt(3)
	v_mfma_f32_16x16x32_bf16 v[116:119], v[200:203], v[144:147], v[116:119]
	v_mfma_f32_16x16x32_bf16 v[124:127], v[200:203], v[148:151], v[124:127]
	v_mfma_f32_16x16x32_bf16 v[52:55], v[200:203], v[152:155], v[52:55]
	v_mfma_f32_16x16x32_bf16 v[60:63], v[200:203], v[156:159], v[60:63]
	ds_read_b128 v[200:203], v162 offset:12288
	s_waitcnt lgkmcnt(3)
	v_mfma_f32_16x16x32_bf16 v[96:99], v[204:207], v[144:147], v[96:99]
	v_mfma_f32_16x16x32_bf16 v[104:107], v[204:207], v[148:151], v[104:107]
	v_mfma_f32_16x16x32_bf16 v[32:35], v[204:207], v[152:155], v[32:35]
	v_mfma_f32_16x16x32_bf16 v[40:43], v[204:207], v[156:159], v[40:43]
	ds_read_b128 v[204:207], v246 offset:14336
	s_waitcnt lgkmcnt(3)
	v_mfma_f32_16x16x32_bf16 v[100:103], v[242:245], v[144:147], v[100:103]
	v_mfma_f32_16x16x32_bf16 v[108:111], v[242:245], v[148:151], v[108:111]
	v_mfma_f32_16x16x32_bf16 v[36:39], v[242:245], v[152:155], v[36:39]
	v_mfma_f32_16x16x32_bf16 v[44:47], v[242:245], v[156:159], v[44:47]
	ds_read_b128 v[242:245], v162 offset:14336
	s_waitcnt lgkmcnt(3)
	v_mfma_f32_16x16x32_bf16 v[80:83], v[196:199], v[144:147], v[80:83]
	v_mfma_f32_16x16x32_bf16 v[88:91], v[196:199], v[148:151], v[88:91]
	v_mfma_f32_16x16x32_bf16 v[16:19], v[196:199], v[152:155], v[16:19]
	v_mfma_f32_16x16x32_bf16 v[24:27], v[196:199], v[156:159], v[24:27]
	s_waitcnt lgkmcnt(2)
	v_mfma_f32_16x16x32_bf16 v[84:87], v[200:203], v[144:147], v[84:87]
	v_mfma_f32_16x16x32_bf16 v[92:95], v[200:203], v[148:151], v[92:95]
	v_mfma_f32_16x16x32_bf16 v[20:23], v[200:203], v[152:155], v[20:23]
	v_mfma_f32_16x16x32_bf16 v[28:31], v[200:203], v[156:159], v[28:31]
	s_waitcnt lgkmcnt(1)
	v_mfma_f32_16x16x32_bf16 v[64:67], v[204:207], v[144:147], v[64:67]
	v_mfma_f32_16x16x32_bf16 v[72:75], v[204:207], v[148:151], v[72:75]
	v_mfma_f32_16x16x32_bf16 v[0:3], v[204:207], v[152:155], v[0:3]
	v_mfma_f32_16x16x32_bf16 v[8:11], v[204:207], v[156:159], v[8:11]
	s_waitcnt lgkmcnt(0)
	v_mfma_f32_16x16x32_bf16 v[68:71], v[242:245], v[144:147], v[68:71]
	v_mfma_f32_16x16x32_bf16 v[76:79], v[242:245], v[148:151], v[76:79]
	v_mfma_f32_16x16x32_bf16 v[4:7], v[242:245], v[152:155], v[4:7]
	v_mfma_f32_16x16x32_bf16 v[12:15], v[242:245], v[156:159], v[12:15]
	s_barrier
	s_nop 7
	s_nop 1
	s_waitcnt vmcnt(0)
	s_waitcnt vmcnt(0)
	v_and_b32_e32 v188, 63, v179
	v_lshrrev_b32_e32 v189, 6, v179
	v_mul_u32_u24_e32 v249, 0x2400, v189
	v_mov_b32_e32 v250, v249
	v_and_b32_e32 v251, 15, v188
	v_mul_u32_u24_e32 v251, 0x110, v251
	v_add_u32_e32 v249, v249, v251
	v_lshrrev_b32_e32 v251, 4, v188
	v_lshl_add_u32 v249, v251, 5, v249
	v_lshrrev_b32_e32 v237, 4, v188
	v_mul_u32_u24_e32 v251, 0x110, v237
	v_add_u32_e32 v250, v250, v251
	v_and_b32_e32 v251, 15, v188
	v_lshlrev_b32_e32 v251, 4, v251
	v_add_u32_e32 v250, v250, v251
	v_lshl_add_u32 v237, v189, 6, v237
	v_lshl_add_u32 v237, v237, 12, v251
	v_add_u32_e32 v238, 16384, v237
	v_add_u32_e32 v239, 32768, v237
	v_add_u32_e32 v240, 49152, v237
	v_add_u32_e32 v241, 65536, v237
	v_add_u32_e32 v242, 81920, v237
	v_add_u32_e32 v243, 98304, v237
	v_add_u32_e32 v248, 114688, v237
	s_lshl_b32 s16, s8, 8
	s_lshl_b32 s18, s2, 9
	s_lshr_b32 s19, s8, 4
	v_readlane_b32 s12, v254, 38
	v_readlane_b32 s13, v254, 37
	v_readlane_b32 s14, v253, 46
	v_readlane_b32 s15, v253, 47
	v_readlane_b32 s22, v254, 40
	v_readlane_b32 s23, v254, 39
	s_add_i32 s17, s16, 0xffff8000
	s_cmpk_lt_u32 s8, 0x80
	s_cselect_b32 s12, s12, s22
	s_cselect_b32 s13, s13, s23
	s_cselect_b32 s14, s14, s62
	s_cselect_b32 s15, s15, s63
	s_cselect_b32 s19, s19, 8
	s_cselect_b32 s16, s16, s17
	s_mov_b32 s17, 0
	s_lshl_b64 s[16:17], s[16:17], 12
	s_add_u32 s16, s16, s18
	s_addc_u32 s17, s17, 0
	s_add_u32 s12, s12, s16
	s_addc_u32 s13, s13, s17
	s_add_u32 s14, s14, s16
	s_addc_u32 s15, s15, s17
	s_mul_i32 s19, s19, 0x6000
	s_add_u32 s20, s0, s19
	s_addc_u32 s21, s1, 0
	s_add_u32 s20, s20, s18
	s_addc_u32 s21, s21, 0
	global_load_dwordx4 v[244:247], v251, s[20:21]
	global_load_dwordx4 v[160:163], v237, s[12:13]
	global_load_dwordx4 v[164:167], v238, s[12:13]
	global_load_dwordx4 v[168:171], v239, s[12:13]
	global_load_dwordx4 v[172:175], v240, s[12:13]
	global_load_dwordx4 v[196:199], v241, s[12:13]
	global_load_dwordx4 v[200:203], v242, s[12:13]
	global_load_dwordx4 v[204:207], v243, s[12:13]
	global_load_dwordx4 v[184:187], v248, s[12:13]
	ds_write_b128 v249, v[112:115]
	ds_write_b128 v249, v[116:119] offset:16
	ds_write_b128 v249, v[96:99] offset:128
	ds_write_b128 v249, v[100:103] offset:144
	ds_write_b128 v249, v[120:123] offset:4352
	ds_write_b128 v249, v[124:127] offset:4368
	ds_write_b128 v249, v[104:107] offset:4480
	ds_write_b128 v249, v[108:111] offset:4496
	s_waitcnt lgkmcnt(0)
	ds_read_b128 v[128:131], v250
	ds_read_b128 v[132:135], v250 offset:1088
	ds_read_b128 v[136:139], v250 offset:2176
	ds_read_b128 v[140:143], v250 offset:3264
	ds_read_b128 v[144:147], v250 offset:4352
	ds_read_b128 v[148:151], v250 offset:5440
	ds_read_b128 v[152:155], v250 offset:6528
	ds_read_b128 v[156:159], v250 offset:7616
	s_waitcnt vmcnt(7) lgkmcnt(7)
	v_fma_f32 v128, v244, v128, v160
	v_fma_f32 v129, v245, v129, v161
	v_fma_f32 v130, v246, v130, v162
	v_fma_f32 v131, v247, v131, v163
	global_store_dwordx4 v237, v[128:131], s[14:15] sc1
	s_waitcnt vmcnt(7) lgkmcnt(6)
	v_fma_f32 v132, v244, v132, v164
	v_fma_f32 v133, v245, v133, v165
	v_fma_f32 v134, v246, v134, v166
	v_fma_f32 v135, v247, v135, v167
	global_store_dwordx4 v238, v[132:135], s[14:15] sc1
	s_waitcnt vmcnt(7) lgkmcnt(5)
	v_fma_f32 v136, v244, v136, v168
	v_fma_f32 v137, v245, v137, v169
	v_fma_f32 v138, v246, v138, v170
	v_fma_f32 v139, v247, v139, v171
	global_store_dwordx4 v239, v[136:139], s[14:15] sc1
	s_waitcnt vmcnt(7) lgkmcnt(4)
	v_fma_f32 v140, v244, v140, v172
	v_fma_f32 v141, v245, v141, v173
	v_fma_f32 v142, v246, v142, v174
	v_fma_f32 v143, v247, v143, v175
	global_store_dwordx4 v240, v[140:143], s[14:15] sc1
	s_waitcnt vmcnt(7) lgkmcnt(3)
	v_fma_f32 v144, v244, v144, v196
	v_fma_f32 v145, v245, v145, v197
	v_fma_f32 v146, v246, v146, v198
	v_fma_f32 v147, v247, v147, v199
	global_store_dwordx4 v241, v[144:147], s[14:15] sc1
	s_waitcnt vmcnt(7) lgkmcnt(2)
	v_fma_f32 v148, v244, v148, v200
	v_fma_f32 v149, v245, v149, v201
	v_fma_f32 v150, v246, v150, v202
	v_fma_f32 v151, v247, v151, v203
	global_store_dwordx4 v242, v[148:151], s[14:15] sc1
	s_waitcnt vmcnt(7) lgkmcnt(1)
	v_fma_f32 v152, v244, v152, v204
	v_fma_f32 v153, v245, v153, v205
	v_fma_f32 v154, v246, v154, v206
	v_fma_f32 v155, v247, v155, v207
	global_store_dwordx4 v243, v[152:155], s[14:15] sc1
	s_waitcnt vmcnt(7) lgkmcnt(0)
	v_fma_f32 v156, v244, v156, v184
	v_fma_f32 v157, v245, v157, v185
	v_fma_f32 v158, v246, v158, v186
	v_fma_f32 v159, v247, v159, v187
	global_store_dwordx4 v248, v[156:159], s[14:15] sc1
	global_load_dwordx4 v[244:247], v251, s[20:21] offset:256
	global_load_dwordx4 v[160:163], v237, s[12:13] offset:256
	global_load_dwordx4 v[164:167], v238, s[12:13] offset:256
	global_load_dwordx4 v[168:171], v239, s[12:13] offset:256
	global_load_dwordx4 v[172:175], v240, s[12:13] offset:256
	global_load_dwordx4 v[196:199], v241, s[12:13] offset:256
	global_load_dwordx4 v[200:203], v242, s[12:13] offset:256
	global_load_dwordx4 v[204:207], v243, s[12:13] offset:256
	global_load_dwordx4 v[184:187], v248, s[12:13] offset:256
	ds_write_b128 v249, v[80:83]
	ds_write_b128 v249, v[84:87] offset:16
	ds_write_b128 v249, v[64:67] offset:128
	ds_write_b128 v249, v[68:71] offset:144
	ds_write_b128 v249, v[88:91] offset:4352
	ds_write_b128 v249, v[92:95] offset:4368
	ds_write_b128 v249, v[72:75] offset:4480
	ds_write_b128 v249, v[76:79] offset:4496
	s_waitcnt lgkmcnt(0)
	ds_read_b128 v[128:131], v250
	ds_read_b128 v[132:135], v250 offset:1088
	ds_read_b128 v[136:139], v250 offset:2176
	ds_read_b128 v[140:143], v250 offset:3264
	ds_read_b128 v[144:147], v250 offset:4352
	ds_read_b128 v[148:151], v250 offset:5440
	ds_read_b128 v[152:155], v250 offset:6528
	ds_read_b128 v[156:159], v250 offset:7616
	s_waitcnt vmcnt(7) lgkmcnt(7)
	v_fma_f32 v128, v244, v128, v160
	v_fma_f32 v129, v245, v129, v161
	v_fma_f32 v130, v246, v130, v162
	v_fma_f32 v131, v247, v131, v163
	global_store_dwordx4 v237, v[128:131], s[14:15] offset:256 sc1
	s_waitcnt vmcnt(7) lgkmcnt(6)
	v_fma_f32 v132, v244, v132, v164
	v_fma_f32 v133, v245, v133, v165
	v_fma_f32 v134, v246, v134, v166
	v_fma_f32 v135, v247, v135, v167
	global_store_dwordx4 v238, v[132:135], s[14:15] offset:256 sc1
	s_waitcnt vmcnt(7) lgkmcnt(5)
	v_fma_f32 v136, v244, v136, v168
	v_fma_f32 v137, v245, v137, v169
	v_fma_f32 v138, v246, v138, v170
	v_fma_f32 v139, v247, v139, v171
	global_store_dwordx4 v239, v[136:139], s[14:15] offset:256 sc1
	s_waitcnt vmcnt(7) lgkmcnt(4)
	v_fma_f32 v140, v244, v140, v172
	v_fma_f32 v141, v245, v141, v173
	v_fma_f32 v142, v246, v142, v174
	v_fma_f32 v143, v247, v143, v175
	global_store_dwordx4 v240, v[140:143], s[14:15] offset:256 sc1
	s_waitcnt vmcnt(7) lgkmcnt(3)
	v_fma_f32 v144, v244, v144, v196
	v_fma_f32 v145, v245, v145, v197
	v_fma_f32 v146, v246, v146, v198
	v_fma_f32 v147, v247, v147, v199
	global_store_dwordx4 v241, v[144:147], s[14:15] offset:256 sc1
	s_waitcnt vmcnt(7) lgkmcnt(2)
	v_fma_f32 v148, v244, v148, v200
	v_fma_f32 v149, v245, v149, v201
	v_fma_f32 v150, v246, v150, v202
	v_fma_f32 v151, v247, v151, v203
	global_store_dwordx4 v242, v[148:151], s[14:15] offset:256 sc1
	s_waitcnt vmcnt(7) lgkmcnt(1)
	v_fma_f32 v152, v244, v152, v204
	v_fma_f32 v153, v245, v153, v205
	v_fma_f32 v154, v246, v154, v206
	v_fma_f32 v155, v247, v155, v207
	global_store_dwordx4 v243, v[152:155], s[14:15] offset:256 sc1
	s_waitcnt vmcnt(7) lgkmcnt(0)
	v_fma_f32 v156, v244, v156, v184
	v_fma_f32 v157, v245, v157, v185
	v_fma_f32 v158, v246, v158, v186
	v_fma_f32 v159, v247, v159, v187
	global_store_dwordx4 v248, v[156:159], s[14:15] offset:256 sc1
	s_add_u32 s12, s12, 0x20000
	s_addc_u32 s13, s13, 0
	s_add_u32 s14, s14, 0x20000
	s_addc_u32 s15, s15, 0
	global_load_dwordx4 v[244:247], v251, s[20:21]
	global_load_dwordx4 v[160:163], v237, s[12:13]
	global_load_dwordx4 v[164:167], v238, s[12:13]
	global_load_dwordx4 v[168:171], v239, s[12:13]
	global_load_dwordx4 v[172:175], v240, s[12:13]
	global_load_dwordx4 v[196:199], v241, s[12:13]
	global_load_dwordx4 v[200:203], v242, s[12:13]
	global_load_dwordx4 v[204:207], v243, s[12:13]
	global_load_dwordx4 v[184:187], v248, s[12:13]
	ds_write_b128 v249, v[48:51]
	ds_write_b128 v249, v[52:55] offset:16
	ds_write_b128 v249, v[32:35] offset:128
	ds_write_b128 v249, v[36:39] offset:144
	ds_write_b128 v249, v[56:59] offset:4352
	ds_write_b128 v249, v[60:63] offset:4368
	ds_write_b128 v249, v[40:43] offset:4480
	ds_write_b128 v249, v[44:47] offset:4496
	s_waitcnt lgkmcnt(0)
	ds_read_b128 v[128:131], v250
	ds_read_b128 v[132:135], v250 offset:1088
	ds_read_b128 v[136:139], v250 offset:2176
	ds_read_b128 v[140:143], v250 offset:3264
	ds_read_b128 v[144:147], v250 offset:4352
	ds_read_b128 v[148:151], v250 offset:5440
	ds_read_b128 v[152:155], v250 offset:6528
	ds_read_b128 v[156:159], v250 offset:7616
	s_waitcnt vmcnt(7) lgkmcnt(7)
	v_fma_f32 v128, v244, v128, v160
	v_fma_f32 v129, v245, v129, v161
	v_fma_f32 v130, v246, v130, v162
	v_fma_f32 v131, v247, v131, v163
	global_store_dwordx4 v237, v[128:131], s[14:15] sc1
	s_waitcnt vmcnt(7) lgkmcnt(6)
	v_fma_f32 v132, v244, v132, v164
	v_fma_f32 v133, v245, v133, v165
	v_fma_f32 v134, v246, v134, v166
	v_fma_f32 v135, v247, v135, v167
	global_store_dwordx4 v238, v[132:135], s[14:15] sc1
	s_waitcnt vmcnt(7) lgkmcnt(5)
	v_fma_f32 v136, v244, v136, v168
	v_fma_f32 v137, v245, v137, v169
	v_fma_f32 v138, v246, v138, v170
	v_fma_f32 v139, v247, v139, v171
	global_store_dwordx4 v239, v[136:139], s[14:15] sc1
	s_waitcnt vmcnt(7) lgkmcnt(4)
	v_fma_f32 v140, v244, v140, v172
	v_fma_f32 v141, v245, v141, v173
	v_fma_f32 v142, v246, v142, v174
	v_fma_f32 v143, v247, v143, v175
	global_store_dwordx4 v240, v[140:143], s[14:15] sc1
	s_waitcnt vmcnt(7) lgkmcnt(3)
	v_fma_f32 v144, v244, v144, v196
	v_fma_f32 v145, v245, v145, v197
	v_fma_f32 v146, v246, v146, v198
	v_fma_f32 v147, v247, v147, v199
	global_store_dwordx4 v241, v[144:147], s[14:15] sc1
	s_waitcnt vmcnt(7) lgkmcnt(2)
	v_fma_f32 v148, v244, v148, v200
	v_fma_f32 v149, v245, v149, v201
	v_fma_f32 v150, v246, v150, v202
	v_fma_f32 v151, v247, v151, v203
	global_store_dwordx4 v242, v[148:151], s[14:15] sc1
	s_waitcnt vmcnt(7) lgkmcnt(1)
	v_fma_f32 v152, v244, v152, v204
	v_fma_f32 v153, v245, v153, v205
	v_fma_f32 v154, v246, v154, v206
	v_fma_f32 v155, v247, v155, v207
	global_store_dwordx4 v243, v[152:155], s[14:15] sc1
	s_waitcnt vmcnt(7) lgkmcnt(0)
	v_fma_f32 v156, v244, v156, v184
	v_fma_f32 v157, v245, v157, v185
	v_fma_f32 v158, v246, v158, v186
	v_fma_f32 v159, v247, v159, v187
	global_store_dwordx4 v248, v[156:159], s[14:15] sc1
	global_load_dwordx4 v[244:247], v251, s[20:21] offset:256
	global_load_dwordx4 v[160:163], v237, s[12:13] offset:256
	global_load_dwordx4 v[164:167], v238, s[12:13] offset:256
	global_load_dwordx4 v[168:171], v239, s[12:13] offset:256
	global_load_dwordx4 v[172:175], v240, s[12:13] offset:256
	global_load_dwordx4 v[196:199], v241, s[12:13] offset:256
	global_load_dwordx4 v[200:203], v242, s[12:13] offset:256
	global_load_dwordx4 v[204:207], v243, s[12:13] offset:256
	global_load_dwordx4 v[184:187], v248, s[12:13] offset:256
	ds_write_b128 v249, v[16:19]
	ds_write_b128 v249, v[20:23] offset:16
	ds_write_b128 v249, v[0:3] offset:128
	ds_write_b128 v249, v[4:7] offset:144
	ds_write_b128 v249, v[24:27] offset:4352
	ds_write_b128 v249, v[28:31] offset:4368
	ds_write_b128 v249, v[8:11] offset:4480
	ds_write_b128 v249, v[12:15] offset:4496
	s_waitcnt lgkmcnt(0)
	ds_read_b128 v[128:131], v250
	ds_read_b128 v[132:135], v250 offset:1088
	ds_read_b128 v[136:139], v250 offset:2176
	ds_read_b128 v[140:143], v250 offset:3264
	ds_read_b128 v[144:147], v250 offset:4352
	ds_read_b128 v[148:151], v250 offset:5440
	ds_read_b128 v[152:155], v250 offset:6528
	ds_read_b128 v[156:159], v250 offset:7616
	s_waitcnt vmcnt(7) lgkmcnt(7)
	v_fma_f32 v128, v244, v128, v160
	v_fma_f32 v129, v245, v129, v161
	v_fma_f32 v130, v246, v130, v162
	v_fma_f32 v131, v247, v131, v163
	global_store_dwordx4 v237, v[128:131], s[14:15] offset:256 sc1
	s_waitcnt vmcnt(7) lgkmcnt(6)
	v_fma_f32 v132, v244, v132, v164
	v_fma_f32 v133, v245, v133, v165
	v_fma_f32 v134, v246, v134, v166
	v_fma_f32 v135, v247, v135, v167
	global_store_dwordx4 v238, v[132:135], s[14:15] offset:256 sc1
	s_waitcnt vmcnt(7) lgkmcnt(5)
	v_fma_f32 v136, v244, v136, v168
	v_fma_f32 v137, v245, v137, v169
	v_fma_f32 v138, v246, v138, v170
	v_fma_f32 v139, v247, v139, v171
	global_store_dwordx4 v239, v[136:139], s[14:15] offset:256 sc1
	s_waitcnt vmcnt(7) lgkmcnt(4)
	v_fma_f32 v140, v244, v140, v172
	v_fma_f32 v141, v245, v141, v173
	v_fma_f32 v142, v246, v142, v174
	v_fma_f32 v143, v247, v143, v175
	global_store_dwordx4 v240, v[140:143], s[14:15] offset:256 sc1
	s_waitcnt vmcnt(7) lgkmcnt(3)
	v_fma_f32 v144, v244, v144, v196
	v_fma_f32 v145, v245, v145, v197
	v_fma_f32 v146, v246, v146, v198
	v_fma_f32 v147, v247, v147, v199
	global_store_dwordx4 v241, v[144:147], s[14:15] offset:256 sc1
	s_waitcnt vmcnt(7) lgkmcnt(2)
	v_fma_f32 v148, v244, v148, v200
	v_fma_f32 v149, v245, v149, v201
	v_fma_f32 v150, v246, v150, v202
	v_fma_f32 v151, v247, v151, v203
	global_store_dwordx4 v242, v[148:151], s[14:15] offset:256 sc1
	s_waitcnt vmcnt(7) lgkmcnt(1)
	v_fma_f32 v152, v244, v152, v204
	v_fma_f32 v153, v245, v153, v205
	v_fma_f32 v154, v246, v154, v206
	v_fma_f32 v155, v247, v155, v207
	global_store_dwordx4 v243, v[152:155], s[14:15] offset:256 sc1
	s_waitcnt vmcnt(7) lgkmcnt(0)
	v_fma_f32 v156, v244, v156, v184
	v_fma_f32 v157, v245, v157, v185
	v_fma_f32 v158, v246, v158, v186
	v_fma_f32 v159, v247, v159, v187
	global_store_dwordx4 v248, v[156:159], s[14:15] offset:256 sc1
	s_waitcnt lgkmcnt(0)
	v_readlane_b32 s16, v254, 11
	s_andn2_b32 s17, s26, 63
	s_add_i32 s4, s4, s16
	s_cmp_lt_i32 s4, s17
	s_cbranch_scc0 .Lhx_out_left
	s_barrier
	s_branch .LBB0_923

.Lre_outh_h0:
	global_load_dwordx4 v[244:247], v251, s[20:21]
	global_load_dwordx4 v[160:163], v237, s[12:13]
	global_load_dwordx4 v[164:167], v238, s[12:13]
	global_load_dwordx4 v[168:171], v239, s[12:13]
	global_load_dwordx4 v[172:175], v240, s[12:13]
	global_load_dwordx4 v[196:199], v241, s[12:13]
	global_load_dwordx4 v[200:203], v242, s[12:13]
	global_load_dwordx4 v[204:207], v243, s[12:13]
	global_load_dwordx4 v[184:187], v248, s[12:13]
	ds_write_b128 v249, v[112:115]
	ds_write_b128 v249, v[116:119] offset:16
	ds_write_b128 v249, v[96:99] offset:128
	ds_write_b128 v249, v[100:103] offset:144
	ds_write_b128 v249, v[120:123] offset:4352
	ds_write_b128 v249, v[124:127] offset:4368
	ds_write_b128 v249, v[104:107] offset:4480
	ds_write_b128 v249, v[108:111] offset:4496
	s_waitcnt lgkmcnt(0)
	ds_read_b128 v[128:131], v250
	ds_read_b128 v[132:135], v250 offset:1088
	ds_read_b128 v[136:139], v250 offset:2176
	ds_read_b128 v[140:143], v250 offset:3264
	ds_read_b128 v[144:147], v250 offset:4352
	ds_read_b128 v[148:151], v250 offset:5440
	ds_read_b128 v[152:155], v250 offset:6528
	ds_read_b128 v[156:159], v250 offset:7616
	s_waitcnt vmcnt(7) lgkmcnt(7)
	v_fma_f32 v128, v244, v128, v160
	v_fma_f32 v129, v245, v129, v161
	v_fma_f32 v130, v246, v130, v162
	v_fma_f32 v131, v247, v131, v163
	global_store_dwordx4 v237, v[128:131], s[14:15] sc1
	s_waitcnt vmcnt(7) lgkmcnt(6)
	v_fma_f32 v132, v244, v132, v164
	v_fma_f32 v133, v245, v133, v165
	v_fma_f32 v134, v246, v134, v166
	v_fma_f32 v135, v247, v135, v167
	global_store_dwordx4 v238, v[132:135], s[14:15] sc1
	s_waitcnt vmcnt(7) lgkmcnt(5)
	v_fma_f32 v136, v244, v136, v168
	v_fma_f32 v137, v245, v137, v169
	v_fma_f32 v138, v246, v138, v170
	v_fma_f32 v139, v247, v139, v171
	global_store_dwordx4 v239, v[136:139], s[14:15] sc1
	s_waitcnt vmcnt(7) lgkmcnt(4)
	v_fma_f32 v140, v244, v140, v172
	v_fma_f32 v141, v245, v141, v173
	v_fma_f32 v142, v246, v142, v174
	v_fma_f32 v143, v247, v143, v175
	global_store_dwordx4 v240, v[140:143], s[14:15] sc1
	s_waitcnt vmcnt(7) lgkmcnt(3)
	v_fma_f32 v144, v244, v144, v196
	v_fma_f32 v145, v245, v145, v197
	v_fma_f32 v146, v246, v146, v198
	v_fma_f32 v147, v247, v147, v199
	global_store_dwordx4 v241, v[144:147], s[14:15] sc1
	s_waitcnt vmcnt(7) lgkmcnt(2)
	v_fma_f32 v148, v244, v148, v200
	v_fma_f32 v149, v245, v149, v201
	v_fma_f32 v150, v246, v150, v202
	v_fma_f32 v151, v247, v151, v203
	global_store_dwordx4 v242, v[148:151], s[14:15] sc1
	s_waitcnt vmcnt(7) lgkmcnt(1)
	v_fma_f32 v152, v244, v152, v204
	v_fma_f32 v153, v245, v153, v205
	v_fma_f32 v154, v246, v154, v206
	v_fma_f32 v155, v247, v155, v207
	global_store_dwordx4 v243, v[152:155], s[14:15] sc1
	s_waitcnt vmcnt(7) lgkmcnt(0)
	v_fma_f32 v156, v244, v156, v184
	v_fma_f32 v157, v245, v157, v185
	v_fma_f32 v158, v246, v158, v186
	v_fma_f32 v159, v247, v159, v187
	global_store_dwordx4 v248, v[156:159], s[14:15] sc1
	global_load_dwordx4 v[244:247], v251, s[20:21] offset:256
	global_load_dwordx4 v[160:163], v237, s[12:13] offset:256
	global_load_dwordx4 v[164:167], v238, s[12:13] offset:256
	global_load_dwordx4 v[168:171], v239, s[12:13] offset:256
	global_load_dwordx4 v[172:175], v240, s[12:13] offset:256
	global_load_dwordx4 v[196:199], v241, s[12:13] offset:256
	global_load_dwordx4 v[200:203], v242, s[12:13] offset:256
	global_load_dwordx4 v[204:207], v243, s[12:13] offset:256
	global_load_dwordx4 v[184:187], v248, s[12:13] offset:256
	ds_write_b128 v249, v[80:83]
	ds_write_b128 v249, v[84:87] offset:16
	ds_write_b128 v249, v[64:67] offset:128
	ds_write_b128 v249, v[68:71] offset:144
	ds_write_b128 v249, v[88:91] offset:4352
	ds_write_b128 v249, v[92:95] offset:4368
	ds_write_b128 v249, v[72:75] offset:4480
	ds_write_b128 v249, v[76:79] offset:4496
	s_waitcnt lgkmcnt(0)
	ds_read_b128 v[128:131], v250
	ds_read_b128 v[132:135], v250 offset:1088
	ds_read_b128 v[136:139], v250 offset:2176
	ds_read_b128 v[140:143], v250 offset:3264
	ds_read_b128 v[144:147], v250 offset:4352
	ds_read_b128 v[148:151], v250 offset:5440
	ds_read_b128 v[152:155], v250 offset:6528
	ds_read_b128 v[156:159], v250 offset:7616
	s_waitcnt vmcnt(7) lgkmcnt(7)
	v_fma_f32 v128, v244, v128, v160
	v_fma_f32 v129, v245, v129, v161
	v_fma_f32 v130, v246, v130, v162
	v_fma_f32 v131, v247, v131, v163
	global_store_dwordx4 v237, v[128:131], s[14:15] offset:256 sc1
	s_waitcnt vmcnt(7) lgkmcnt(6)
	v_fma_f32 v132, v244, v132, v164
	v_fma_f32 v133, v245, v133, v165
	v_fma_f32 v134, v246, v134, v166
	v_fma_f32 v135, v247, v135, v167
	global_store_dwordx4 v238, v[132:135], s[14:15] offset:256 sc1
	s_waitcnt vmcnt(7) lgkmcnt(5)
	v_fma_f32 v136, v244, v136, v168
	v_fma_f32 v137, v245, v137, v169
	v_fma_f32 v138, v246, v138, v170
	v_fma_f32 v139, v247, v139, v171
	global_store_dwordx4 v239, v[136:139], s[14:15] offset:256 sc1
	s_waitcnt vmcnt(7) lgkmcnt(4)
	v_fma_f32 v140, v244, v140, v172
	v_fma_f32 v141, v245, v141, v173
	v_fma_f32 v142, v246, v142, v174
	v_fma_f32 v143, v247, v143, v175
	global_store_dwordx4 v240, v[140:143], s[14:15] offset:256 sc1
	s_waitcnt vmcnt(7) lgkmcnt(3)
	v_fma_f32 v144, v244, v144, v196
	v_fma_f32 v145, v245, v145, v197
	v_fma_f32 v146, v246, v146, v198
	v_fma_f32 v147, v247, v147, v199
	global_store_dwordx4 v241, v[144:147], s[14:15] offset:256 sc1
	s_waitcnt vmcnt(7) lgkmcnt(2)
	v_fma_f32 v148, v244, v148, v200
	v_fma_f32 v149, v245, v149, v201
	v_fma_f32 v150, v246, v150, v202
	v_fma_f32 v151, v247, v151, v203
	global_store_dwordx4 v242, v[148:151], s[14:15] offset:256 sc1
	s_waitcnt vmcnt(7) lgkmcnt(1)
	v_fma_f32 v152, v244, v152, v204
	v_fma_f32 v153, v245, v153, v205
	v_fma_f32 v154, v246, v154, v206
	v_fma_f32 v155, v247, v155, v207
	global_store_dwordx4 v243, v[152:155], s[14:15] offset:256 sc1
	s_waitcnt vmcnt(7) lgkmcnt(0)
	v_fma_f32 v156, v244, v156, v184
	v_fma_f32 v157, v245, v157, v185
	v_fma_f32 v158, v246, v158, v186
	v_fma_f32 v159, v247, v159, v187
	global_store_dwordx4 v248, v[156:159], s[14:15] offset:256 sc1
	s_waitcnt lgkmcnt(0)
	s_mov_b32 s100, 0
	s_barrier
	s_branch .LBB0_926

.Lg16_gu_k:
	s_add_i32 s8, s1, 2
	s_lshl_b32 s96, s8, 13
	s_add_i32 m0, vcc_lo, 16384
	v_lshl_add_u64 v[160:161], v[188:189], 0, s[96:97]
	global_load_lds_dwordx4 v[160:161], off
	global_load_lds_dwordx4 v[160:161], off offset:1024
	ds_read_b128 v[196:199], v246 offset:0
	ds_read_b128 v[200:203], v162 offset:0
	ds_read_b128 v[204:207], v246 offset:2048
	ds_read_b128 v[242:245], v162 offset:2048
	s_add_i32 s8, s1, 2
	s_lshl_b32 s96, s8, 11
	v_lshl_add_u64 v[248:249], v[184:185], 0, s[96:97]
	v_lshl_add_u64 v[250:251], v[186:187], 0, s[96:97]
	s_waitcnt vmcnt(8) lgkmcnt(3)
	v_mfma_f32_16x16x32_bf16 v[112:115], v[196:199], v[128:131], v[112:115]
	v_mfma_f32_16x16x32_bf16 v[120:123], v[196:199], v[132:135], v[120:123]
	v_mfma_f32_16x16x32_bf16 v[80:83], v[196:199], v[136:139], v[80:83]
	v_mfma_f32_16x16x32_bf16 v[88:91], v[196:199], v[140:143], v[88:91]
	ds_read_b128 v[196:199], v246 offset:4096
	s_waitcnt lgkmcnt(3)
	v_mfma_f32_16x16x32_bf16 v[116:119], v[200:203], v[128:131], v[116:119]
	v_mfma_f32_16x16x32_bf16 v[124:127], v[200:203], v[132:135], v[124:127]
	v_mfma_f32_16x16x32_bf16 v[84:87], v[200:203], v[136:139], v[84:87]
	v_mfma_f32_16x16x32_bf16 v[92:95], v[200:203], v[140:143], v[92:95]
	ds_read_b128 v[200:203], v162 offset:4096
	s_waitcnt lgkmcnt(3)
	v_mfma_f32_16x16x32_bf16 v[96:99], v[204:207], v[128:131], v[96:99]
	v_mfma_f32_16x16x32_bf16 v[104:107], v[204:207], v[132:135], v[104:107]
	v_mfma_f32_16x16x32_bf16 v[64:67], v[204:207], v[136:139], v[64:67]
	v_mfma_f32_16x16x32_bf16 v[72:75], v[204:207], v[140:143], v[72:75]
	ds_read_b128 v[204:207], v246 offset:6144
	s_waitcnt lgkmcnt(3)
	v_mfma_f32_16x16x32_bf16 v[100:103], v[242:245], v[128:131], v[100:103]
	v_mfma_f32_16x16x32_bf16 v[108:111], v[242:245], v[132:135], v[108:111]
	v_mfma_f32_16x16x32_bf16 v[68:71], v[242:245], v[136:139], v[68:71]
	v_mfma_f32_16x16x32_bf16 v[76:79], v[242:245], v[140:143], v[76:79]
	ds_read_b128 v[242:245], v162 offset:6144
	s_waitcnt lgkmcnt(3)
	v_mfma_f32_16x16x32_bf16 v[48:51], v[196:199], v[128:131], v[48:51]
	v_mfma_f32_16x16x32_bf16 v[56:59], v[196:199], v[132:135], v[56:59]
	v_mfma_f32_16x16x32_bf16 v[16:19], v[196:199], v[136:139], v[16:19]
	v_mfma_f32_16x16x32_bf16 v[24:27], v[196:199], v[140:143], v[24:27]
	s_waitcnt lgkmcnt(2)
	v_mfma_f32_16x16x32_bf16 v[52:55], v[200:203], v[128:131], v[52:55]
	v_mfma_f32_16x16x32_bf16 v[60:63], v[200:203], v[132:135], v[60:63]
	v_mfma_f32_16x16x32_bf16 v[20:23], v[200:203], v[136:139], v[20:23]
	v_mfma_f32_16x16x32_bf16 v[28:31], v[200:203], v[140:143], v[28:31]
	s_waitcnt lgkmcnt(1)
	v_mfma_f32_16x16x32_bf16 v[32:35], v[204:207], v[128:131], v[32:35]
	v_mfma_f32_16x16x32_bf16 v[40:43], v[204:207], v[132:135], v[40:43]
	v_mfma_f32_16x16x32_bf16 v[0:3], v[204:207], v[136:139], v[0:3]
	v_mfma_f32_16x16x32_bf16 v[8:11], v[204:207], v[140:143], v[8:11]
	s_waitcnt lgkmcnt(0)
	v_mfma_f32_16x16x32_bf16 v[36:39], v[242:245], v[128:131], v[36:39]
	v_mfma_f32_16x16x32_bf16 v[44:47], v[242:245], v[132:135], v[44:47]
	v_mfma_f32_16x16x32_bf16 v[4:7], v[242:245], v[136:139], v[4:7]
	v_mfma_f32_16x16x32_bf16 v[12:15], v[242:245], v[140:143], v[12:15]
	global_load_dwordx4 v[128:131], v[248:249], off
	global_load_dwordx4 v[132:135], v[248:249], off offset:256
	global_load_dwordx4 v[136:139], v[250:251], off
	global_load_dwordx4 v[140:143], v[250:251], off offset:256
	s_waitcnt vmcnt(10)
	s_barrier
	s_add_i32 s8, s1, 3
	s_lshl_b32 s96, s8, 13
	s_mov_b32 m0, vcc_lo
	v_lshl_add_u64 v[160:161], v[188:189], 0, s[96:97]
	global_load_lds_dwordx4 v[160:161], off
	global_load_lds_dwordx4 v[160:161], off offset:1024
	ds_read_b128 v[196:199], v246 offset:8192
	ds_read_b128 v[200:203], v162 offset:8192
	ds_read_b128 v[204:207], v246 offset:10240
	ds_read_b128 v[242:245], v162 offset:10240
	s_add_i32 s8, s1, 3
	s_lshl_b32 s96, s8, 11
	v_lshl_add_u64 v[248:249], v[184:185], 0, s[96:97]
	v_lshl_add_u64 v[250:251], v[186:187], 0, s[96:97]
	s_waitcnt vmcnt(8) lgkmcnt(3)
	v_mfma_f32_16x16x32_bf16 v[112:115], v[196:199], v[144:147], v[112:115]
	v_mfma_f32_16x16x32_bf16 v[120:123], v[196:199], v[148:151], v[120:123]
	v_mfma_f32_16x16x32_bf16 v[80:83], v[196:199], v[152:155], v[80:83]
	v_mfma_f32_16x16x32_bf16 v[88:91], v[196:199], v[156:159], v[88:91]
	ds_read_b128 v[196:199], v246 offset:12288
	s_waitcnt lgkmcnt(3)
	v_mfma_f32_16x16x32_bf16 v[116:119], v[200:203], v[144:147], v[116:119]
	v_mfma_f32_16x16x32_bf16 v[124:127], v[200:203], v[148:151], v[124:127]
	v_mfma_f32_16x16x32_bf16 v[84:87], v[200:203], v[152:155], v[84:87]
	v_mfma_f32_16x16x32_bf16 v[92:95], v[200:203], v[156:159], v[92:95]
	ds_read_b128 v[200:203], v162 offset:12288
	s_waitcnt lgkmcnt(3)
	v_mfma_f32_16x16x32_bf16 v[96:99], v[204:207], v[144:147], v[96:99]
	v_mfma_f32_16x16x32_bf16 v[104:107], v[204:207], v[148:151], v[104:107]
	v_mfma_f32_16x16x32_bf16 v[64:67], v[204:207], v[152:155], v[64:67]
	v_mfma_f32_16x16x32_bf16 v[72:75], v[204:207], v[156:159], v[72:75]
	ds_read_b128 v[204:207], v246 offset:14336
	s_waitcnt lgkmcnt(3)
	v_mfma_f32_16x16x32_bf16 v[100:103], v[242:245], v[144:147], v[100:103]
	v_mfma_f32_16x16x32_bf16 v[108:111], v[242:245], v[148:151], v[108:111]
	v_mfma_f32_16x16x32_bf16 v[68:71], v[242:245], v[152:155], v[68:71]
	v_mfma_f32_16x16x32_bf16 v[76:79], v[242:245], v[156:159], v[76:79]
	ds_read_b128 v[242:245], v162 offset:14336
	s_waitcnt lgkmcnt(3)
	v_mfma_f32_16x16x32_bf16 v[48:51], v[196:199], v[144:147], v[48:51]
	v_mfma_f32_16x16x32_bf16 v[56:59], v[196:199], v[148:151], v[56:59]
	v_mfma_f32_16x16x32_bf16 v[16:19], v[196:199], v[152:155], v[16:19]
	v_mfma_f32_16x16x32_bf16 v[24:27], v[196:199], v[156:159], v[24:27]
	s_waitcnt lgkmcnt(2)
	v_mfma_f32_16x16x32_bf16 v[52:55], v[200:203], v[144:147], v[52:55]
	v_mfma_f32_16x16x32_bf16 v[60:63], v[200:203], v[148:151], v[60:63]
	v_mfma_f32_16x16x32_bf16 v[20:23], v[200:203], v[152:155], v[20:23]
	v_mfma_f32_16x16x32_bf16 v[28:31], v[200:203], v[156:159], v[28:31]
	s_waitcnt lgkmcnt(1)
	v_mfma_f32_16x16x32_bf16 v[32:35], v[204:207], v[144:147], v[32:35]
	v_mfma_f32_16x16x32_bf16 v[40:43], v[204:207], v[148:151], v[40:43]
	v_mfma_f32_16x16x32_bf16 v[0:3], v[204:207], v[152:155], v[0:3]
	v_mfma_f32_16x16x32_bf16 v[8:11], v[204:207], v[156:159], v[8:11]
	s_waitcnt lgkmcnt(0)
	v_mfma_f32_16x16x32_bf16 v[36:39], v[242:245], v[144:147], v[36:39]
	v_mfma_f32_16x16x32_bf16 v[44:47], v[242:245], v[148:151], v[44:47]
	v_mfma_f32_16x16x32_bf16 v[4:7], v[242:245], v[152:155], v[4:7]
	v_mfma_f32_16x16x32_bf16 v[12:15], v[242:245], v[156:159], v[12:15]
	global_load_dwordx4 v[144:147], v[248:249], off
	global_load_dwordx4 v[148:151], v[248:249], off offset:256
	global_load_dwordx4 v[152:155], v[250:251], off
	global_load_dwordx4 v[156:159], v[250:251], off offset:256
	s_waitcnt vmcnt(10)
	s_barrier
	s_add_i32 s8, s1, 4
	s_lshl_b32 s96, s8, 13
	s_add_i32 m0, vcc_lo, 8192
	v_lshl_add_u64 v[160:161], v[188:189], 0, s[96:97]
	global_load_lds_dwordx4 v[160:161], off
	global_load_lds_dwordx4 v[160:161], off offset:1024
	ds_read_b128 v[196:199], v246 offset:16384
	ds_read_b128 v[200:203], v162 offset:16384
	ds_read_b128 v[204:207], v246 offset:18432
	ds_read_b128 v[242:245], v162 offset:18432
	s_add_i32 s8, s1, 4
	s_lshl_b32 s96, s8, 11
	v_lshl_add_u64 v[248:249], v[184:185], 0, s[96:97]
	v_lshl_add_u64 v[250:251], v[186:187], 0, s[96:97]
	s_waitcnt vmcnt(8) lgkmcnt(3)
	v_mfma_f32_16x16x32_bf16 v[112:115], v[196:199], v[128:131], v[112:115]
	v_mfma_f32_16x16x32_bf16 v[120:123], v[196:199], v[132:135], v[120:123]
	v_mfma_f32_16x16x32_bf16 v[80:83], v[196:199], v[136:139], v[80:83]
	v_mfma_f32_16x16x32_bf16 v[88:91], v[196:199], v[140:143], v[88:91]
	ds_read_b128 v[196:199], v246 offset:20480
	s_waitcnt lgkmcnt(3)
	v_mfma_f32_16x16x32_bf16 v[116:119], v[200:203], v[128:131], v[116:119]
	v_mfma_f32_16x16x32_bf16 v[124:127], v[200:203], v[132:135], v[124:127]
	v_mfma_f32_16x16x32_bf16 v[84:87], v[200:203], v[136:139], v[84:87]
	v_mfma_f32_16x16x32_bf16 v[92:95], v[200:203], v[140:143], v[92:95]
	ds_read_b128 v[200:203], v162 offset:20480
	s_waitcnt lgkmcnt(3)
	v_mfma_f32_16x16x32_bf16 v[96:99], v[204:207], v[128:131], v[96:99]
	v_mfma_f32_16x16x32_bf16 v[104:107], v[204:207], v[132:135], v[104:107]
	v_mfma_f32_16x16x32_bf16 v[64:67], v[204:207], v[136:139], v[64:67]
	v_mfma_f32_16x16x32_bf16 v[72:75], v[204:207], v[140:143], v[72:75]
	ds_read_b128 v[204:207], v246 offset:22528
	s_waitcnt lgkmcnt(3)
	v_mfma_f32_16x16x32_bf16 v[100:103], v[242:245], v[128:131], v[100:103]
	v_mfma_f32_16x16x32_bf16 v[108:111], v[242:245], v[132:135], v[108:111]
	v_mfma_f32_16x16x32_bf16 v[68:71], v[242:245], v[136:139], v[68:71]
	v_mfma_f32_16x16x32_bf16 v[76:79], v[242:245], v[140:143], v[76:79]
	ds_read_b128 v[242:245], v162 offset:22528
	s_waitcnt lgkmcnt(3)
	v_mfma_f32_16x16x32_bf16 v[48:51], v[196:199], v[128:131], v[48:51]
	v_mfma_f32_16x16x32_bf16 v[56:59], v[196:199], v[132:135], v[56:59]
	v_mfma_f32_16x16x32_bf16 v[16:19], v[196:199], v[136:139], v[16:19]
	v_mfma_f32_16x16x32_bf16 v[24:27], v[196:199], v[140:143], v[24:27]
	s_waitcnt lgkmcnt(2)
	v_mfma_f32_16x16x32_bf16 v[52:55], v[200:203], v[128:131], v[52:55]
	v_mfma_f32_16x16x32_bf16 v[60:63], v[200:203], v[132:135], v[60:63]
	v_mfma_f32_16x16x32_bf16 v[20:23], v[200:203], v[136:139], v[20:23]
	v_mfma_f32_16x16x32_bf16 v[28:31], v[200:203], v[140:143], v[28:31]
	s_waitcnt lgkmcnt(1)
	v_mfma_f32_16x16x32_bf16 v[32:35], v[204:207], v[128:131], v[32:35]
	v_mfma_f32_16x16x32_bf16 v[40:43], v[204:207], v[132:135], v[40:43]
	v_mfma_f32_16x16x32_bf16 v[0:3], v[204:207], v[136:139], v[0:3]
	v_mfma_f32_16x16x32_bf16 v[8:11], v[204:207], v[140:143], v[8:11]
	s_waitcnt lgkmcnt(0)
	v_mfma_f32_16x16x32_bf16 v[36:39], v[242:245], v[128:131], v[36:39]
	v_mfma_f32_16x16x32_bf16 v[44:47], v[242:245], v[132:135], v[44:47]
	v_mfma_f32_16x16x32_bf16 v[4:7], v[242:245], v[136:139], v[4:7]
	v_mfma_f32_16x16x32_bf16 v[12:15], v[242:245], v[140:143], v[12:15]
	global_load_dwordx4 v[128:131], v[248:249], off
	global_load_dwordx4 v[132:135], v[248:249], off offset:256
	global_load_dwordx4 v[136:139], v[250:251], off
	global_load_dwordx4 v[140:143], v[250:251], off offset:256
	s_waitcnt vmcnt(10)
	s_barrier
	s_add_i32 s8, s1, 5
	s_lshl_b32 s96, s8, 13
	s_add_i32 m0, vcc_lo, 16384
	v_lshl_add_u64 v[160:161], v[188:189], 0, s[96:97]
	global_load_lds_dwordx4 v[160:161], off
	global_load_lds_dwordx4 v[160:161], off offset:1024
	ds_read_b128 v[196:199], v246 offset:0
	ds_read_b128 v[200:203], v162 offset:0
	ds_read_b128 v[204:207], v246 offset:2048
	ds_read_b128 v[242:245], v162 offset:2048
	s_add_i32 s8, s1, 5
	s_lshl_b32 s96, s8, 11
	v_lshl_add_u64 v[248:249], v[184:185], 0, s[96:97]
	v_lshl_add_u64 v[250:251], v[186:187], 0, s[96:97]
	s_waitcnt vmcnt(8) lgkmcnt(3)
	v_mfma_f32_16x16x32_bf16 v[112:115], v[196:199], v[144:147], v[112:115]
	v_mfma_f32_16x16x32_bf16 v[120:123], v[196:199], v[148:151], v[120:123]
	v_mfma_f32_16x16x32_bf16 v[80:83], v[196:199], v[152:155], v[80:83]
	v_mfma_f32_16x16x32_bf16 v[88:91], v[196:199], v[156:159], v[88:91]
	ds_read_b128 v[196:199], v246 offset:4096
	s_waitcnt lgkmcnt(3)
	v_mfma_f32_16x16x32_bf16 v[116:119], v[200:203], v[144:147], v[116:119]
	v_mfma_f32_16x16x32_bf16 v[124:127], v[200:203], v[148:151], v[124:127]
	v_mfma_f32_16x16x32_bf16 v[84:87], v[200:203], v[152:155], v[84:87]
	v_mfma_f32_16x16x32_bf16 v[92:95], v[200:203], v[156:159], v[92:95]
	ds_read_b128 v[200:203], v162 offset:4096
	s_waitcnt lgkmcnt(3)
	v_mfma_f32_16x16x32_bf16 v[96:99], v[204:207], v[144:147], v[96:99]
	v_mfma_f32_16x16x32_bf16 v[104:107], v[204:207], v[148:151], v[104:107]
	v_mfma_f32_16x16x32_bf16 v[64:67], v[204:207], v[152:155], v[64:67]
	v_mfma_f32_16x16x32_bf16 v[72:75], v[204:207], v[156:159], v[72:75]
	ds_read_b128 v[204:207], v246 offset:6144
	s_waitcnt lgkmcnt(3)
	v_mfma_f32_16x16x32_bf16 v[100:103], v[242:245], v[144:147], v[100:103]
	v_mfma_f32_16x16x32_bf16 v[108:111], v[242:245], v[148:151], v[108:111]
	v_mfma_f32_16x16x32_bf16 v[68:71], v[242:245], v[152:155], v[68:71]
	v_mfma_f32_16x16x32_bf16 v[76:79], v[242:245], v[156:159], v[76:79]
	ds_read_b128 v[242:245], v162 offset:6144
	s_waitcnt lgkmcnt(3)
	v_mfma_f32_16x16x32_bf16 v[48:51], v[196:199], v[144:147], v[48:51]
	v_mfma_f32_16x16x32_bf16 v[56:59], v[196:199], v[148:151], v[56:59]
	v_mfma_f32_16x16x32_bf16 v[16:19], v[196:199], v[152:155], v[16:19]
	v_mfma_f32_16x16x32_bf16 v[24:27], v[196:199], v[156:159], v[24:27]
	s_waitcnt lgkmcnt(2)
	v_mfma_f32_16x16x32_bf16 v[52:55], v[200:203], v[144:147], v[52:55]
	v_mfma_f32_16x16x32_bf16 v[60:63], v[200:203], v[148:151], v[60:63]
	v_mfma_f32_16x16x32_bf16 v[20:23], v[200:203], v[152:155], v[20:23]
	v_mfma_f32_16x16x32_bf16 v[28:31], v[200:203], v[156:159], v[28:31]
	s_waitcnt lgkmcnt(1)
	v_mfma_f32_16x16x32_bf16 v[32:35], v[204:207], v[144:147], v[32:35]
	v_mfma_f32_16x16x32_bf16 v[40:43], v[204:207], v[148:151], v[40:43]
	v_mfma_f32_16x16x32_bf16 v[0:3], v[204:207], v[152:155], v[0:3]
	v_mfma_f32_16x16x32_bf16 v[8:11], v[204:207], v[156:159], v[8:11]
	s_waitcnt lgkmcnt(0)
	v_mfma_f32_16x16x32_bf16 v[36:39], v[242:245], v[144:147], v[36:39]
	v_mfma_f32_16x16x32_bf16 v[44:47], v[242:245], v[148:151], v[44:47]
	v_mfma_f32_16x16x32_bf16 v[4:7], v[242:245], v[152:155], v[4:7]
	v_mfma_f32_16x16x32_bf16 v[12:15], v[242:245], v[156:159], v[12:15]
	global_load_dwordx4 v[144:147], v[248:249], off
	global_load_dwordx4 v[148:151], v[248:249], off offset:256
	global_load_dwordx4 v[152:155], v[250:251], off
	global_load_dwordx4 v[156:159], v[250:251], off offset:256
	s_waitcnt vmcnt(10)
	s_barrier
	s_add_i32 s8, s1, 6
	s_lshl_b32 s96, s8, 13
	s_mov_b32 m0, vcc_lo
	v_lshl_add_u64 v[160:161], v[188:189], 0, s[96:97]
	global_load_lds_dwordx4 v[160:161], off
	global_load_lds_dwordx4 v[160:161], off offset:1024
	ds_read_b128 v[196:199], v246 offset:8192
	ds_read_b128 v[200:203], v162 offset:8192
	ds_read_b128 v[204:207], v246 offset:10240
	ds_read_b128 v[242:245], v162 offset:10240
	s_add_i32 s8, s1, 6
	s_lshl_b32 s96, s8, 11
	v_lshl_add_u64 v[248:249], v[184:185], 0, s[96:97]
	v_lshl_add_u64 v[250:251], v[186:187], 0, s[96:97]
	s_waitcnt vmcnt(8) lgkmcnt(3)
	v_mfma_f32_16x16x32_bf16 v[112:115], v[196:199], v[128:131], v[112:115]
	v_mfma_f32_16x16x32_bf16 v[120:123], v[196:199], v[132:135], v[120:123]
	v_mfma_f32_16x16x32_bf16 v[80:83], v[196:199], v[136:139], v[80:83]
	v_mfma_f32_16x16x32_bf16 v[88:91], v[196:199], v[140:143], v[88:91]
	ds_read_b128 v[196:199], v246 offset:12288
	s_waitcnt lgkmcnt(3)
	v_mfma_f32_16x16x32_bf16 v[116:119], v[200:203], v[128:131], v[116:119]
	v_mfma_f32_16x16x32_bf16 v[124:127], v[200:203], v[132:135], v[124:127]
	v_mfma_f32_16x16x32_bf16 v[84:87], v[200:203], v[136:139], v[84:87]
	v_mfma_f32_16x16x32_bf16 v[92:95], v[200:203], v[140:143], v[92:95]
	ds_read_b128 v[200:203], v162 offset:12288
	s_waitcnt lgkmcnt(3)
	v_mfma_f32_16x16x32_bf16 v[96:99], v[204:207], v[128:131], v[96:99]
	v_mfma_f32_16x16x32_bf16 v[104:107], v[204:207], v[132:135], v[104:107]
	v_mfma_f32_16x16x32_bf16 v[64:67], v[204:207], v[136:139], v[64:67]
	v_mfma_f32_16x16x32_bf16 v[72:75], v[204:207], v[140:143], v[72:75]
	ds_read_b128 v[204:207], v246 offset:14336
	s_waitcnt lgkmcnt(3)
	v_mfma_f32_16x16x32_bf16 v[100:103], v[242:245], v[128:131], v[100:103]
	v_mfma_f32_16x16x32_bf16 v[108:111], v[242:245], v[132:135], v[108:111]
	v_mfma_f32_16x16x32_bf16 v[68:71], v[242:245], v[136:139], v[68:71]
	v_mfma_f32_16x16x32_bf16 v[76:79], v[242:245], v[140:143], v[76:79]
	ds_read_b128 v[242:245], v162 offset:14336
	s_waitcnt lgkmcnt(3)
	v_mfma_f32_16x16x32_bf16 v[48:51], v[196:199], v[128:131], v[48:51]
	v_mfma_f32_16x16x32_bf16 v[56:59], v[196:199], v[132:135], v[56:59]
	v_mfma_f32_16x16x32_bf16 v[16:19], v[196:199], v[136:139], v[16:19]
	v_mfma_f32_16x16x32_bf16 v[24:27], v[196:199], v[140:143], v[24:27]
	s_waitcnt lgkmcnt(2)
	v_mfma_f32_16x16x32_bf16 v[52:55], v[200:203], v[128:131], v[52:55]
	v_mfma_f32_16x16x32_bf16 v[60:63], v[200:203], v[132:135], v[60:63]
	v_mfma_f32_16x16x32_bf16 v[20:23], v[200:203], v[136:139], v[20:23]
	v_mfma_f32_16x16x32_bf16 v[28:31], v[200:203], v[140:143], v[28:31]
	s_waitcnt lgkmcnt(1)
	v_mfma_f32_16x16x32_bf16 v[32:35], v[204:207], v[128:131], v[32:35]
	v_mfma_f32_16x16x32_bf16 v[40:43], v[204:207], v[132:135], v[40:43]
	v_mfma_f32_16x16x32_bf16 v[0:3], v[204:207], v[136:139], v[0:3]
	v_mfma_f32_16x16x32_bf16 v[8:11], v[204:207], v[140:143], v[8:11]
	s_waitcnt lgkmcnt(0)
	v_mfma_f32_16x16x32_bf16 v[36:39], v[242:245], v[128:131], v[36:39]
	v_mfma_f32_16x16x32_bf16 v[44:47], v[242:245], v[132:135], v[44:47]
	v_mfma_f32_16x16x32_bf16 v[4:7], v[242:245], v[136:139], v[4:7]
	v_mfma_f32_16x16x32_bf16 v[12:15], v[242:245], v[140:143], v[12:15]
	global_load_dwordx4 v[128:131], v[248:249], off
	global_load_dwordx4 v[132:135], v[248:249], off offset:256
	global_load_dwordx4 v[136:139], v[250:251], off
	global_load_dwordx4 v[140:143], v[250:251], off offset:256
	s_waitcnt vmcnt(10)
	s_barrier
	s_add_i32 s8, s1, 7
	s_lshl_b32 s96, s8, 13
	s_add_i32 m0, vcc_lo, 8192
	v_lshl_add_u64 v[160:161], v[188:189], 0, s[96:97]
	global_load_lds_dwordx4 v[160:161], off
	global_load_lds_dwordx4 v[160:161], off offset:1024
	ds_read_b128 v[196:199], v246 offset:16384
	ds_read_b128 v[200:203], v162 offset:16384
	ds_read_b128 v[204:207], v246 offset:18432
	ds_read_b128 v[242:245], v162 offset:18432
	s_add_i32 s8, s1, 7
	s_lshl_b32 s96, s8, 11
	v_lshl_add_u64 v[248:249], v[184:185], 0, s[96:97]
	v_lshl_add_u64 v[250:251], v[186:187], 0, s[96:97]
	s_waitcnt vmcnt(8) lgkmcnt(3)
	v_mfma_f32_16x16x32_bf16 v[112:115], v[196:199], v[144:147], v[112:115]
	v_mfma_f32_16x16x32_bf16 v[120:123], v[196:199], v[148:151], v[120:123]
	v_mfma_f32_16x16x32_bf16 v[80:83], v[196:199], v[152:155], v[80:83]
	v_mfma_f32_16x16x32_bf16 v[88:91], v[196:199], v[156:159], v[88:91]
	ds_read_b128 v[196:199], v246 offset:20480
	s_waitcnt lgkmcnt(3)
	v_mfma_f32_16x16x32_bf16 v[116:119], v[200:203], v[144:147], v[116:119]
	v_mfma_f32_16x16x32_bf16 v[124:127], v[200:203], v[148:151], v[124:127]
	v_mfma_f32_16x16x32_bf16 v[84:87], v[200:203], v[152:155], v[84:87]
	v_mfma_f32_16x16x32_bf16 v[92:95], v[200:203], v[156:159], v[92:95]
	ds_read_b128 v[200:203], v162 offset:20480
	s_waitcnt lgkmcnt(3)
	v_mfma_f32_16x16x32_bf16 v[96:99], v[204:207], v[144:147], v[96:99]
	v_mfma_f32_16x16x32_bf16 v[104:107], v[204:207], v[148:151], v[104:107]
	v_mfma_f32_16x16x32_bf16 v[64:67], v[204:207], v[152:155], v[64:67]
	v_mfma_f32_16x16x32_bf16 v[72:75], v[204:207], v[156:159], v[72:75]
	ds_read_b128 v[204:207], v246 offset:22528
	s_waitcnt lgkmcnt(3)
	v_mfma_f32_16x16x32_bf16 v[100:103], v[242:245], v[144:147], v[100:103]
	v_mfma_f32_16x16x32_bf16 v[108:111], v[242:245], v[148:151], v[108:111]
	v_mfma_f32_16x16x32_bf16 v[68:71], v[242:245], v[152:155], v[68:71]
	v_mfma_f32_16x16x32_bf16 v[76:79], v[242:245], v[156:159], v[76:79]
	ds_read_b128 v[242:245], v162 offset:22528
	s_waitcnt lgkmcnt(3)
	v_mfma_f32_16x16x32_bf16 v[48:51], v[196:199], v[144:147], v[48:51]
	v_mfma_f32_16x16x32_bf16 v[56:59], v[196:199], v[148:151], v[56:59]
	v_mfma_f32_16x16x32_bf16 v[16:19], v[196:199], v[152:155], v[16:19]
	v_mfma_f32_16x16x32_bf16 v[24:27], v[196:199], v[156:159], v[24:27]
	s_waitcnt lgkmcnt(2)
	v_mfma_f32_16x16x32_bf16 v[52:55], v[200:203], v[144:147], v[52:55]
	v_mfma_f32_16x16x32_bf16 v[60:63], v[200:203], v[148:151], v[60:63]
	v_mfma_f32_16x16x32_bf16 v[20:23], v[200:203], v[152:155], v[20:23]
	v_mfma_f32_16x16x32_bf16 v[28:31], v[200:203], v[156:159], v[28:31]
	s_waitcnt lgkmcnt(1)
	v_mfma_f32_16x16x32_bf16 v[32:35], v[204:207], v[144:147], v[32:35]
	v_mfma_f32_16x16x32_bf16 v[40:43], v[204:207], v[148:151], v[40:43]
	v_mfma_f32_16x16x32_bf16 v[0:3], v[204:207], v[152:155], v[0:3]
	v_mfma_f32_16x16x32_bf16 v[8:11], v[204:207], v[156:159], v[8:11]
	s_waitcnt lgkmcnt(0)
	v_mfma_f32_16x16x32_bf16 v[36:39], v[242:245], v[144:147], v[36:39]
	v_mfma_f32_16x16x32_bf16 v[44:47], v[242:245], v[148:151], v[44:47]
	v_mfma_f32_16x16x32_bf16 v[4:7], v[242:245], v[152:155], v[4:7]
	v_mfma_f32_16x16x32_bf16 v[12:15], v[242:245], v[156:159], v[12:15]
	global_load_dwordx4 v[144:147], v[248:249], off
	global_load_dwordx4 v[148:151], v[248:249], off offset:256
	global_load_dwordx4 v[152:155], v[250:251], off
	global_load_dwordx4 v[156:159], v[250:251], off offset:256
	s_waitcnt vmcnt(10)
	s_barrier
	s_add_i32 s1, s1, 6
	s_cmp_lt_u32 s1, 30
	s_cbranch_scc1 .Lg16_gu_k
	ds_read_b128 v[196:199], v246 offset:0
	ds_read_b128 v[200:203], v162 offset:0
	ds_read_b128 v[204:207], v246 offset:2048
	ds_read_b128 v[242:245], v162 offset:2048
	s_waitcnt vmcnt(6) lgkmcnt(3)
	v_mfma_f32_16x16x32_bf16 v[112:115], v[196:199], v[128:131], v[112:115]
	v_mfma_f32_16x16x32_bf16 v[120:123], v[196:199], v[132:135], v[120:123]
	v_mfma_f32_16x16x32_bf16 v[80:83], v[196:199], v[136:139], v[80:83]
	v_mfma_f32_16x16x32_bf16 v[88:91], v[196:199], v[140:143], v[88:91]
	ds_read_b128 v[196:199], v246 offset:4096
	s_waitcnt lgkmcnt(3)
	v_mfma_f32_16x16x32_bf16 v[116:119], v[200:203], v[128:131], v[116:119]
	v_mfma_f32_16x16x32_bf16 v[124:127], v[200:203], v[132:135], v[124:127]
	v_mfma_f32_16x16x32_bf16 v[84:87], v[200:203], v[136:139], v[84:87]
	v_mfma_f32_16x16x32_bf16 v[92:95], v[200:203], v[140:143], v[92:95]
	ds_read_b128 v[200:203], v162 offset:4096
	s_waitcnt lgkmcnt(3)
	v_mfma_f32_16x16x32_bf16 v[96:99], v[204:207], v[128:131], v[96:99]
	v_mfma_f32_16x16x32_bf16 v[104:107], v[204:207], v[132:135], v[104:107]
	v_mfma_f32_16x16x32_bf16 v[64:67], v[204:207], v[136:139], v[64:67]
	v_mfma_f32_16x16x32_bf16 v[72:75], v[204:207], v[140:143], v[72:75]
	ds_read_b128 v[204:207], v246 offset:6144
	s_waitcnt lgkmcnt(3)
	v_mfma_f32_16x16x32_bf16 v[100:103], v[242:245], v[128:131], v[100:103]
	v_mfma_f32_16x16x32_bf16 v[108:111], v[242:245], v[132:135], v[108:111]
	v_mfma_f32_16x16x32_bf16 v[68:71], v[242:245], v[136:139], v[68:71]
	v_mfma_f32_16x16x32_bf16 v[76:79], v[242:245], v[140:143], v[76:79]
	ds_read_b128 v[242:245], v162 offset:6144
	s_waitcnt lgkmcnt(3)
	v_mfma_f32_16x16x32_bf16 v[48:51], v[196:199], v[128:131], v[48:51]
	v_mfma_f32_16x16x32_bf16 v[56:59], v[196:199], v[132:135], v[56:59]
	v_mfma_f32_16x16x32_bf16 v[16:19], v[196:199], v[136:139], v[16:19]
	v_mfma_f32_16x16x32_bf16 v[24:27], v[196:199], v[140:143], v[24:27]
	s_waitcnt lgkmcnt(2)
	v_mfma_f32_16x16x32_bf16 v[52:55], v[200:203], v[128:131], v[52:55]
	v_mfma_f32_16x16x32_bf16 v[60:63], v[200:203], v[132:135], v[60:63]
	v_mfma_f32_16x16x32_bf16 v[20:23], v[200:203], v[136:139], v[20:23]
	v_mfma_f32_16x16x32_bf16 v[28:31], v[200:203], v[140:143], v[28:31]
	s_waitcnt lgkmcnt(1)
	v_mfma_f32_16x16x32_bf16 v[32:35], v[204:207], v[128:131], v[32:35]
	v_mfma_f32_16x16x32_bf16 v[40:43], v[204:207], v[132:135], v[40:43]
	v_mfma_f32_16x16x32_bf16 v[0:3], v[204:207], v[136:139], v[0:3]
	v_mfma_f32_16x16x32_bf16 v[8:11], v[204:207], v[140:143], v[8:11]
	s_waitcnt lgkmcnt(0)
	v_mfma_f32_16x16x32_bf16 v[36:39], v[242:245], v[128:131], v[36:39]
	v_mfma_f32_16x16x32_bf16 v[44:47], v[242:245], v[132:135], v[44:47]
	v_mfma_f32_16x16x32_bf16 v[4:7], v[242:245], v[136:139], v[4:7]
	v_mfma_f32_16x16x32_bf16 v[12:15], v[242:245], v[140:143], v[12:15]
	s_waitcnt vmcnt(4)
	s_barrier
	ds_read_b128 v[196:199], v246 offset:8192
	ds_read_b128 v[200:203], v162 offset:8192
	ds_read_b128 v[204:207], v246 offset:10240
	ds_read_b128 v[242:245], v162 offset:10240
	s_waitcnt vmcnt(0) lgkmcnt(3)
	v_mfma_f32_16x16x32_bf16 v[112:115], v[196:199], v[144:147], v[112:115]
	v_mfma_f32_16x16x32_bf16 v[120:123], v[196:199], v[148:151], v[120:123]
	v_mfma_f32_16x16x32_bf16 v[80:83], v[196:199], v[152:155], v[80:83]
	v_mfma_f32_16x16x32_bf16 v[88:91], v[196:199], v[156:159], v[88:91]
	ds_read_b128 v[196:199], v246 offset:12288
	s_waitcnt lgkmcnt(3)
	v_mfma_f32_16x16x32_bf16 v[116:119], v[200:203], v[144:147], v[116:119]
	v_mfma_f32_16x16x32_bf16 v[124:127], v[200:203], v[148:151], v[124:127]
	v_mfma_f32_16x16x32_bf16 v[84:87], v[200:203], v[152:155], v[84:87]
	v_mfma_f32_16x16x32_bf16 v[92:95], v[200:203], v[156:159], v[92:95]
	ds_read_b128 v[200:203], v162 offset:12288
	s_waitcnt lgkmcnt(3)
	v_mfma_f32_16x16x32_bf16 v[96:99], v[204:207], v[144:147], v[96:99]
	v_mfma_f32_16x16x32_bf16 v[104:107], v[204:207], v[148:151], v[104:107]
	v_mfma_f32_16x16x32_bf16 v[64:67], v[204:207], v[152:155], v[64:67]
	v_mfma_f32_16x16x32_bf16 v[72:75], v[204:207], v[156:159], v[72:75]
	ds_read_b128 v[204:207], v246 offset:14336
	s_waitcnt lgkmcnt(3)
	v_mfma_f32_16x16x32_bf16 v[100:103], v[242:245], v[144:147], v[100:103]
	v_mfma_f32_16x16x32_bf16 v[108:111], v[242:245], v[148:151], v[108:111]
	v_mfma_f32_16x16x32_bf16 v[68:71], v[242:245], v[152:155], v[68:71]
	v_mfma_f32_16x16x32_bf16 v[76:79], v[242:245], v[156:159], v[76:79]
	ds_read_b128 v[242:245], v162 offset:14336
	s_waitcnt lgkmcnt(3)
	v_mfma_f32_16x16x32_bf16 v[48:51], v[196:199], v[144:147], v[48:51]
	v_mfma_f32_16x16x32_bf16 v[56:59], v[196:199], v[148:151], v[56:59]
	v_mfma_f32_16x16x32_bf16 v[16:19], v[196:199], v[152:155], v[16:19]
	v_mfma_f32_16x16x32_bf16 v[24:27], v[196:199], v[156:159], v[24:27]
	s_waitcnt lgkmcnt(2)
	v_mfma_f32_16x16x32_bf16 v[52:55], v[200:203], v[144:147], v[52:55]
	v_mfma_f32_16x16x32_bf16 v[60:63], v[200:203], v[148:151], v[60:63]
	v_mfma_f32_16x16x32_bf16 v[20:23], v[200:203], v[152:155], v[20:23]
	v_mfma_f32_16x16x32_bf16 v[28:31], v[200:203], v[156:159], v[28:31]
	s_waitcnt lgkmcnt(1)
	v_mfma_f32_16x16x32_bf16 v[32:35], v[204:207], v[144:147], v[32:35]
	v_mfma_f32_16x16x32_bf16 v[40:43], v[204:207], v[148:151], v[40:43]
	v_mfma_f32_16x16x32_bf16 v[0:3], v[204:207], v[152:155], v[0:3]
	v_mfma_f32_16x16x32_bf16 v[8:11], v[204:207], v[156:159], v[8:11]
	s_waitcnt lgkmcnt(0)
	v_mfma_f32_16x16x32_bf16 v[36:39], v[242:245], v[144:147], v[36:39]
	v_mfma_f32_16x16x32_bf16 v[44:47], v[242:245], v[148:151], v[44:47]
	v_mfma_f32_16x16x32_bf16 v[4:7], v[242:245], v[152:155], v[4:7]
	v_mfma_f32_16x16x32_bf16 v[12:15], v[242:245], v[156:159], v[12:15]
	s_barrier
	s_nop 7
	s_nop 1
	s_waitcnt vmcnt(0)
	v_and_b32_e32 v128, 63, v179
	v_lshrrev_b32_e32 v129, 6, v179
	s_lshl_b32 s14, s7, 3
	s_mul_hi_u32 s15, s14, 0x2c000
	s_mul_i32 s14, s14, 0x2c000
	s_lshl_b32 s16, s0, 12
	s_add_u32 s12, s66, s14
	s_addc_u32 s13, s67, s15
	s_add_u32 s12, s12, s16
	s_addc_u32 s13, s13, 0
	v_and_b32_e32 v130, 15, v128
	v_lshlrev_b32_e32 v132, 4, v130
	v_lshrrev_b32_e32 v130, 4, v128
	v_lshl_add_u32 v132, v130, 9, v132
	v_mul_u32_u24_e32 v130, 0x58000, v129
	v_add_u32_e32 v132, v132, v130
	v_add_u32_e32 v133, 0x2c000, v132
	v_mul_f32_e32 v140, 0xbfb8aa3b, v112
	v_mul_f32_e32 v141, 0xbfb8aa3b, v113
	v_mul_f32_e32 v142, 0xbfb8aa3b, v114
	v_mul_f32_e32 v143, 0xbfb8aa3b, v115
	v_mul_f32_e32 v144, 0xbfb8aa3b, v116
	v_mul_f32_e32 v145, 0xbfb8aa3b, v117
	v_mul_f32_e32 v146, 0xbfb8aa3b, v118
	v_mul_f32_e32 v147, 0xbfb8aa3b, v119
	v_exp_f32_e32 v140, v140
	v_exp_f32_e32 v141, v141
	v_exp_f32_e32 v142, v142
	v_exp_f32_e32 v143, v143
	v_exp_f32_e32 v144, v144
	v_exp_f32_e32 v145, v145
	v_exp_f32_e32 v146, v146
	v_exp_f32_e32 v147, v147
	v_add_f32_e32 v140, 1.0, v140
	v_add_f32_e32 v141, 1.0, v141
	v_add_f32_e32 v142, 1.0, v142
	v_add_f32_e32 v143, 1.0, v143
	v_add_f32_e32 v144, 1.0, v144
	v_add_f32_e32 v145, 1.0, v145
	v_add_f32_e32 v146, 1.0, v146
	v_add_f32_e32 v147, 1.0, v147
	v_rcp_f32_e32 v140, v140
	v_rcp_f32_e32 v141, v141
	v_rcp_f32_e32 v142, v142
	v_rcp_f32_e32 v143, v143
	v_rcp_f32_e32 v144, v144
	v_rcp_f32_e32 v145, v145
	v_rcp_f32_e32 v146, v146
	v_rcp_f32_e32 v147, v147
	v_mul_f32_e32 v140, v112, v140
	v_mul_f32_e32 v141, v113, v141
	v_mul_f32_e32 v142, v114, v142
	v_mul_f32_e32 v143, v115, v143
	v_mul_f32_e32 v144, v116, v144
	v_mul_f32_e32 v145, v117, v145
	v_mul_f32_e32 v146, v118, v146
	v_mul_f32_e32 v147, v119, v147
	v_mul_f32_e32 v140, v96, v140
	v_mul_f32_e32 v141, v97, v141
	v_mul_f32_e32 v142, v98, v142
	v_mul_f32_e32 v143, v99, v143
	v_mul_f32_e32 v144, v100, v144
	v_mul_f32_e32 v145, v101, v145
	v_mul_f32_e32 v146, v102, v146
	v_mul_f32_e32 v147, v103, v147
	v_cvt_pk_bf16_f32 v148, v140, v141
	v_cvt_pk_bf16_f32 v149, v142, v143
	v_cvt_pk_bf16_f32 v150, v144, v145
	v_cvt_pk_bf16_f32 v151, v146, v147
	global_store_dwordx4 v132, v[148:151], s[12:13] sc1
	v_mul_f32_e32 v140, 0xbfb8aa3b, v120
	v_mul_f32_e32 v141, 0xbfb8aa3b, v121
	v_mul_f32_e32 v142, 0xbfb8aa3b, v122
	v_mul_f32_e32 v143, 0xbfb8aa3b, v123
	v_mul_f32_e32 v144, 0xbfb8aa3b, v124
	v_mul_f32_e32 v145, 0xbfb8aa3b, v125
	v_mul_f32_e32 v146, 0xbfb8aa3b, v126
	v_mul_f32_e32 v147, 0xbfb8aa3b, v127
	v_exp_f32_e32 v140, v140
	v_exp_f32_e32 v141, v141
	v_exp_f32_e32 v142, v142
	v_exp_f32_e32 v143, v143
	v_exp_f32_e32 v144, v144
	v_exp_f32_e32 v145, v145
	v_exp_f32_e32 v146, v146
	v_exp_f32_e32 v147, v147
	v_add_f32_e32 v140, 1.0, v140
	v_add_f32_e32 v141, 1.0, v141
	v_add_f32_e32 v142, 1.0, v142
	v_add_f32_e32 v143, 1.0, v143
	v_add_f32_e32 v144, 1.0, v144
	v_add_f32_e32 v145, 1.0, v145
	v_add_f32_e32 v146, 1.0, v146
	v_add_f32_e32 v147, 1.0, v147
	v_rcp_f32_e32 v140, v140
	v_rcp_f32_e32 v141, v141
	v_rcp_f32_e32 v142, v142
	v_rcp_f32_e32 v143, v143
	v_rcp_f32_e32 v144, v144
	v_rcp_f32_e32 v145, v145
	v_rcp_f32_e32 v146, v146
	v_rcp_f32_e32 v147, v147
	v_mul_f32_e32 v140, v120, v140
	v_mul_f32_e32 v141, v121, v141
	v_mul_f32_e32 v142, v122, v142
	v_mul_f32_e32 v143, v123, v143
	v_mul_f32_e32 v144, v124, v144
	v_mul_f32_e32 v145, v125, v145
	v_mul_f32_e32 v146, v126, v146
	v_mul_f32_e32 v147, v127, v147
	v_mul_f32_e32 v140, v104, v140
	v_mul_f32_e32 v141, v105, v141
	v_mul_f32_e32 v142, v106, v142
	v_mul_f32_e32 v143, v107, v143
	v_mul_f32_e32 v144, v108, v144
	v_mul_f32_e32 v145, v109, v145
	v_mul_f32_e32 v146, v110, v146
	v_mul_f32_e32 v147, v111, v147
	v_cvt_pk_bf16_f32 v152, v140, v141
	v_cvt_pk_bf16_f32 v153, v142, v143
	v_cvt_pk_bf16_f32 v154, v144, v145
	v_cvt_pk_bf16_f32 v155, v146, v147
	global_store_dwordx4 v132, v[152:155], s[12:13] offset:256 sc1
	v_mul_f32_e32 v140, 0xbfb8aa3b, v80
	v_mul_f32_e32 v141, 0xbfb8aa3b, v81
	v_mul_f32_e32 v142, 0xbfb8aa3b, v82
	v_mul_f32_e32 v143, 0xbfb8aa3b, v83
	v_mul_f32_e32 v144, 0xbfb8aa3b, v84
	v_mul_f32_e32 v145, 0xbfb8aa3b, v85
	v_mul_f32_e32 v146, 0xbfb8aa3b, v86
	v_mul_f32_e32 v147, 0xbfb8aa3b, v87
	v_exp_f32_e32 v140, v140
	v_exp_f32_e32 v141, v141
	v_exp_f32_e32 v142, v142
	v_exp_f32_e32 v143, v143
	v_exp_f32_e32 v144, v144
	v_exp_f32_e32 v145, v145
	v_exp_f32_e32 v146, v146
	v_exp_f32_e32 v147, v147
	v_add_f32_e32 v140, 1.0, v140
	v_add_f32_e32 v141, 1.0, v141
	v_add_f32_e32 v142, 1.0, v142
	v_add_f32_e32 v143, 1.0, v143
	v_add_f32_e32 v144, 1.0, v144
	v_add_f32_e32 v145, 1.0, v145
	v_add_f32_e32 v146, 1.0, v146
	v_add_f32_e32 v147, 1.0, v147
	v_rcp_f32_e32 v140, v140
	v_rcp_f32_e32 v141, v141
	v_rcp_f32_e32 v142, v142
	v_rcp_f32_e32 v143, v143
	v_rcp_f32_e32 v144, v144
	v_rcp_f32_e32 v145, v145
	v_rcp_f32_e32 v146, v146
	v_rcp_f32_e32 v147, v147
	v_mul_f32_e32 v140, v80, v140
	v_mul_f32_e32 v141, v81, v141
	v_mul_f32_e32 v142, v82, v142
	v_mul_f32_e32 v143, v83, v143
	v_mul_f32_e32 v144, v84, v144
	v_mul_f32_e32 v145, v85, v145
	v_mul_f32_e32 v146, v86, v146
	v_mul_f32_e32 v147, v87, v147
	v_mul_f32_e32 v140, v64, v140
	v_mul_f32_e32 v141, v65, v141
	v_mul_f32_e32 v142, v66, v142
	v_mul_f32_e32 v143, v67, v143
	v_mul_f32_e32 v144, v68, v144
	v_mul_f32_e32 v145, v69, v145
	v_mul_f32_e32 v146, v70, v146
	v_mul_f32_e32 v147, v71, v147
	v_cvt_pk_bf16_f32 v156, v140, v141
	v_cvt_pk_bf16_f32 v157, v142, v143
	v_cvt_pk_bf16_f32 v158, v144, v145
	v_cvt_pk_bf16_f32 v159, v146, v147
	global_store_dwordx4 v133, v[156:159], s[12:13] sc1
	v_mul_f32_e32 v140, 0xbfb8aa3b, v88
	v_mul_f32_e32 v141, 0xbfb8aa3b, v89
	v_mul_f32_e32 v142, 0xbfb8aa3b, v90
	v_mul_f32_e32 v143, 0xbfb8aa3b, v91
	v_mul_f32_e32 v144, 0xbfb8aa3b, v92
	v_mul_f32_e32 v145, 0xbfb8aa3b, v93
	v_mul_f32_e32 v146, 0xbfb8aa3b, v94
	v_mul_f32_e32 v147, 0xbfb8aa3b, v95
	v_exp_f32_e32 v140, v140
	v_exp_f32_e32 v141, v141
	v_exp_f32_e32 v142, v142
	v_exp_f32_e32 v143, v143
	v_exp_f32_e32 v144, v144
	v_exp_f32_e32 v145, v145
	v_exp_f32_e32 v146, v146
	v_exp_f32_e32 v147, v147
	v_add_f32_e32 v140, 1.0, v140
	v_add_f32_e32 v141, 1.0, v141
	v_add_f32_e32 v142, 1.0, v142
	v_add_f32_e32 v143, 1.0, v143
	v_add_f32_e32 v144, 1.0, v144
	v_add_f32_e32 v145, 1.0, v145
	v_add_f32_e32 v146, 1.0, v146
	v_add_f32_e32 v147, 1.0, v147
	v_rcp_f32_e32 v140, v140
	v_rcp_f32_e32 v141, v141
	v_rcp_f32_e32 v142, v142
	v_rcp_f32_e32 v143, v143
	v_rcp_f32_e32 v144, v144
	v_rcp_f32_e32 v145, v145
	v_rcp_f32_e32 v146, v146
	v_rcp_f32_e32 v147, v147
	v_mul_f32_e32 v140, v88, v140
	v_mul_f32_e32 v141, v89, v141
	v_mul_f32_e32 v142, v90, v142
	v_mul_f32_e32 v143, v91, v143
	v_mul_f32_e32 v144, v92, v144
	v_mul_f32_e32 v145, v93, v145
	v_mul_f32_e32 v146, v94, v146
	v_mul_f32_e32 v147, v95, v147
	v_mul_f32_e32 v140, v72, v140
	v_mul_f32_e32 v141, v73, v141
	v_mul_f32_e32 v142, v74, v142
	v_mul_f32_e32 v143, v75, v143
	v_mul_f32_e32 v144, v76, v144
	v_mul_f32_e32 v145, v77, v145
	v_mul_f32_e32 v146, v78, v146
	v_mul_f32_e32 v147, v79, v147
	v_cvt_pk_bf16_f32 v160, v140, v141
	v_cvt_pk_bf16_f32 v161, v142, v143
	v_cvt_pk_bf16_f32 v162, v144, v145
	v_cvt_pk_bf16_f32 v163, v146, v147
	global_store_dwordx4 v133, v[160:163], s[12:13] offset:256 sc1
	v_mul_f32_e32 v140, 0xbfb8aa3b, v48
	v_mul_f32_e32 v141, 0xbfb8aa3b, v49
	v_mul_f32_e32 v142, 0xbfb8aa3b, v50
	v_mul_f32_e32 v143, 0xbfb8aa3b, v51
	v_mul_f32_e32 v144, 0xbfb8aa3b, v52
	v_mul_f32_e32 v145, 0xbfb8aa3b, v53
	v_mul_f32_e32 v146, 0xbfb8aa3b, v54
	v_mul_f32_e32 v147, 0xbfb8aa3b, v55
	v_exp_f32_e32 v140, v140
	v_exp_f32_e32 v141, v141
	v_exp_f32_e32 v142, v142
	v_exp_f32_e32 v143, v143
	v_exp_f32_e32 v144, v144
	v_exp_f32_e32 v145, v145
	v_exp_f32_e32 v146, v146
	v_exp_f32_e32 v147, v147
	v_add_f32_e32 v140, 1.0, v140
	v_add_f32_e32 v141, 1.0, v141
	v_add_f32_e32 v142, 1.0, v142
	v_add_f32_e32 v143, 1.0, v143
	v_add_f32_e32 v144, 1.0, v144
	v_add_f32_e32 v145, 1.0, v145
	v_add_f32_e32 v146, 1.0, v146
	v_add_f32_e32 v147, 1.0, v147
	v_rcp_f32_e32 v140, v140
	v_rcp_f32_e32 v141, v141
	v_rcp_f32_e32 v142, v142
	v_rcp_f32_e32 v143, v143
	v_rcp_f32_e32 v144, v144
	v_rcp_f32_e32 v145, v145
	v_rcp_f32_e32 v146, v146
	v_rcp_f32_e32 v147, v147
	v_mul_f32_e32 v140, v48, v140
	v_mul_f32_e32 v141, v49, v141
	v_mul_f32_e32 v142, v50, v142
	v_mul_f32_e32 v143, v51, v143
	v_mul_f32_e32 v144, v52, v144
	v_mul_f32_e32 v145, v53, v145
	v_mul_f32_e32 v146, v54, v146
	v_mul_f32_e32 v147, v55, v147
	v_mul_f32_e32 v140, v32, v140
	v_mul_f32_e32 v141, v33, v141
	v_mul_f32_e32 v142, v34, v142
	v_mul_f32_e32 v143, v35, v143
	v_mul_f32_e32 v144, v36, v144
	v_mul_f32_e32 v145, v37, v145
	v_mul_f32_e32 v146, v38, v146
	v_mul_f32_e32 v147, v39, v147
	v_cvt_pk_bf16_f32 v148, v140, v141
	v_cvt_pk_bf16_f32 v149, v142, v143
	v_cvt_pk_bf16_f32 v150, v144, v145
	v_cvt_pk_bf16_f32 v151, v146, v147
	global_store_dwordx4 v132, v[148:151], s[12:13] offset:2048 sc1
	v_mul_f32_e32 v140, 0xbfb8aa3b, v56
	v_mul_f32_e32 v141, 0xbfb8aa3b, v57
	v_mul_f32_e32 v142, 0xbfb8aa3b, v58
	v_mul_f32_e32 v143, 0xbfb8aa3b, v59
	v_mul_f32_e32 v144, 0xbfb8aa3b, v60
	v_mul_f32_e32 v145, 0xbfb8aa3b, v61
	v_mul_f32_e32 v146, 0xbfb8aa3b, v62
	v_mul_f32_e32 v147, 0xbfb8aa3b, v63
	v_exp_f32_e32 v140, v140
	v_exp_f32_e32 v141, v141
	v_exp_f32_e32 v142, v142
	v_exp_f32_e32 v143, v143
	v_exp_f32_e32 v144, v144
	v_exp_f32_e32 v145, v145
	v_exp_f32_e32 v146, v146
	v_exp_f32_e32 v147, v147
	v_add_f32_e32 v140, 1.0, v140
	v_add_f32_e32 v141, 1.0, v141
	v_add_f32_e32 v142, 1.0, v142
	v_add_f32_e32 v143, 1.0, v143
	v_add_f32_e32 v144, 1.0, v144
	v_add_f32_e32 v145, 1.0, v145
	v_add_f32_e32 v146, 1.0, v146
	v_add_f32_e32 v147, 1.0, v147
	v_rcp_f32_e32 v140, v140
	v_rcp_f32_e32 v141, v141
	v_rcp_f32_e32 v142, v142
	v_rcp_f32_e32 v143, v143
	v_rcp_f32_e32 v144, v144
	v_rcp_f32_e32 v145, v145
	v_rcp_f32_e32 v146, v146
	v_rcp_f32_e32 v147, v147
	v_mul_f32_e32 v140, v56, v140
	v_mul_f32_e32 v141, v57, v141
	v_mul_f32_e32 v142, v58, v142
	v_mul_f32_e32 v143, v59, v143
	v_mul_f32_e32 v144, v60, v144
	v_mul_f32_e32 v145, v61, v145
	v_mul_f32_e32 v146, v62, v146
	v_mul_f32_e32 v147, v63, v147
	v_mul_f32_e32 v140, v40, v140
	v_mul_f32_e32 v141, v41, v141
	v_mul_f32_e32 v142, v42, v142
	v_mul_f32_e32 v143, v43, v143
	v_mul_f32_e32 v144, v44, v144
	v_mul_f32_e32 v145, v45, v145
	v_mul_f32_e32 v146, v46, v146
	v_mul_f32_e32 v147, v47, v147
	v_cvt_pk_bf16_f32 v152, v140, v141
	v_cvt_pk_bf16_f32 v153, v142, v143
	v_cvt_pk_bf16_f32 v154, v144, v145
	v_cvt_pk_bf16_f32 v155, v146, v147
	global_store_dwordx4 v132, v[152:155], s[12:13] offset:2304 sc1
	v_mul_f32_e32 v140, 0xbfb8aa3b, v16
	v_mul_f32_e32 v141, 0xbfb8aa3b, v17
	v_mul_f32_e32 v142, 0xbfb8aa3b, v18
	v_mul_f32_e32 v143, 0xbfb8aa3b, v19
	v_mul_f32_e32 v144, 0xbfb8aa3b, v20
	v_mul_f32_e32 v145, 0xbfb8aa3b, v21
	v_mul_f32_e32 v146, 0xbfb8aa3b, v22
	v_mul_f32_e32 v147, 0xbfb8aa3b, v23
	v_exp_f32_e32 v140, v140
	v_exp_f32_e32 v141, v141
	v_exp_f32_e32 v142, v142
	v_exp_f32_e32 v143, v143
	v_exp_f32_e32 v144, v144
	v_exp_f32_e32 v145, v145
	v_exp_f32_e32 v146, v146
	v_exp_f32_e32 v147, v147
	v_add_f32_e32 v140, 1.0, v140
	v_add_f32_e32 v141, 1.0, v141
	v_add_f32_e32 v142, 1.0, v142
	v_add_f32_e32 v143, 1.0, v143
	v_add_f32_e32 v144, 1.0, v144
	v_add_f32_e32 v145, 1.0, v145
	v_add_f32_e32 v146, 1.0, v146
	v_add_f32_e32 v147, 1.0, v147
	v_rcp_f32_e32 v140, v140
	v_rcp_f32_e32 v141, v141
	v_rcp_f32_e32 v142, v142
	v_rcp_f32_e32 v143, v143
	v_rcp_f32_e32 v144, v144
	v_rcp_f32_e32 v145, v145
	v_rcp_f32_e32 v146, v146
	v_rcp_f32_e32 v147, v147
	v_mul_f32_e32 v140, v16, v140
	v_mul_f32_e32 v141, v17, v141
	v_mul_f32_e32 v142, v18, v142
	v_mul_f32_e32 v143, v19, v143
	v_mul_f32_e32 v144, v20, v144
	v_mul_f32_e32 v145, v21, v145
	v_mul_f32_e32 v146, v22, v146
	v_mul_f32_e32 v147, v23, v147
	v_mul_f32_e32 v140, v0, v140
	v_mul_f32_e32 v141, v1, v141
	v_mul_f32_e32 v142, v2, v142
	v_mul_f32_e32 v143, v3, v143
	v_mul_f32_e32 v144, v4, v144
	v_mul_f32_e32 v145, v5, v145
	v_mul_f32_e32 v146, v6, v146
	v_mul_f32_e32 v147, v7, v147
	v_cvt_pk_bf16_f32 v156, v140, v141
	v_cvt_pk_bf16_f32 v157, v142, v143
	v_cvt_pk_bf16_f32 v158, v144, v145
	v_cvt_pk_bf16_f32 v159, v146, v147
	global_store_dwordx4 v133, v[156:159], s[12:13] offset:2048 sc1
	v_mul_f32_e32 v140, 0xbfb8aa3b, v24
	v_mul_f32_e32 v141, 0xbfb8aa3b, v25
	v_mul_f32_e32 v142, 0xbfb8aa3b, v26
	v_mul_f32_e32 v143, 0xbfb8aa3b, v27
	v_mul_f32_e32 v144, 0xbfb8aa3b, v28
	v_mul_f32_e32 v145, 0xbfb8aa3b, v29
	v_mul_f32_e32 v146, 0xbfb8aa3b, v30
	v_mul_f32_e32 v147, 0xbfb8aa3b, v31
	v_exp_f32_e32 v140, v140
	v_exp_f32_e32 v141, v141
	v_exp_f32_e32 v142, v142
	v_exp_f32_e32 v143, v143
	v_exp_f32_e32 v144, v144
	v_exp_f32_e32 v145, v145
	v_exp_f32_e32 v146, v146
	v_exp_f32_e32 v147, v147
	v_add_f32_e32 v140, 1.0, v140
	v_add_f32_e32 v141, 1.0, v141
	v_add_f32_e32 v142, 1.0, v142
	v_add_f32_e32 v143, 1.0, v143
	v_add_f32_e32 v144, 1.0, v144
	v_add_f32_e32 v145, 1.0, v145
	v_add_f32_e32 v146, 1.0, v146
	v_add_f32_e32 v147, 1.0, v147
	v_rcp_f32_e32 v140, v140
	v_rcp_f32_e32 v141, v141
	v_rcp_f32_e32 v142, v142
	v_rcp_f32_e32 v143, v143
	v_rcp_f32_e32 v144, v144
	v_rcp_f32_e32 v145, v145
	v_rcp_f32_e32 v146, v146
	v_rcp_f32_e32 v147, v147
	v_mul_f32_e32 v140, v24, v140
	v_mul_f32_e32 v141, v25, v141
	v_mul_f32_e32 v142, v26, v142
	v_mul_f32_e32 v143, v27, v143
	v_mul_f32_e32 v144, v28, v144
	v_mul_f32_e32 v145, v29, v145
	v_mul_f32_e32 v146, v30, v146
	v_mul_f32_e32 v147, v31, v147
	v_mul_f32_e32 v140, v8, v140
	v_mul_f32_e32 v141, v9, v141
	v_mul_f32_e32 v142, v10, v142
	v_mul_f32_e32 v143, v11, v143
	v_mul_f32_e32 v144, v12, v144
	v_mul_f32_e32 v145, v13, v145
	v_mul_f32_e32 v146, v14, v146
	v_mul_f32_e32 v147, v15, v147
	v_cvt_pk_bf16_f32 v160, v140, v141
	v_cvt_pk_bf16_f32 v161, v142, v143
	v_cvt_pk_bf16_f32 v162, v144, v145
	v_cvt_pk_bf16_f32 v163, v146, v147
	global_store_dwordx4 v133, v[160:163], s[12:13] offset:2304 sc1
	v_readlane_b32 s0, v254, 11
	s_add_i32 s2, s2, s0
	s_cmp_lt_i32 s2, s3
	s_barrier
	s_cbranch_scc1 .LBB0_1031

.Lg16_down_k:
	s_add_i32 s9, s8, 2
	s_lshl_b32 s96, s9, 13
	s_add_i32 m0, vcc_lo, 16384
	v_lshl_add_u64 v[160:161], v[188:189], 0, s[96:97]
	global_load_lds_dwordx4 v[160:161], off
	global_load_lds_dwordx4 v[160:161], off offset:1024
	ds_read_b128 v[196:199], v246 offset:0
	ds_read_b128 v[200:203], v162 offset:0
	ds_read_b128 v[204:207], v246 offset:2048
	ds_read_b128 v[242:245], v162 offset:2048
	s_add_i32 s9, s8, 2
	s_lshl_b32 s96, s9, 11
	v_lshl_add_u64 v[248:249], v[184:185], 0, s[96:97]
	v_lshl_add_u64 v[250:251], v[186:187], 0, s[96:97]
	s_waitcnt vmcnt(8) lgkmcnt(3)
	v_mfma_f32_16x16x32_bf16 v[112:115], v[196:199], v[128:131], v[112:115]
	v_mfma_f32_16x16x32_bf16 v[120:123], v[196:199], v[132:135], v[120:123]
	v_mfma_f32_16x16x32_bf16 v[48:51], v[196:199], v[136:139], v[48:51]
	v_mfma_f32_16x16x32_bf16 v[56:59], v[196:199], v[140:143], v[56:59]
	ds_read_b128 v[196:199], v246 offset:4096
	s_waitcnt lgkmcnt(3)
	v_mfma_f32_16x16x32_bf16 v[116:119], v[200:203], v[128:131], v[116:119]
	v_mfma_f32_16x16x32_bf16 v[124:127], v[200:203], v[132:135], v[124:127]
	v_mfma_f32_16x16x32_bf16 v[52:55], v[200:203], v[136:139], v[52:55]
	v_mfma_f32_16x16x32_bf16 v[60:63], v[200:203], v[140:143], v[60:63]
	ds_read_b128 v[200:203], v162 offset:4096
	s_waitcnt lgkmcnt(3)
	v_mfma_f32_16x16x32_bf16 v[96:99], v[204:207], v[128:131], v[96:99]
	v_mfma_f32_16x16x32_bf16 v[104:107], v[204:207], v[132:135], v[104:107]
	v_mfma_f32_16x16x32_bf16 v[32:35], v[204:207], v[136:139], v[32:35]
	v_mfma_f32_16x16x32_bf16 v[40:43], v[204:207], v[140:143], v[40:43]
	ds_read_b128 v[204:207], v246 offset:6144
	s_waitcnt lgkmcnt(3)
	v_mfma_f32_16x16x32_bf16 v[100:103], v[242:245], v[128:131], v[100:103]
	v_mfma_f32_16x16x32_bf16 v[108:111], v[242:245], v[132:135], v[108:111]
	v_mfma_f32_16x16x32_bf16 v[36:39], v[242:245], v[136:139], v[36:39]
	v_mfma_f32_16x16x32_bf16 v[44:47], v[242:245], v[140:143], v[44:47]
	ds_read_b128 v[242:245], v162 offset:6144
	s_waitcnt lgkmcnt(3)
	v_mfma_f32_16x16x32_bf16 v[80:83], v[196:199], v[128:131], v[80:83]
	v_mfma_f32_16x16x32_bf16 v[88:91], v[196:199], v[132:135], v[88:91]
	v_mfma_f32_16x16x32_bf16 v[16:19], v[196:199], v[136:139], v[16:19]
	v_mfma_f32_16x16x32_bf16 v[24:27], v[196:199], v[140:143], v[24:27]
	s_waitcnt lgkmcnt(2)
	v_mfma_f32_16x16x32_bf16 v[84:87], v[200:203], v[128:131], v[84:87]
	v_mfma_f32_16x16x32_bf16 v[92:95], v[200:203], v[132:135], v[92:95]
	v_mfma_f32_16x16x32_bf16 v[20:23], v[200:203], v[136:139], v[20:23]
	v_mfma_f32_16x16x32_bf16 v[28:31], v[200:203], v[140:143], v[28:31]
	s_waitcnt lgkmcnt(1)
	v_mfma_f32_16x16x32_bf16 v[64:67], v[204:207], v[128:131], v[64:67]
	v_mfma_f32_16x16x32_bf16 v[72:75], v[204:207], v[132:135], v[72:75]
	v_mfma_f32_16x16x32_bf16 v[0:3], v[204:207], v[136:139], v[0:3]
	v_mfma_f32_16x16x32_bf16 v[8:11], v[204:207], v[140:143], v[8:11]
	s_waitcnt lgkmcnt(0)
	v_mfma_f32_16x16x32_bf16 v[68:71], v[242:245], v[128:131], v[68:71]
	v_mfma_f32_16x16x32_bf16 v[76:79], v[242:245], v[132:135], v[76:79]
	v_mfma_f32_16x16x32_bf16 v[4:7], v[242:245], v[136:139], v[4:7]
	v_mfma_f32_16x16x32_bf16 v[12:15], v[242:245], v[140:143], v[12:15]
	global_load_dwordx4 v[128:131], v[248:249], off
	global_load_dwordx4 v[132:135], v[248:249], off offset:256
	global_load_dwordx4 v[136:139], v[250:251], off
	global_load_dwordx4 v[140:143], v[250:251], off offset:256
	s_waitcnt vmcnt(10)
	s_barrier
	s_add_i32 s9, s8, 3
	s_lshl_b32 s96, s9, 13
	s_mov_b32 m0, vcc_lo
	v_lshl_add_u64 v[160:161], v[188:189], 0, s[96:97]
	global_load_lds_dwordx4 v[160:161], off
	global_load_lds_dwordx4 v[160:161], off offset:1024
	ds_read_b128 v[196:199], v246 offset:8192
	ds_read_b128 v[200:203], v162 offset:8192
	ds_read_b128 v[204:207], v246 offset:10240
	ds_read_b128 v[242:245], v162 offset:10240
	s_add_i32 s9, s8, 3
	s_lshl_b32 s96, s9, 11
	v_lshl_add_u64 v[248:249], v[184:185], 0, s[96:97]
	v_lshl_add_u64 v[250:251], v[186:187], 0, s[96:97]
	s_waitcnt vmcnt(8) lgkmcnt(3)
	v_mfma_f32_16x16x32_bf16 v[112:115], v[196:199], v[144:147], v[112:115]
	v_mfma_f32_16x16x32_bf16 v[120:123], v[196:199], v[148:151], v[120:123]
	v_mfma_f32_16x16x32_bf16 v[48:51], v[196:199], v[152:155], v[48:51]
	v_mfma_f32_16x16x32_bf16 v[56:59], v[196:199], v[156:159], v[56:59]
	ds_read_b128 v[196:199], v246 offset:12288
	s_waitcnt lgkmcnt(3)
	v_mfma_f32_16x16x32_bf16 v[116:119], v[200:203], v[144:147], v[116:119]
	v_mfma_f32_16x16x32_bf16 v[124:127], v[200:203], v[148:151], v[124:127]
	v_mfma_f32_16x16x32_bf16 v[52:55], v[200:203], v[152:155], v[52:55]
	v_mfma_f32_16x16x32_bf16 v[60:63], v[200:203], v[156:159], v[60:63]
	ds_read_b128 v[200:203], v162 offset:12288
	s_waitcnt lgkmcnt(3)
	v_mfma_f32_16x16x32_bf16 v[96:99], v[204:207], v[144:147], v[96:99]
	v_mfma_f32_16x16x32_bf16 v[104:107], v[204:207], v[148:151], v[104:107]
	v_mfma_f32_16x16x32_bf16 v[32:35], v[204:207], v[152:155], v[32:35]
	v_mfma_f32_16x16x32_bf16 v[40:43], v[204:207], v[156:159], v[40:43]
	ds_read_b128 v[204:207], v246 offset:14336
	s_waitcnt lgkmcnt(3)
	v_mfma_f32_16x16x32_bf16 v[100:103], v[242:245], v[144:147], v[100:103]
	v_mfma_f32_16x16x32_bf16 v[108:111], v[242:245], v[148:151], v[108:111]
	v_mfma_f32_16x16x32_bf16 v[36:39], v[242:245], v[152:155], v[36:39]
	v_mfma_f32_16x16x32_bf16 v[44:47], v[242:245], v[156:159], v[44:47]
	ds_read_b128 v[242:245], v162 offset:14336
	s_waitcnt lgkmcnt(3)
	v_mfma_f32_16x16x32_bf16 v[80:83], v[196:199], v[144:147], v[80:83]
	v_mfma_f32_16x16x32_bf16 v[88:91], v[196:199], v[148:151], v[88:91]
	v_mfma_f32_16x16x32_bf16 v[16:19], v[196:199], v[152:155], v[16:19]
	v_mfma_f32_16x16x32_bf16 v[24:27], v[196:199], v[156:159], v[24:27]
	s_waitcnt lgkmcnt(2)
	v_mfma_f32_16x16x32_bf16 v[84:87], v[200:203], v[144:147], v[84:87]
	v_mfma_f32_16x16x32_bf16 v[92:95], v[200:203], v[148:151], v[92:95]
	v_mfma_f32_16x16x32_bf16 v[20:23], v[200:203], v[152:155], v[20:23]
	v_mfma_f32_16x16x32_bf16 v[28:31], v[200:203], v[156:159], v[28:31]
	s_waitcnt lgkmcnt(1)
	v_mfma_f32_16x16x32_bf16 v[64:67], v[204:207], v[144:147], v[64:67]
	v_mfma_f32_16x16x32_bf16 v[72:75], v[204:207], v[148:151], v[72:75]
	v_mfma_f32_16x16x32_bf16 v[0:3], v[204:207], v[152:155], v[0:3]
	v_mfma_f32_16x16x32_bf16 v[8:11], v[204:207], v[156:159], v[8:11]
	s_waitcnt lgkmcnt(0)
	v_mfma_f32_16x16x32_bf16 v[68:71], v[242:245], v[144:147], v[68:71]
	v_mfma_f32_16x16x32_bf16 v[76:79], v[242:245], v[148:151], v[76:79]
	v_mfma_f32_16x16x32_bf16 v[4:7], v[242:245], v[152:155], v[4:7]
	v_mfma_f32_16x16x32_bf16 v[12:15], v[242:245], v[156:159], v[12:15]
	global_load_dwordx4 v[144:147], v[248:249], off
	global_load_dwordx4 v[148:151], v[248:249], off offset:256
	global_load_dwordx4 v[152:155], v[250:251], off
	global_load_dwordx4 v[156:159], v[250:251], off offset:256
	s_waitcnt vmcnt(10)
	s_barrier
	s_add_i32 s9, s8, 4
	s_lshl_b32 s96, s9, 13
	s_add_i32 m0, vcc_lo, 8192
	v_lshl_add_u64 v[160:161], v[188:189], 0, s[96:97]
	global_load_lds_dwordx4 v[160:161], off
	global_load_lds_dwordx4 v[160:161], off offset:1024
	ds_read_b128 v[196:199], v246 offset:16384
	ds_read_b128 v[200:203], v162 offset:16384
	ds_read_b128 v[204:207], v246 offset:18432
	ds_read_b128 v[242:245], v162 offset:18432
	s_add_i32 s9, s8, 4
	s_lshl_b32 s96, s9, 11
	v_lshl_add_u64 v[248:249], v[184:185], 0, s[96:97]
	v_lshl_add_u64 v[250:251], v[186:187], 0, s[96:97]
	s_waitcnt vmcnt(8) lgkmcnt(3)
	v_mfma_f32_16x16x32_bf16 v[112:115], v[196:199], v[128:131], v[112:115]
	v_mfma_f32_16x16x32_bf16 v[120:123], v[196:199], v[132:135], v[120:123]
	v_mfma_f32_16x16x32_bf16 v[48:51], v[196:199], v[136:139], v[48:51]
	v_mfma_f32_16x16x32_bf16 v[56:59], v[196:199], v[140:143], v[56:59]
	ds_read_b128 v[196:199], v246 offset:20480
	s_waitcnt lgkmcnt(3)
	v_mfma_f32_16x16x32_bf16 v[116:119], v[200:203], v[128:131], v[116:119]
	v_mfma_f32_16x16x32_bf16 v[124:127], v[200:203], v[132:135], v[124:127]
	v_mfma_f32_16x16x32_bf16 v[52:55], v[200:203], v[136:139], v[52:55]
	v_mfma_f32_16x16x32_bf16 v[60:63], v[200:203], v[140:143], v[60:63]
	ds_read_b128 v[200:203], v162 offset:20480
	s_waitcnt lgkmcnt(3)
	v_mfma_f32_16x16x32_bf16 v[96:99], v[204:207], v[128:131], v[96:99]
	v_mfma_f32_16x16x32_bf16 v[104:107], v[204:207], v[132:135], v[104:107]
	v_mfma_f32_16x16x32_bf16 v[32:35], v[204:207], v[136:139], v[32:35]
	v_mfma_f32_16x16x32_bf16 v[40:43], v[204:207], v[140:143], v[40:43]
	ds_read_b128 v[204:207], v246 offset:22528
	s_waitcnt lgkmcnt(3)
	v_mfma_f32_16x16x32_bf16 v[100:103], v[242:245], v[128:131], v[100:103]
	v_mfma_f32_16x16x32_bf16 v[108:111], v[242:245], v[132:135], v[108:111]
	v_mfma_f32_16x16x32_bf16 v[36:39], v[242:245], v[136:139], v[36:39]
	v_mfma_f32_16x16x32_bf16 v[44:47], v[242:245], v[140:143], v[44:47]
	ds_read_b128 v[242:245], v162 offset:22528
	s_waitcnt lgkmcnt(3)
	v_mfma_f32_16x16x32_bf16 v[80:83], v[196:199], v[128:131], v[80:83]
	v_mfma_f32_16x16x32_bf16 v[88:91], v[196:199], v[132:135], v[88:91]
	v_mfma_f32_16x16x32_bf16 v[16:19], v[196:199], v[136:139], v[16:19]
	v_mfma_f32_16x16x32_bf16 v[24:27], v[196:199], v[140:143], v[24:27]
	s_waitcnt lgkmcnt(2)
	v_mfma_f32_16x16x32_bf16 v[84:87], v[200:203], v[128:131], v[84:87]
	v_mfma_f32_16x16x32_bf16 v[92:95], v[200:203], v[132:135], v[92:95]
	v_mfma_f32_16x16x32_bf16 v[20:23], v[200:203], v[136:139], v[20:23]
	v_mfma_f32_16x16x32_bf16 v[28:31], v[200:203], v[140:143], v[28:31]
	s_waitcnt lgkmcnt(1)
	v_mfma_f32_16x16x32_bf16 v[64:67], v[204:207], v[128:131], v[64:67]
	v_mfma_f32_16x16x32_bf16 v[72:75], v[204:207], v[132:135], v[72:75]
	v_mfma_f32_16x16x32_bf16 v[0:3], v[204:207], v[136:139], v[0:3]
	v_mfma_f32_16x16x32_bf16 v[8:11], v[204:207], v[140:143], v[8:11]
	s_waitcnt lgkmcnt(0)
	v_mfma_f32_16x16x32_bf16 v[68:71], v[242:245], v[128:131], v[68:71]
	v_mfma_f32_16x16x32_bf16 v[76:79], v[242:245], v[132:135], v[76:79]
	v_mfma_f32_16x16x32_bf16 v[4:7], v[242:245], v[136:139], v[4:7]
	v_mfma_f32_16x16x32_bf16 v[12:15], v[242:245], v[140:143], v[12:15]
	global_load_dwordx4 v[128:131], v[248:249], off
	global_load_dwordx4 v[132:135], v[248:249], off offset:256
	global_load_dwordx4 v[136:139], v[250:251], off
	global_load_dwordx4 v[140:143], v[250:251], off offset:256
	s_waitcnt vmcnt(10)
	s_barrier
	s_add_i32 s9, s8, 5
	s_lshl_b32 s96, s9, 13
	s_add_i32 m0, vcc_lo, 16384
	v_lshl_add_u64 v[160:161], v[188:189], 0, s[96:97]
	global_load_lds_dwordx4 v[160:161], off
	global_load_lds_dwordx4 v[160:161], off offset:1024
	ds_read_b128 v[196:199], v246 offset:0
	ds_read_b128 v[200:203], v162 offset:0
	ds_read_b128 v[204:207], v246 offset:2048
	ds_read_b128 v[242:245], v162 offset:2048
	s_add_i32 s9, s8, 5
	s_lshl_b32 s96, s9, 11
	v_lshl_add_u64 v[248:249], v[184:185], 0, s[96:97]
	v_lshl_add_u64 v[250:251], v[186:187], 0, s[96:97]
	s_waitcnt vmcnt(8) lgkmcnt(3)
	v_mfma_f32_16x16x32_bf16 v[112:115], v[196:199], v[144:147], v[112:115]
	v_mfma_f32_16x16x32_bf16 v[120:123], v[196:199], v[148:151], v[120:123]
	v_mfma_f32_16x16x32_bf16 v[48:51], v[196:199], v[152:155], v[48:51]
	v_mfma_f32_16x16x32_bf16 v[56:59], v[196:199], v[156:159], v[56:59]
	ds_read_b128 v[196:199], v246 offset:4096
	s_waitcnt lgkmcnt(3)
	v_mfma_f32_16x16x32_bf16 v[116:119], v[200:203], v[144:147], v[116:119]
	v_mfma_f32_16x16x32_bf16 v[124:127], v[200:203], v[148:151], v[124:127]
	v_mfma_f32_16x16x32_bf16 v[52:55], v[200:203], v[152:155], v[52:55]
	v_mfma_f32_16x16x32_bf16 v[60:63], v[200:203], v[156:159], v[60:63]
	ds_read_b128 v[200:203], v162 offset:4096
	s_waitcnt lgkmcnt(3)
	v_mfma_f32_16x16x32_bf16 v[96:99], v[204:207], v[144:147], v[96:99]
	v_mfma_f32_16x16x32_bf16 v[104:107], v[204:207], v[148:151], v[104:107]
	v_mfma_f32_16x16x32_bf16 v[32:35], v[204:207], v[152:155], v[32:35]
	v_mfma_f32_16x16x32_bf16 v[40:43], v[204:207], v[156:159], v[40:43]
	ds_read_b128 v[204:207], v246 offset:6144
	s_waitcnt lgkmcnt(3)
	v_mfma_f32_16x16x32_bf16 v[100:103], v[242:245], v[144:147], v[100:103]
	v_mfma_f32_16x16x32_bf16 v[108:111], v[242:245], v[148:151], v[108:111]
	v_mfma_f32_16x16x32_bf16 v[36:39], v[242:245], v[152:155], v[36:39]
	v_mfma_f32_16x16x32_bf16 v[44:47], v[242:245], v[156:159], v[44:47]
	ds_read_b128 v[242:245], v162 offset:6144
	s_waitcnt lgkmcnt(3)
	v_mfma_f32_16x16x32_bf16 v[80:83], v[196:199], v[144:147], v[80:83]
	v_mfma_f32_16x16x32_bf16 v[88:91], v[196:199], v[148:151], v[88:91]
	v_mfma_f32_16x16x32_bf16 v[16:19], v[196:199], v[152:155], v[16:19]
	v_mfma_f32_16x16x32_bf16 v[24:27], v[196:199], v[156:159], v[24:27]
	s_waitcnt lgkmcnt(2)
	v_mfma_f32_16x16x32_bf16 v[84:87], v[200:203], v[144:147], v[84:87]
	v_mfma_f32_16x16x32_bf16 v[92:95], v[200:203], v[148:151], v[92:95]
	v_mfma_f32_16x16x32_bf16 v[20:23], v[200:203], v[152:155], v[20:23]
	v_mfma_f32_16x16x32_bf16 v[28:31], v[200:203], v[156:159], v[28:31]
	s_waitcnt lgkmcnt(1)
	v_mfma_f32_16x16x32_bf16 v[64:67], v[204:207], v[144:147], v[64:67]
	v_mfma_f32_16x16x32_bf16 v[72:75], v[204:207], v[148:151], v[72:75]
	v_mfma_f32_16x16x32_bf16 v[0:3], v[204:207], v[152:155], v[0:3]
	v_mfma_f32_16x16x32_bf16 v[8:11], v[204:207], v[156:159], v[8:11]
	s_waitcnt lgkmcnt(0)
	v_mfma_f32_16x16x32_bf16 v[68:71], v[242:245], v[144:147], v[68:71]
	v_mfma_f32_16x16x32_bf16 v[76:79], v[242:245], v[148:151], v[76:79]
	v_mfma_f32_16x16x32_bf16 v[4:7], v[242:245], v[152:155], v[4:7]
	v_mfma_f32_16x16x32_bf16 v[12:15], v[242:245], v[156:159], v[12:15]
	global_load_dwordx4 v[144:147], v[248:249], off
	global_load_dwordx4 v[148:151], v[248:249], off offset:256
	global_load_dwordx4 v[152:155], v[250:251], off
	global_load_dwordx4 v[156:159], v[250:251], off offset:256
	s_waitcnt vmcnt(10)
	s_barrier
	s_add_i32 s9, s8, 6
	s_lshl_b32 s96, s9, 13
	s_mov_b32 m0, vcc_lo
	v_lshl_add_u64 v[160:161], v[188:189], 0, s[96:97]
	global_load_lds_dwordx4 v[160:161], off
	global_load_lds_dwordx4 v[160:161], off offset:1024
	ds_read_b128 v[196:199], v246 offset:8192
	ds_read_b128 v[200:203], v162 offset:8192
	ds_read_b128 v[204:207], v246 offset:10240
	ds_read_b128 v[242:245], v162 offset:10240
	s_add_i32 s9, s8, 6
	s_lshl_b32 s96, s9, 11
	v_lshl_add_u64 v[248:249], v[184:185], 0, s[96:97]
	v_lshl_add_u64 v[250:251], v[186:187], 0, s[96:97]
	s_waitcnt vmcnt(8) lgkmcnt(3)
	v_mfma_f32_16x16x32_bf16 v[112:115], v[196:199], v[128:131], v[112:115]
	v_mfma_f32_16x16x32_bf16 v[120:123], v[196:199], v[132:135], v[120:123]
	v_mfma_f32_16x16x32_bf16 v[48:51], v[196:199], v[136:139], v[48:51]
	v_mfma_f32_16x16x32_bf16 v[56:59], v[196:199], v[140:143], v[56:59]
	ds_read_b128 v[196:199], v246 offset:12288
	s_waitcnt lgkmcnt(3)
	v_mfma_f32_16x16x32_bf16 v[116:119], v[200:203], v[128:131], v[116:119]
	v_mfma_f32_16x16x32_bf16 v[124:127], v[200:203], v[132:135], v[124:127]
	v_mfma_f32_16x16x32_bf16 v[52:55], v[200:203], v[136:139], v[52:55]
	v_mfma_f32_16x16x32_bf16 v[60:63], v[200:203], v[140:143], v[60:63]
	ds_read_b128 v[200:203], v162 offset:12288
	s_waitcnt lgkmcnt(3)
	v_mfma_f32_16x16x32_bf16 v[96:99], v[204:207], v[128:131], v[96:99]
	v_mfma_f32_16x16x32_bf16 v[104:107], v[204:207], v[132:135], v[104:107]
	v_mfma_f32_16x16x32_bf16 v[32:35], v[204:207], v[136:139], v[32:35]
	v_mfma_f32_16x16x32_bf16 v[40:43], v[204:207], v[140:143], v[40:43]
	ds_read_b128 v[204:207], v246 offset:14336
	s_waitcnt lgkmcnt(3)
	v_mfma_f32_16x16x32_bf16 v[100:103], v[242:245], v[128:131], v[100:103]
	v_mfma_f32_16x16x32_bf16 v[108:111], v[242:245], v[132:135], v[108:111]
	v_mfma_f32_16x16x32_bf16 v[36:39], v[242:245], v[136:139], v[36:39]
	v_mfma_f32_16x16x32_bf16 v[44:47], v[242:245], v[140:143], v[44:47]
	ds_read_b128 v[242:245], v162 offset:14336
	s_waitcnt lgkmcnt(3)
	v_mfma_f32_16x16x32_bf16 v[80:83], v[196:199], v[128:131], v[80:83]
	v_mfma_f32_16x16x32_bf16 v[88:91], v[196:199], v[132:135], v[88:91]
	v_mfma_f32_16x16x32_bf16 v[16:19], v[196:199], v[136:139], v[16:19]
	v_mfma_f32_16x16x32_bf16 v[24:27], v[196:199], v[140:143], v[24:27]
	s_waitcnt lgkmcnt(2)
	v_mfma_f32_16x16x32_bf16 v[84:87], v[200:203], v[128:131], v[84:87]
	v_mfma_f32_16x16x32_bf16 v[92:95], v[200:203], v[132:135], v[92:95]
	v_mfma_f32_16x16x32_bf16 v[20:23], v[200:203], v[136:139], v[20:23]
	v_mfma_f32_16x16x32_bf16 v[28:31], v[200:203], v[140:143], v[28:31]
	s_waitcnt lgkmcnt(1)
	v_mfma_f32_16x16x32_bf16 v[64:67], v[204:207], v[128:131], v[64:67]
	v_mfma_f32_16x16x32_bf16 v[72:75], v[204:207], v[132:135], v[72:75]
	v_mfma_f32_16x16x32_bf16 v[0:3], v[204:207], v[136:139], v[0:3]
	v_mfma_f32_16x16x32_bf16 v[8:11], v[204:207], v[140:143], v[8:11]
	s_waitcnt lgkmcnt(0)
	v_mfma_f32_16x16x32_bf16 v[68:71], v[242:245], v[128:131], v[68:71]
	v_mfma_f32_16x16x32_bf16 v[76:79], v[242:245], v[132:135], v[76:79]
	v_mfma_f32_16x16x32_bf16 v[4:7], v[242:245], v[136:139], v[4:7]
	v_mfma_f32_16x16x32_bf16 v[12:15], v[242:245], v[140:143], v[12:15]
	global_load_dwordx4 v[128:131], v[248:249], off
	global_load_dwordx4 v[132:135], v[248:249], off offset:256
	global_load_dwordx4 v[136:139], v[250:251], off
	global_load_dwordx4 v[140:143], v[250:251], off offset:256
	s_waitcnt vmcnt(10)
	s_barrier
	s_add_i32 s9, s8, 7
	s_lshl_b32 s96, s9, 13
	s_add_i32 m0, vcc_lo, 8192
	v_lshl_add_u64 v[160:161], v[188:189], 0, s[96:97]
	global_load_lds_dwordx4 v[160:161], off
	global_load_lds_dwordx4 v[160:161], off offset:1024
	ds_read_b128 v[196:199], v246 offset:16384
	ds_read_b128 v[200:203], v162 offset:16384
	ds_read_b128 v[204:207], v246 offset:18432
	ds_read_b128 v[242:245], v162 offset:18432
	s_add_i32 s9, s8, 7
	s_lshl_b32 s96, s9, 11
	v_lshl_add_u64 v[248:249], v[184:185], 0, s[96:97]
	v_lshl_add_u64 v[250:251], v[186:187], 0, s[96:97]
	s_waitcnt vmcnt(8) lgkmcnt(3)
	v_mfma_f32_16x16x32_bf16 v[112:115], v[196:199], v[144:147], v[112:115]
	v_mfma_f32_16x16x32_bf16 v[120:123], v[196:199], v[148:151], v[120:123]
	v_mfma_f32_16x16x32_bf16 v[48:51], v[196:199], v[152:155], v[48:51]
	v_mfma_f32_16x16x32_bf16 v[56:59], v[196:199], v[156:159], v[56:59]
	ds_read_b128 v[196:199], v246 offset:20480
	s_waitcnt lgkmcnt(3)
	v_mfma_f32_16x16x32_bf16 v[116:119], v[200:203], v[144:147], v[116:119]
	v_mfma_f32_16x16x32_bf16 v[124:127], v[200:203], v[148:151], v[124:127]
	v_mfma_f32_16x16x32_bf16 v[52:55], v[200:203], v[152:155], v[52:55]
	v_mfma_f32_16x16x32_bf16 v[60:63], v[200:203], v[156:159], v[60:63]
	ds_read_b128 v[200:203], v162 offset:20480
	s_waitcnt lgkmcnt(3)
	v_mfma_f32_16x16x32_bf16 v[96:99], v[204:207], v[144:147], v[96:99]
	v_mfma_f32_16x16x32_bf16 v[104:107], v[204:207], v[148:151], v[104:107]
	v_mfma_f32_16x16x32_bf16 v[32:35], v[204:207], v[152:155], v[32:35]
	v_mfma_f32_16x16x32_bf16 v[40:43], v[204:207], v[156:159], v[40:43]
	ds_read_b128 v[204:207], v246 offset:22528
	s_waitcnt lgkmcnt(3)
	v_mfma_f32_16x16x32_bf16 v[100:103], v[242:245], v[144:147], v[100:103]
	v_mfma_f32_16x16x32_bf16 v[108:111], v[242:245], v[148:151], v[108:111]
	v_mfma_f32_16x16x32_bf16 v[36:39], v[242:245], v[152:155], v[36:39]
	v_mfma_f32_16x16x32_bf16 v[44:47], v[242:245], v[156:159], v[44:47]
	ds_read_b128 v[242:245], v162 offset:22528
	s_waitcnt lgkmcnt(3)
	v_mfma_f32_16x16x32_bf16 v[80:83], v[196:199], v[144:147], v[80:83]
	v_mfma_f32_16x16x32_bf16 v[88:91], v[196:199], v[148:151], v[88:91]
	v_mfma_f32_16x16x32_bf16 v[16:19], v[196:199], v[152:155], v[16:19]
	v_mfma_f32_16x16x32_bf16 v[24:27], v[196:199], v[156:159], v[24:27]
	s_waitcnt lgkmcnt(2)
	v_mfma_f32_16x16x32_bf16 v[84:87], v[200:203], v[144:147], v[84:87]
	v_mfma_f32_16x16x32_bf16 v[92:95], v[200:203], v[148:151], v[92:95]
	v_mfma_f32_16x16x32_bf16 v[20:23], v[200:203], v[152:155], v[20:23]
	v_mfma_f32_16x16x32_bf16 v[28:31], v[200:203], v[156:159], v[28:31]
	s_waitcnt lgkmcnt(1)
	v_mfma_f32_16x16x32_bf16 v[64:67], v[204:207], v[144:147], v[64:67]
	v_mfma_f32_16x16x32_bf16 v[72:75], v[204:207], v[148:151], v[72:75]
	v_mfma_f32_16x16x32_bf16 v[0:3], v[204:207], v[152:155], v[0:3]
	v_mfma_f32_16x16x32_bf16 v[8:11], v[204:207], v[156:159], v[8:11]
	s_waitcnt lgkmcnt(0)
	v_mfma_f32_16x16x32_bf16 v[68:71], v[242:245], v[144:147], v[68:71]
	v_mfma_f32_16x16x32_bf16 v[76:79], v[242:245], v[148:151], v[76:79]
	v_mfma_f32_16x16x32_bf16 v[4:7], v[242:245], v[152:155], v[4:7]
	v_mfma_f32_16x16x32_bf16 v[12:15], v[242:245], v[156:159], v[12:15]
	global_load_dwordx4 v[144:147], v[248:249], off
	global_load_dwordx4 v[148:151], v[248:249], off offset:256
	global_load_dwordx4 v[152:155], v[250:251], off
	global_load_dwordx4 v[156:159], v[250:251], off offset:256
	s_waitcnt vmcnt(10)
	s_barrier
	s_add_i32 s8, s8, 6
	s_cmp_lt_u32 s8, 84
	s_cbranch_scc1 .Lg16_down_k
	s_mov_b32 s96, 0xac000
	s_add_i32 m0, vcc_lo, 16384
	v_lshl_add_u64 v[160:161], v[188:189], 0, s[96:97]
	global_load_lds_dwordx4 v[160:161], off
	global_load_lds_dwordx4 v[160:161], off offset:1024
	ds_read_b128 v[196:199], v246 offset:0
	ds_read_b128 v[200:203], v162 offset:0
	ds_read_b128 v[204:207], v246 offset:2048
	ds_read_b128 v[242:245], v162 offset:2048
	s_mov_b32 s96, 0x2b000
	v_lshl_add_u64 v[248:249], v[184:185], 0, s[96:97]
	v_lshl_add_u64 v[250:251], v[186:187], 0, s[96:97]
	s_waitcnt vmcnt(8) lgkmcnt(3)
	v_mfma_f32_16x16x32_bf16 v[112:115], v[196:199], v[128:131], v[112:115]
	v_mfma_f32_16x16x32_bf16 v[120:123], v[196:199], v[132:135], v[120:123]
	v_mfma_f32_16x16x32_bf16 v[48:51], v[196:199], v[136:139], v[48:51]
	v_mfma_f32_16x16x32_bf16 v[56:59], v[196:199], v[140:143], v[56:59]
	ds_read_b128 v[196:199], v246 offset:4096
	s_waitcnt lgkmcnt(3)
	v_mfma_f32_16x16x32_bf16 v[116:119], v[200:203], v[128:131], v[116:119]
	v_mfma_f32_16x16x32_bf16 v[124:127], v[200:203], v[132:135], v[124:127]
	v_mfma_f32_16x16x32_bf16 v[52:55], v[200:203], v[136:139], v[52:55]
	v_mfma_f32_16x16x32_bf16 v[60:63], v[200:203], v[140:143], v[60:63]
	ds_read_b128 v[200:203], v162 offset:4096
	s_waitcnt lgkmcnt(3)
	v_mfma_f32_16x16x32_bf16 v[96:99], v[204:207], v[128:131], v[96:99]
	v_mfma_f32_16x16x32_bf16 v[104:107], v[204:207], v[132:135], v[104:107]
	v_mfma_f32_16x16x32_bf16 v[32:35], v[204:207], v[136:139], v[32:35]
	v_mfma_f32_16x16x32_bf16 v[40:43], v[204:207], v[140:143], v[40:43]
	ds_read_b128 v[204:207], v246 offset:6144
	s_waitcnt lgkmcnt(3)
	v_mfma_f32_16x16x32_bf16 v[100:103], v[242:245], v[128:131], v[100:103]
	v_mfma_f32_16x16x32_bf16 v[108:111], v[242:245], v[132:135], v[108:111]
	v_mfma_f32_16x16x32_bf16 v[36:39], v[242:245], v[136:139], v[36:39]
	v_mfma_f32_16x16x32_bf16 v[44:47], v[242:245], v[140:143], v[44:47]
	ds_read_b128 v[242:245], v162 offset:6144
	s_waitcnt lgkmcnt(3)
	v_mfma_f32_16x16x32_bf16 v[80:83], v[196:199], v[128:131], v[80:83]
	v_mfma_f32_16x16x32_bf16 v[88:91], v[196:199], v[132:135], v[88:91]
	v_mfma_f32_16x16x32_bf16 v[16:19], v[196:199], v[136:139], v[16:19]
	v_mfma_f32_16x16x32_bf16 v[24:27], v[196:199], v[140:143], v[24:27]
	s_waitcnt lgkmcnt(2)
	v_mfma_f32_16x16x32_bf16 v[84:87], v[200:203], v[128:131], v[84:87]
	v_mfma_f32_16x16x32_bf16 v[92:95], v[200:203], v[132:135], v[92:95]
	v_mfma_f32_16x16x32_bf16 v[20:23], v[200:203], v[136:139], v[20:23]
	v_mfma_f32_16x16x32_bf16 v[28:31], v[200:203], v[140:143], v[28:31]
	s_waitcnt lgkmcnt(1)
	v_mfma_f32_16x16x32_bf16 v[64:67], v[204:207], v[128:131], v[64:67]
	v_mfma_f32_16x16x32_bf16 v[72:75], v[204:207], v[132:135], v[72:75]
	v_mfma_f32_16x16x32_bf16 v[0:3], v[204:207], v[136:139], v[0:3]
	v_mfma_f32_16x16x32_bf16 v[8:11], v[204:207], v[140:143], v[8:11]
	s_waitcnt lgkmcnt(0)
	v_mfma_f32_16x16x32_bf16 v[68:71], v[242:245], v[128:131], v[68:71]
	v_mfma_f32_16x16x32_bf16 v[76:79], v[242:245], v[132:135], v[76:79]
	v_mfma_f32_16x16x32_bf16 v[4:7], v[242:245], v[136:139], v[4:7]
	v_mfma_f32_16x16x32_bf16 v[12:15], v[242:245], v[140:143], v[12:15]
	global_load_dwordx4 v[128:131], v[248:249], off
	global_load_dwordx4 v[132:135], v[248:249], off offset:256
	global_load_dwordx4 v[136:139], v[250:251], off
	global_load_dwordx4 v[140:143], v[250:251], off offset:256
	s_waitcnt vmcnt(10)
	s_barrier
	s_mov_b32 s96, 0xae000
	s_mov_b32 m0, vcc_lo
	v_lshl_add_u64 v[160:161], v[188:189], 0, s[96:97]
	global_load_lds_dwordx4 v[160:161], off
	global_load_lds_dwordx4 v[160:161], off offset:1024
	ds_read_b128 v[196:199], v246 offset:8192
	ds_read_b128 v[200:203], v162 offset:8192
	ds_read_b128 v[204:207], v246 offset:10240
	ds_read_b128 v[242:245], v162 offset:10240
	s_mov_b32 s96, 0x2b800
	v_lshl_add_u64 v[248:249], v[184:185], 0, s[96:97]
	v_lshl_add_u64 v[250:251], v[186:187], 0, s[96:97]
	s_waitcnt vmcnt(8) lgkmcnt(3)
	v_mfma_f32_16x16x32_bf16 v[112:115], v[196:199], v[144:147], v[112:115]
	v_mfma_f32_16x16x32_bf16 v[120:123], v[196:199], v[148:151], v[120:123]
	v_mfma_f32_16x16x32_bf16 v[48:51], v[196:199], v[152:155], v[48:51]
	v_mfma_f32_16x16x32_bf16 v[56:59], v[196:199], v[156:159], v[56:59]
	ds_read_b128 v[196:199], v246 offset:12288
	s_waitcnt lgkmcnt(3)
	v_mfma_f32_16x16x32_bf16 v[116:119], v[200:203], v[144:147], v[116:119]
	v_mfma_f32_16x16x32_bf16 v[124:127], v[200:203], v[148:151], v[124:127]
	v_mfma_f32_16x16x32_bf16 v[52:55], v[200:203], v[152:155], v[52:55]
	v_mfma_f32_16x16x32_bf16 v[60:63], v[200:203], v[156:159], v[60:63]
	ds_read_b128 v[200:203], v162 offset:12288
	s_waitcnt lgkmcnt(3)
	v_mfma_f32_16x16x32_bf16 v[96:99], v[204:207], v[144:147], v[96:99]
	v_mfma_f32_16x16x32_bf16 v[104:107], v[204:207], v[148:151], v[104:107]
	v_mfma_f32_16x16x32_bf16 v[32:35], v[204:207], v[152:155], v[32:35]
	v_mfma_f32_16x16x32_bf16 v[40:43], v[204:207], v[156:159], v[40:43]
	ds_read_b128 v[204:207], v246 offset:14336
	s_waitcnt lgkmcnt(3)
	v_mfma_f32_16x16x32_bf16 v[100:103], v[242:245], v[144:147], v[100:103]
	v_mfma_f32_16x16x32_bf16 v[108:111], v[242:245], v[148:151], v[108:111]
	v_mfma_f32_16x16x32_bf16 v[36:39], v[242:245], v[152:155], v[36:39]
	v_mfma_f32_16x16x32_bf16 v[44:47], v[242:245], v[156:159], v[44:47]
	ds_read_b128 v[242:245], v162 offset:14336
	s_waitcnt lgkmcnt(3)
	v_mfma_f32_16x16x32_bf16 v[80:83], v[196:199], v[144:147], v[80:83]
	v_mfma_f32_16x16x32_bf16 v[88:91], v[196:199], v[148:151], v[88:91]
	v_mfma_f32_16x16x32_bf16 v[16:19], v[196:199], v[152:155], v[16:19]
	v_mfma_f32_16x16x32_bf16 v[24:27], v[196:199], v[156:159], v[24:27]
	s_waitcnt lgkmcnt(2)
	v_mfma_f32_16x16x32_bf16 v[84:87], v[200:203], v[144:147], v[84:87]
	v_mfma_f32_16x16x32_bf16 v[92:95], v[200:203], v[148:151], v[92:95]
	v_mfma_f32_16x16x32_bf16 v[20:23], v[200:203], v[152:155], v[20:23]
	v_mfma_f32_16x16x32_bf16 v[28:31], v[200:203], v[156:159], v[28:31]
	s_waitcnt lgkmcnt(1)
	v_mfma_f32_16x16x32_bf16 v[64:67], v[204:207], v[144:147], v[64:67]
	v_mfma_f32_16x16x32_bf16 v[72:75], v[204:207], v[148:151], v[72:75]
	v_mfma_f32_16x16x32_bf16 v[0:3], v[204:207], v[152:155], v[0:3]
	v_mfma_f32_16x16x32_bf16 v[8:11], v[204:207], v[156:159], v[8:11]
	s_waitcnt lgkmcnt(0)
	v_mfma_f32_16x16x32_bf16 v[68:71], v[242:245], v[144:147], v[68:71]
	v_mfma_f32_16x16x32_bf16 v[76:79], v[242:245], v[148:151], v[76:79]
	v_mfma_f32_16x16x32_bf16 v[4:7], v[242:245], v[152:155], v[4:7]
	v_mfma_f32_16x16x32_bf16 v[12:15], v[242:245], v[156:159], v[12:15]
	global_load_dwordx4 v[144:147], v[248:249], off
	global_load_dwordx4 v[148:151], v[248:249], off offset:256
	global_load_dwordx4 v[152:155], v[250:251], off
	global_load_dwordx4 v[156:159], v[250:251], off offset:256
	s_waitcnt vmcnt(10)
	s_barrier
	ds_read_b128 v[196:199], v246 offset:16384
	ds_read_b128 v[200:203], v162 offset:16384
	ds_read_b128 v[204:207], v246 offset:18432
	ds_read_b128 v[242:245], v162 offset:18432
	s_waitcnt vmcnt(6) lgkmcnt(3)
	v_mfma_f32_16x16x32_bf16 v[112:115], v[196:199], v[128:131], v[112:115]
	v_mfma_f32_16x16x32_bf16 v[120:123], v[196:199], v[132:135], v[120:123]
	v_mfma_f32_16x16x32_bf16 v[48:51], v[196:199], v[136:139], v[48:51]
	v_mfma_f32_16x16x32_bf16 v[56:59], v[196:199], v[140:143], v[56:59]
	ds_read_b128 v[196:199], v246 offset:20480
	s_waitcnt lgkmcnt(3)
	v_mfma_f32_16x16x32_bf16 v[116:119], v[200:203], v[128:131], v[116:119]
	v_mfma_f32_16x16x32_bf16 v[124:127], v[200:203], v[132:135], v[124:127]
	v_mfma_f32_16x16x32_bf16 v[52:55], v[200:203], v[136:139], v[52:55]
	v_mfma_f32_16x16x32_bf16 v[60:63], v[200:203], v[140:143], v[60:63]
	ds_read_b128 v[200:203], v162 offset:20480
	s_waitcnt lgkmcnt(3)
	v_mfma_f32_16x16x32_bf16 v[96:99], v[204:207], v[128:131], v[96:99]
	v_mfma_f32_16x16x32_bf16 v[104:107], v[204:207], v[132:135], v[104:107]
	v_mfma_f32_16x16x32_bf16 v[32:35], v[204:207], v[136:139], v[32:35]
	v_mfma_f32_16x16x32_bf16 v[40:43], v[204:207], v[140:143], v[40:43]
	ds_read_b128 v[204:207], v246 offset:22528
	s_waitcnt lgkmcnt(3)
	v_mfma_f32_16x16x32_bf16 v[100:103], v[242:245], v[128:131], v[100:103]
	v_mfma_f32_16x16x32_bf16 v[108:111], v[242:245], v[132:135], v[108:111]
	v_mfma_f32_16x16x32_bf16 v[36:39], v[242:245], v[136:139], v[36:39]
	v_mfma_f32_16x16x32_bf16 v[44:47], v[242:245], v[140:143], v[44:47]
	ds_read_b128 v[242:245], v162 offset:22528
	s_waitcnt lgkmcnt(3)
	v_mfma_f32_16x16x32_bf16 v[80:83], v[196:199], v[128:131], v[80:83]
	v_mfma_f32_16x16x32_bf16 v[88:91], v[196:199], v[132:135], v[88:91]
	v_mfma_f32_16x16x32_bf16 v[16:19], v[196:199], v[136:139], v[16:19]
	v_mfma_f32_16x16x32_bf16 v[24:27], v[196:199], v[140:143], v[24:27]
	s_waitcnt lgkmcnt(2)
	v_mfma_f32_16x16x32_bf16 v[84:87], v[200:203], v[128:131], v[84:87]
	v_mfma_f32_16x16x32_bf16 v[92:95], v[200:203], v[132:135], v[92:95]
	v_mfma_f32_16x16x32_bf16 v[20:23], v[200:203], v[136:139], v[20:23]
	v_mfma_f32_16x16x32_bf16 v[28:31], v[200:203], v[140:143], v[28:31]
	s_waitcnt lgkmcnt(1)
	v_mfma_f32_16x16x32_bf16 v[64:67], v[204:207], v[128:131], v[64:67]
	v_mfma_f32_16x16x32_bf16 v[72:75], v[204:207], v[132:135], v[72:75]
	v_mfma_f32_16x16x32_bf16 v[0:3], v[204:207], v[136:139], v[0:3]
	v_mfma_f32_16x16x32_bf16 v[8:11], v[204:207], v[140:143], v[8:11]
	s_waitcnt lgkmcnt(0)
	v_mfma_f32_16x16x32_bf16 v[68:71], v[242:245], v[128:131], v[68:71]
	v_mfma_f32_16x16x32_bf16 v[76:79], v[242:245], v[132:135], v[76:79]
	v_mfma_f32_16x16x32_bf16 v[4:7], v[242:245], v[136:139], v[4:7]
	v_mfma_f32_16x16x32_bf16 v[12:15], v[242:245], v[140:143], v[12:15]
	s_waitcnt vmcnt(4)
	s_barrier
	ds_read_b128 v[196:199], v246 offset:0
	ds_read_b128 v[200:203], v162 offset:0
	ds_read_b128 v[204:207], v246 offset:2048
	ds_read_b128 v[242:245], v162 offset:2048
	s_waitcnt vmcnt(0) lgkmcnt(3)
	v_mfma_f32_16x16x32_bf16 v[112:115], v[196:199], v[144:147], v[112:115]
	v_mfma_f32_16x16x32_bf16 v[120:123], v[196:199], v[148:151], v[120:123]
	v_mfma_f32_16x16x32_bf16 v[48:51], v[196:199], v[152:155], v[48:51]
	v_mfma_f32_16x16x32_bf16 v[56:59], v[196:199], v[156:159], v[56:59]
	ds_read_b128 v[196:199], v246 offset:4096
	s_waitcnt lgkmcnt(3)
	v_mfma_f32_16x16x32_bf16 v[116:119], v[200:203], v[144:147], v[116:119]
	v_mfma_f32_16x16x32_bf16 v[124:127], v[200:203], v[148:151], v[124:127]
	v_mfma_f32_16x16x32_bf16 v[52:55], v[200:203], v[152:155], v[52:55]
	v_mfma_f32_16x16x32_bf16 v[60:63], v[200:203], v[156:159], v[60:63]
	ds_read_b128 v[200:203], v162 offset:4096
	s_waitcnt lgkmcnt(3)
	v_mfma_f32_16x16x32_bf16 v[96:99], v[204:207], v[144:147], v[96:99]
	v_mfma_f32_16x16x32_bf16 v[104:107], v[204:207], v[148:151], v[104:107]
	v_mfma_f32_16x16x32_bf16 v[32:35], v[204:207], v[152:155], v[32:35]
	v_mfma_f32_16x16x32_bf16 v[40:43], v[204:207], v[156:159], v[40:43]
	ds_read_b128 v[204:207], v246 offset:6144
	s_waitcnt lgkmcnt(3)
	v_mfma_f32_16x16x32_bf16 v[100:103], v[242:245], v[144:147], v[100:103]
	v_mfma_f32_16x16x32_bf16 v[108:111], v[242:245], v[148:151], v[108:111]
	v_mfma_f32_16x16x32_bf16 v[36:39], v[242:245], v[152:155], v[36:39]
	v_mfma_f32_16x16x32_bf16 v[44:47], v[242:245], v[156:159], v[44:47]
	ds_read_b128 v[242:245], v162 offset:6144
	s_waitcnt lgkmcnt(3)
	v_mfma_f32_16x16x32_bf16 v[80:83], v[196:199], v[144:147], v[80:83]
	v_mfma_f32_16x16x32_bf16 v[88:91], v[196:199], v[148:151], v[88:91]
	v_mfma_f32_16x16x32_bf16 v[16:19], v[196:199], v[152:155], v[16:19]
	v_mfma_f32_16x16x32_bf16 v[24:27], v[196:199], v[156:159], v[24:27]
	s_waitcnt lgkmcnt(2)
	v_mfma_f32_16x16x32_bf16 v[84:87], v[200:203], v[144:147], v[84:87]
	v_mfma_f32_16x16x32_bf16 v[92:95], v[200:203], v[148:151], v[92:95]
	v_mfma_f32_16x16x32_bf16 v[20:23], v[200:203], v[152:155], v[20:23]
	v_mfma_f32_16x16x32_bf16 v[28:31], v[200:203], v[156:159], v[28:31]
	s_waitcnt lgkmcnt(1)
	v_mfma_f32_16x16x32_bf16 v[64:67], v[204:207], v[144:147], v[64:67]
	v_mfma_f32_16x16x32_bf16 v[72:75], v[204:207], v[148:151], v[72:75]
	v_mfma_f32_16x16x32_bf16 v[0:3], v[204:207], v[152:155], v[0:3]
	v_mfma_f32_16x16x32_bf16 v[8:11], v[204:207], v[156:159], v[8:11]
	s_waitcnt lgkmcnt(0)
	v_mfma_f32_16x16x32_bf16 v[68:71], v[242:245], v[144:147], v[68:71]
	v_mfma_f32_16x16x32_bf16 v[76:79], v[242:245], v[148:151], v[76:79]
	v_mfma_f32_16x16x32_bf16 v[4:7], v[242:245], v[152:155], v[4:7]
	v_mfma_f32_16x16x32_bf16 v[12:15], v[242:245], v[156:159], v[12:15]
	s_barrier
	s_nop 7
	s_nop 1
	s_waitcnt vmcnt(0)
	s_waitcnt vmcnt(0)
	v_and_b32_e32 v188, 63, v179
	v_lshrrev_b32_e32 v189, 6, v179
	v_mul_u32_u24_e32 v249, 0x2400, v189
	v_mov_b32_e32 v250, v249
	v_and_b32_e32 v251, 15, v188
	v_mul_u32_u24_e32 v251, 0x110, v251
	v_add_u32_e32 v249, v249, v251
	v_lshrrev_b32_e32 v251, 4, v188
	v_lshl_add_u32 v249, v251, 5, v249
	v_lshrrev_b32_e32 v237, 4, v188
	v_mul_u32_u24_e32 v251, 0x110, v237
	v_add_u32_e32 v250, v250, v251
	v_and_b32_e32 v251, 15, v188
	v_lshlrev_b32_e32 v251, 4, v251
	v_add_u32_e32 v250, v250, v251
	v_lshl_add_u32 v237, v189, 6, v237
	v_lshl_add_u32 v237, v237, 12, v251
	v_add_u32_e32 v238, 16384, v237
	v_add_u32_e32 v239, 32768, v237
	v_add_u32_e32 v240, 49152, v237
	v_add_u32_e32 v241, 65536, v237
	v_add_u32_e32 v242, 81920, v237
	v_add_u32_e32 v243, 98304, v237
	v_add_u32_e32 v248, 114688, v237
	s_lshl_b32 s16, s7, 8
	s_lshl_b32 s18, s6, 9
	s_lshr_b32 s19, s7, 4
	v_readlane_b32 s12, v253, 46
	v_readlane_b32 s13, v253, 47
	v_readlane_b32 s14, v253, 46
	v_readlane_b32 s15, v253, 47
	s_add_i32 s17, s16, 0xffff8000
	s_cmpk_lt_u32 s7, 0x80
	s_cselect_b32 s12, s12, s62
	s_cselect_b32 s13, s13, s63
	s_cselect_b32 s14, s14, s62
	s_cselect_b32 s15, s15, s63
	s_cselect_b32 s19, s19, 8
	s_cselect_b32 s16, s16, s17
	s_mov_b32 s17, 0
	s_lshl_b64 s[16:17], s[16:17], 12
	s_add_u32 s16, s16, s18
	s_addc_u32 s17, s17, 0
	s_add_u32 s12, s12, s16
	s_addc_u32 s13, s13, s17
	s_add_u32 s14, s14, s16
	s_addc_u32 s15, s15, s17
	s_mul_i32 s19, s19, 0x6000
	s_add_u32 s20, s0, s19
	s_addc_u32 s21, s1, 0
	s_add_u32 s20, s20, s18
	s_addc_u32 s21, s21, 0
	global_load_dwordx4 v[244:247], v251, s[20:21]
	global_load_dwordx4 v[160:163], v237, s[12:13]
	global_load_dwordx4 v[164:167], v238, s[12:13]
	global_load_dwordx4 v[168:171], v239, s[12:13]
	global_load_dwordx4 v[172:175], v240, s[12:13]
	global_load_dwordx4 v[196:199], v241, s[12:13]
	global_load_dwordx4 v[200:203], v242, s[12:13]
	global_load_dwordx4 v[204:207], v243, s[12:13]
	global_load_dwordx4 v[184:187], v248, s[12:13]
	ds_write_b128 v249, v[112:115]
	ds_write_b128 v249, v[116:119] offset:16
	ds_write_b128 v249, v[96:99] offset:128
	ds_write_b128 v249, v[100:103] offset:144
	ds_write_b128 v249, v[120:123] offset:4352
	ds_write_b128 v249, v[124:127] offset:4368
	ds_write_b128 v249, v[104:107] offset:4480
	ds_write_b128 v249, v[108:111] offset:4496
	s_waitcnt lgkmcnt(0)
	ds_read_b128 v[128:131], v250
	ds_read_b128 v[132:135], v250 offset:1088
	ds_read_b128 v[136:139], v250 offset:2176
	ds_read_b128 v[140:143], v250 offset:3264
	ds_read_b128 v[144:147], v250 offset:4352
	ds_read_b128 v[148:151], v250 offset:5440
	ds_read_b128 v[152:155], v250 offset:6528
	ds_read_b128 v[156:159], v250 offset:7616
	s_waitcnt vmcnt(7) lgkmcnt(7)
	v_fma_f32 v128, v244, v128, v160
	v_fma_f32 v129, v245, v129, v161
	v_fma_f32 v130, v246, v130, v162
	v_fma_f32 v131, v247, v131, v163
	global_store_dwordx4 v237, v[128:131], s[14:15] sc1
	s_waitcnt vmcnt(7) lgkmcnt(6)
	v_fma_f32 v132, v244, v132, v164
	v_fma_f32 v133, v245, v133, v165
	v_fma_f32 v134, v246, v134, v166
	v_fma_f32 v135, v247, v135, v167
	global_store_dwordx4 v238, v[132:135], s[14:15] sc1
	s_waitcnt vmcnt(7) lgkmcnt(5)
	v_fma_f32 v136, v244, v136, v168
	v_fma_f32 v137, v245, v137, v169
	v_fma_f32 v138, v246, v138, v170
	v_fma_f32 v139, v247, v139, v171
	global_store_dwordx4 v239, v[136:139], s[14:15] sc1
	s_waitcnt vmcnt(7) lgkmcnt(4)
	v_fma_f32 v140, v244, v140, v172
	v_fma_f32 v141, v245, v141, v173
	v_fma_f32 v142, v246, v142, v174
	v_fma_f32 v143, v247, v143, v175
	global_store_dwordx4 v240, v[140:143], s[14:15] sc1
	s_waitcnt vmcnt(7) lgkmcnt(3)
	v_fma_f32 v144, v244, v144, v196
	v_fma_f32 v145, v245, v145, v197
	v_fma_f32 v146, v246, v146, v198
	v_fma_f32 v147, v247, v147, v199
	global_store_dwordx4 v241, v[144:147], s[14:15] sc1
	s_waitcnt vmcnt(7) lgkmcnt(2)
	v_fma_f32 v148, v244, v148, v200
	v_fma_f32 v149, v245, v149, v201
	v_fma_f32 v150, v246, v150, v202
	v_fma_f32 v151, v247, v151, v203
	global_store_dwordx4 v242, v[148:151], s[14:15] sc1
	s_waitcnt vmcnt(7) lgkmcnt(1)
	v_fma_f32 v152, v244, v152, v204
	v_fma_f32 v153, v245, v153, v205
	v_fma_f32 v154, v246, v154, v206
	v_fma_f32 v155, v247, v155, v207
	global_store_dwordx4 v243, v[152:155], s[14:15] sc1
	s_waitcnt vmcnt(7) lgkmcnt(0)
	v_fma_f32 v156, v244, v156, v184
	v_fma_f32 v157, v245, v157, v185
	v_fma_f32 v158, v246, v158, v186
	v_fma_f32 v159, v247, v159, v187
	global_store_dwordx4 v248, v[156:159], s[14:15] sc1
	global_load_dwordx4 v[244:247], v251, s[20:21] offset:256
	global_load_dwordx4 v[160:163], v237, s[12:13] offset:256
	global_load_dwordx4 v[164:167], v238, s[12:13] offset:256
	global_load_dwordx4 v[168:171], v239, s[12:13] offset:256
	global_load_dwordx4 v[172:175], v240, s[12:13] offset:256
	global_load_dwordx4 v[196:199], v241, s[12:13] offset:256
	global_load_dwordx4 v[200:203], v242, s[12:13] offset:256
	global_load_dwordx4 v[204:207], v243, s[12:13] offset:256
	global_load_dwordx4 v[184:187], v248, s[12:13] offset:256
	ds_write_b128 v249, v[80:83]
	ds_write_b128 v249, v[84:87] offset:16
	ds_write_b128 v249, v[64:67] offset:128
	ds_write_b128 v249, v[68:71] offset:144
	ds_write_b128 v249, v[88:91] offset:4352
	ds_write_b128 v249, v[92:95] offset:4368
	ds_write_b128 v249, v[72:75] offset:4480
	ds_write_b128 v249, v[76:79] offset:4496
	s_waitcnt lgkmcnt(0)
	ds_read_b128 v[128:131], v250
	ds_read_b128 v[132:135], v250 offset:1088
	ds_read_b128 v[136:139], v250 offset:2176
	ds_read_b128 v[140:143], v250 offset:3264
	ds_read_b128 v[144:147], v250 offset:4352
	ds_read_b128 v[148:151], v250 offset:5440
	ds_read_b128 v[152:155], v250 offset:6528
	ds_read_b128 v[156:159], v250 offset:7616
	s_waitcnt vmcnt(7) lgkmcnt(7)
	v_fma_f32 v128, v244, v128, v160
	v_fma_f32 v129, v245, v129, v161
	v_fma_f32 v130, v246, v130, v162
	v_fma_f32 v131, v247, v131, v163
	global_store_dwordx4 v237, v[128:131], s[14:15] offset:256 sc1
	s_waitcnt vmcnt(7) lgkmcnt(6)
	v_fma_f32 v132, v244, v132, v164
	v_fma_f32 v133, v245, v133, v165
	v_fma_f32 v134, v246, v134, v166
	v_fma_f32 v135, v247, v135, v167
	global_store_dwordx4 v238, v[132:135], s[14:15] offset:256 sc1
	s_waitcnt vmcnt(7) lgkmcnt(5)
	v_fma_f32 v136, v244, v136, v168
	v_fma_f32 v137, v245, v137, v169
	v_fma_f32 v138, v246, v138, v170
	v_fma_f32 v139, v247, v139, v171
	global_store_dwordx4 v239, v[136:139], s[14:15] offset:256 sc1
	s_waitcnt vmcnt(7) lgkmcnt(4)
	v_fma_f32 v140, v244, v140, v172
	v_fma_f32 v141, v245, v141, v173
	v_fma_f32 v142, v246, v142, v174
	v_fma_f32 v143, v247, v143, v175
	global_store_dwordx4 v240, v[140:143], s[14:15] offset:256 sc1
	s_waitcnt vmcnt(7) lgkmcnt(3)
	v_fma_f32 v144, v244, v144, v196
	v_fma_f32 v145, v245, v145, v197
	v_fma_f32 v146, v246, v146, v198
	v_fma_f32 v147, v247, v147, v199
	global_store_dwordx4 v241, v[144:147], s[14:15] offset:256 sc1
	s_waitcnt vmcnt(7) lgkmcnt(2)
	v_fma_f32 v148, v244, v148, v200
	v_fma_f32 v149, v245, v149, v201
	v_fma_f32 v150, v246, v150, v202
	v_fma_f32 v151, v247, v151, v203
	global_store_dwordx4 v242, v[148:151], s[14:15] offset:256 sc1
	s_waitcnt vmcnt(7) lgkmcnt(1)
	v_fma_f32 v152, v244, v152, v204
	v_fma_f32 v153, v245, v153, v205
	v_fma_f32 v154, v246, v154, v206
	v_fma_f32 v155, v247, v155, v207
	global_store_dwordx4 v243, v[152:155], s[14:15] offset:256 sc1
	s_waitcnt vmcnt(7) lgkmcnt(0)
	v_fma_f32 v156, v244, v156, v184
	v_fma_f32 v157, v245, v157, v185
	v_fma_f32 v158, v246, v158, v186
	v_fma_f32 v159, v247, v159, v187
	global_store_dwordx4 v248, v[156:159], s[14:15] offset:256 sc1
	s_add_u32 s12, s12, 0x20000
	s_addc_u32 s13, s13, 0
	s_add_u32 s14, s14, 0x20000
	s_addc_u32 s15, s15, 0
	global_load_dwordx4 v[244:247], v251, s[20:21]
	global_load_dwordx4 v[160:163], v237, s[12:13]
	global_load_dwordx4 v[164:167], v238, s[12:13]
	global_load_dwordx4 v[168:171], v239, s[12:13]
	global_load_dwordx4 v[172:175], v240, s[12:13]
	global_load_dwordx4 v[196:199], v241, s[12:13]
	global_load_dwordx4 v[200:203], v242, s[12:13]
	global_load_dwordx4 v[204:207], v243, s[12:13]
	global_load_dwordx4 v[184:187], v248, s[12:13]
	ds_write_b128 v249, v[48:51]
	ds_write_b128 v249, v[52:55] offset:16
	ds_write_b128 v249, v[32:35] offset:128
	ds_write_b128 v249, v[36:39] offset:144
	ds_write_b128 v249, v[56:59] offset:4352
	ds_write_b128 v249, v[60:63] offset:4368
	ds_write_b128 v249, v[40:43] offset:4480
	ds_write_b128 v249, v[44:47] offset:4496
	s_waitcnt lgkmcnt(0)
	ds_read_b128 v[128:131], v250
	ds_read_b128 v[132:135], v250 offset:1088
	ds_read_b128 v[136:139], v250 offset:2176
	ds_read_b128 v[140:143], v250 offset:3264
	ds_read_b128 v[144:147], v250 offset:4352
	ds_read_b128 v[148:151], v250 offset:5440
	ds_read_b128 v[152:155], v250 offset:6528
	ds_read_b128 v[156:159], v250 offset:7616
	s_waitcnt vmcnt(7) lgkmcnt(7)
	v_fma_f32 v128, v244, v128, v160
	v_fma_f32 v129, v245, v129, v161
	v_fma_f32 v130, v246, v130, v162
	v_fma_f32 v131, v247, v131, v163
	global_store_dwordx4 v237, v[128:131], s[14:15] sc1
	s_waitcnt vmcnt(7) lgkmcnt(6)
	v_fma_f32 v132, v244, v132, v164
	v_fma_f32 v133, v245, v133, v165
	v_fma_f32 v134, v246, v134, v166
	v_fma_f32 v135, v247, v135, v167
	global_store_dwordx4 v238, v[132:135], s[14:15] sc1
	s_waitcnt vmcnt(7) lgkmcnt(5)
	v_fma_f32 v136, v244, v136, v168
	v_fma_f32 v137, v245, v137, v169
	v_fma_f32 v138, v246, v138, v170
	v_fma_f32 v139, v247, v139, v171
	global_store_dwordx4 v239, v[136:139], s[14:15] sc1
	s_waitcnt vmcnt(7) lgkmcnt(4)
	v_fma_f32 v140, v244, v140, v172
	v_fma_f32 v141, v245, v141, v173
	v_fma_f32 v142, v246, v142, v174
	v_fma_f32 v143, v247, v143, v175
	global_store_dwordx4 v240, v[140:143], s[14:15] sc1
	s_waitcnt vmcnt(7) lgkmcnt(3)
	v_fma_f32 v144, v244, v144, v196
	v_fma_f32 v145, v245, v145, v197
	v_fma_f32 v146, v246, v146, v198
	v_fma_f32 v147, v247, v147, v199
	global_store_dwordx4 v241, v[144:147], s[14:15] sc1
	s_waitcnt vmcnt(7) lgkmcnt(2)
	v_fma_f32 v148, v244, v148, v200
	v_fma_f32 v149, v245, v149, v201
	v_fma_f32 v150, v246, v150, v202
	v_fma_f32 v151, v247, v151, v203
	global_store_dwordx4 v242, v[148:151], s[14:15] sc1
	s_waitcnt vmcnt(7) lgkmcnt(1)
	v_fma_f32 v152, v244, v152, v204
	v_fma_f32 v153, v245, v153, v205
	v_fma_f32 v154, v246, v154, v206
	v_fma_f32 v155, v247, v155, v207
	global_store_dwordx4 v243, v[152:155], s[14:15] sc1
	s_waitcnt vmcnt(7) lgkmcnt(0)
	v_fma_f32 v156, v244, v156, v184
	v_fma_f32 v157, v245, v157, v185
	v_fma_f32 v158, v246, v158, v186
	v_fma_f32 v159, v247, v159, v187
	global_store_dwordx4 v248, v[156:159], s[14:15] sc1
	global_load_dwordx4 v[244:247], v251, s[20:21] offset:256
	global_load_dwordx4 v[160:163], v237, s[12:13] offset:256
	global_load_dwordx4 v[164:167], v238, s[12:13] offset:256
	global_load_dwordx4 v[168:171], v239, s[12:13] offset:256
	global_load_dwordx4 v[172:175], v240, s[12:13] offset:256
	global_load_dwordx4 v[196:199], v241, s[12:13] offset:256
	global_load_dwordx4 v[200:203], v242, s[12:13] offset:256
	global_load_dwordx4 v[204:207], v243, s[12:13] offset:256
	global_load_dwordx4 v[184:187], v248, s[12:13] offset:256
	ds_write_b128 v249, v[16:19]
	ds_write_b128 v249, v[20:23] offset:16
	ds_write_b128 v249, v[0:3] offset:128
	ds_write_b128 v249, v[4:7] offset:144
	ds_write_b128 v249, v[24:27] offset:4352
	ds_write_b128 v249, v[28:31] offset:4368
	ds_write_b128 v249, v[8:11] offset:4480
	ds_write_b128 v249, v[12:15] offset:4496
	s_waitcnt lgkmcnt(0)
	ds_read_b128 v[128:131], v250
	ds_read_b128 v[132:135], v250 offset:1088
	ds_read_b128 v[136:139], v250 offset:2176
	ds_read_b128 v[140:143], v250 offset:3264
	ds_read_b128 v[144:147], v250 offset:4352
	ds_read_b128 v[148:151], v250 offset:5440
	ds_read_b128 v[152:155], v250 offset:6528
	ds_read_b128 v[156:159], v250 offset:7616
	s_waitcnt vmcnt(7) lgkmcnt(7)
	v_fma_f32 v128, v244, v128, v160
	v_fma_f32 v129, v245, v129, v161
	v_fma_f32 v130, v246, v130, v162
	v_fma_f32 v131, v247, v131, v163
	global_store_dwordx4 v237, v[128:131], s[14:15] offset:256 sc1
	s_waitcnt vmcnt(7) lgkmcnt(6)
	v_fma_f32 v132, v244, v132, v164
	v_fma_f32 v133, v245, v133, v165
	v_fma_f32 v134, v246, v134, v166
	v_fma_f32 v135, v247, v135, v167
	global_store_dwordx4 v238, v[132:135], s[14:15] offset:256 sc1
	s_waitcnt vmcnt(7) lgkmcnt(5)
	v_fma_f32 v136, v244, v136, v168
	v_fma_f32 v137, v245, v137, v169
	v_fma_f32 v138, v246, v138, v170
	v_fma_f32 v139, v247, v139, v171
	global_store_dwordx4 v239, v[136:139], s[14:15] offset:256 sc1
	s_waitcnt vmcnt(7) lgkmcnt(4)
	v_fma_f32 v140, v244, v140, v172
	v_fma_f32 v141, v245, v141, v173
	v_fma_f32 v142, v246, v142, v174
	v_fma_f32 v143, v247, v143, v175
	global_store_dwordx4 v240, v[140:143], s[14:15] offset:256 sc1
	s_waitcnt vmcnt(7) lgkmcnt(3)
	v_fma_f32 v144, v244, v144, v196
	v_fma_f32 v145, v245, v145, v197
	v_fma_f32 v146, v246, v146, v198
	v_fma_f32 v147, v247, v147, v199
	global_store_dwordx4 v241, v[144:147], s[14:15] offset:256 sc1
	s_waitcnt vmcnt(7) lgkmcnt(2)
	v_fma_f32 v148, v244, v148, v200
	v_fma_f32 v149, v245, v149, v201
	v_fma_f32 v150, v246, v150, v202
	v_fma_f32 v151, v247, v151, v203
	global_store_dwordx4 v242, v[148:151], s[14:15] offset:256 sc1
	s_waitcnt vmcnt(7) lgkmcnt(1)
	v_fma_f32 v152, v244, v152, v204
	v_fma_f32 v153, v245, v153, v205
	v_fma_f32 v154, v246, v154, v206
	v_fma_f32 v155, v247, v155, v207
	global_store_dwordx4 v243, v[152:155], s[14:15] offset:256 sc1
	s_waitcnt vmcnt(7) lgkmcnt(0)
	v_fma_f32 v156, v244, v156, v184
	v_fma_f32 v157, v245, v157, v185
	v_fma_f32 v158, v246, v158, v186
	v_fma_f32 v159, v247, v159, v187
	global_store_dwordx4 v248, v[156:159], s[14:15] offset:256 sc1
	s_waitcnt lgkmcnt(0)
	v_readlane_b32 s16, v254, 11
	s_andn2_b32 s17, s26, 63
	s_add_i32 s2, s2, s16
	s_cmp_lt_i32 s2, s17
	s_cbranch_scc0 .Lhx_down_left
	s_barrier
	s_branch .LBB0_1086
